# v13 + removed the back-to-back s_setprio 0/3 pair in the middle of each 32-MFMA K-loop segment in all 9 GEMM copies (2 fewer issue slots per segment)
# speedup vs baseline: 1.0048x; 1.0017x over previous
; #define PG8_STAGE(bufoff, gbase, voff) do { _Pragma("unroll") for (int _i = 0; _i < 2; ++_i) \
;         __builtin_amdgcn_global_load_lds((const unsigned*)((const char*)(gbase) + (voff)[_i]), (LAS unsigned*)(lds + (bufoff) + ldsw + _i * 8192), 16, 0, 0); } while (0)
; #define PG8_LDA(dst, b, h) do { _Pragma("unroll") for (int m = 0; m < 4; ++m) _Pragma("unroll") for (int k = 0; k < 2; ++k) dst[m][k] = *(const LAS bf16x8*)(lds + PG8_SA(b, h) + aoff + m * 2048 + k * 1024); } while (0)
; #define PG8_LDB(dst, b, h) do { _Pragma("unroll") for (int n = 0; n < 2; ++n) _Pragma("unroll") for (int k = 0; k < 2; ++k) dst[n][k] = *(const LAS bf16x8*)(lds + PG8_SB(b, h) + boff + n * 2048 + k * 1024); } while (0)
; #define PG8_MMA(ai, bj, At, Bt) do { __builtin_amdgcn_s_setprio(3); _Pragma("unroll") for (int m = 0; m < 4; ++m) _Pragma("unroll") for (int n = 0; n < 2; ++n) _Pragma("unroll") for (int k = 0; k < 2; ++k) \
;         acc[ai][bj][m][n] = __builtin_amdgcn_mfma_f32_16x16x32_bf16(Bt[n][k], At[m][k], acc[ai][bj][m][n], 0, 0, 0); __builtin_amdgcn_s_setprio(0); } while (0)
; #define PG8_WAIT_V(n) asm volatile("s_waitcnt vmcnt(" #n ")" ::: "memory")
; #define PG8_WAIT_L(n) asm volatile("s_waitcnt lgkmcnt(" #n ")" ::: "memory")
; #define PG8_BAR __builtin_amdgcn_s_barrier()
; #define PG8_SCHED __builtin_amdgcn_sched_barrier(0)
;     ...
;             PG8_LDB(B0, 0, 0); PG8_LDB(B1, 0, 1); PG8_SCHED; PG8_LDA(At, 0, 0); PG8_STAGE(PG8_SA(1, 1), a1 + hstepA, voffA);
;             PG8_WAIT_V(8); PG8_WAIT_L(0); PG8_BAR; PG8_MMA(0, 0, At, B0); PG8_MMA(0, 1, At, B1); PG8_BAR; PG8_SCHED;
;             PG8_LDA(At, 0, 1); PG8_STAGE(PG8_SB(0, 0), b2, voffB); PG8_STAGE(PG8_SB(0, 1), b2 + hstepB, voffB); PG8_STAGE(PG8_SA(0, 0), a2, voffA);
;             PG8_WAIT_V(8); PG8_WAIT_L(0); PG8_BAR; PG8_MMA(1, 0, At, B0); PG8_MMA(1, 1, At, B1); PG8_BAR; PG8_SCHED;
.LBB0_42:
	s_add_u32 s4, s74, 0x100
	s_addc_u32 s5, s75, 0
	s_add_i32 s87, 0, 0x10000
	s_cmp_eq_u32 s86, 12
	s_cselect_b32 s79, s71, s5
	s_cselect_b32 s78, s70, s4
	v_add_u32_e32 v165, s87, v146
	s_cselect_b32 s77, s11, s61
	s_cselect_b32 s76, s42, s60
	s_add_i32 s93, 0, 0x14000
	ds_read_b128 v[142:145], v165
	ds_read_b128 v[166:169], v165 offset:1024
	ds_read_b128 v[170:173], v165 offset:2048
	ds_read_b128 v[174:177], v165 offset:3072
	v_add_u32_e32 v165, s93, v146
	ds_read_b128 v[192:195], v165
	ds_read_b128 v[196:199], v165 offset:1024
	ds_read_b128 v[200:203], v165 offset:2048
	ds_read_b128 v[204:207], v165 offset:3072
	v_lshl_add_u64 v[240:241], s[74:75], 0, v[140:141]
	s_add_i32 m0, s68, 0xc000
	ds_read_b128 v[208:211], v164
	ds_read_b128 v[212:215], v164 offset:1024
	ds_read_b128 v[216:219], v164 offset:2048
	ds_read_b128 v[220:223], v164 offset:3072
	ds_read_b128 v[224:227], v164 offset:4096
	ds_read_b128 v[228:231], v164 offset:5120
	ds_read_b128 v[232:235], v164 offset:6144
	ds_read_b128 v[236:239], v164 offset:7168
	global_load_lds_dwordx4 v[240:241], off
	v_lshl_add_u64 v[240:241], s[74:75], 0, v[138:139]
	s_add_i32 m0, s68, 0xe000
	s_nop 0
	global_load_lds_dwordx4 v[240:241], off
	s_waitcnt vmcnt(8)
	s_waitcnt lgkmcnt(0)
	s_barrier
	s_setprio 3
	s_waitcnt lgkmcnt(0)
	v_mfma_f32_16x16x32_bf16 v[126:129], v[142:145], v[208:211], v[126:129]
	v_mfma_f32_16x16x32_bf16 v[122:125], v[170:173], v[208:211], v[122:125]
	v_mfma_f32_16x16x32_bf16 v[110:113], v[142:145], v[216:219], v[110:113]
	v_mfma_f32_16x16x32_bf16 v[106:109], v[170:173], v[216:219], v[106:109]
	v_mfma_f32_16x16x32_bf16 v[94:97], v[142:145], v[224:227], v[94:97]
	v_mfma_f32_16x16x32_bf16 v[90:93], v[170:173], v[224:227], v[90:93]
	v_mfma_f32_16x16x32_bf16 v[78:81], v[142:145], v[232:235], v[78:81]
	v_mfma_f32_16x16x32_bf16 v[74:77], v[170:173], v[232:235], v[74:77]
	v_mfma_f32_16x16x32_bf16 v[126:129], v[166:169], v[212:215], v[126:129]
	v_mfma_f32_16x16x32_bf16 v[122:125], v[174:177], v[212:215], v[122:125]
	v_mfma_f32_16x16x32_bf16 v[110:113], v[166:169], v[220:223], v[110:113]
	v_mfma_f32_16x16x32_bf16 v[106:109], v[174:177], v[220:223], v[106:109]
	v_mfma_f32_16x16x32_bf16 v[94:97], v[166:169], v[228:231], v[94:97]
	v_mfma_f32_16x16x32_bf16 v[90:93], v[174:177], v[228:231], v[90:93]
	v_mfma_f32_16x16x32_bf16 v[78:81], v[166:169], v[236:239], v[78:81]
	v_mfma_f32_16x16x32_bf16 v[74:77], v[174:177], v[236:239], v[74:77]
	v_mfma_f32_16x16x32_bf16 v[118:121], v[192:195], v[208:211], v[118:121]
	v_mfma_f32_16x16x32_bf16 v[114:117], v[200:203], v[208:211], v[114:117]
	v_mfma_f32_16x16x32_bf16 v[102:105], v[192:195], v[216:219], v[102:105]
	v_mfma_f32_16x16x32_bf16 v[98:101], v[200:203], v[216:219], v[98:101]
	v_mfma_f32_16x16x32_bf16 v[86:89], v[192:195], v[224:227], v[86:89]
	v_mfma_f32_16x16x32_bf16 v[82:85], v[200:203], v[224:227], v[82:85]
	v_mfma_f32_16x16x32_bf16 v[70:73], v[192:195], v[232:235], v[70:73]
	v_mfma_f32_16x16x32_bf16 v[66:69], v[200:203], v[232:235], v[66:69]
	v_mfma_f32_16x16x32_bf16 v[118:121], v[196:199], v[212:215], v[118:121]
	v_mfma_f32_16x16x32_bf16 v[114:117], v[204:207], v[212:215], v[114:117]
	v_mfma_f32_16x16x32_bf16 v[102:105], v[196:199], v[220:223], v[102:105]
	v_mfma_f32_16x16x32_bf16 v[98:101], v[204:207], v[220:223], v[98:101]
	v_mfma_f32_16x16x32_bf16 v[86:89], v[196:199], v[228:231], v[86:89]
	v_mfma_f32_16x16x32_bf16 v[82:85], v[204:207], v[228:231], v[82:85]
	v_mfma_f32_16x16x32_bf16 v[70:73], v[196:199], v[236:239], v[70:73]
	v_mfma_f32_16x16x32_bf16 v[66:69], v[204:207], v[236:239], v[66:69]
	s_setprio 0
	s_barrier
	s_add_i32 s74, s87, s30
	v_lshl_add_u64 v[240:241], s[76:77], 0, v[134:135]
	s_mov_b32 m0, s74
	ds_read_b128 v[208:211], v164 offset:16384
	ds_read_b128 v[212:215], v164 offset:17408
	ds_read_b128 v[216:219], v164 offset:18432
	ds_read_b128 v[220:223], v164 offset:19456
	ds_read_b128 v[224:227], v164 offset:20480
	ds_read_b128 v[228:231], v164 offset:21504
	ds_read_b128 v[232:235], v164 offset:22528
	ds_read_b128 v[236:239], v164 offset:23552
	global_load_lds_dwordx4 v[240:241], off
	s_add_i32 m0, s74, 0x2000
	s_add_u32 s74, s76, 0x10000
	v_lshl_add_u64 v[242:243], s[76:77], 0, v[130:131]
	s_addc_u32 s75, s77, 0
	s_add_i32 s87, s93, s30
	global_load_lds_dwordx4 v[242:243], off
	v_lshl_add_u64 v[244:245], s[74:75], 0, v[134:135]
	s_mov_b32 m0, s87
	v_lshl_add_u64 v[246:247], s[78:79], 0, v[132:133]
	global_load_lds_dwordx4 v[244:245], off
	v_lshl_add_u64 v[244:245], s[74:75], 0, v[130:131]
	s_add_i32 m0, s87, 0x2000
	s_nop 0
	global_load_lds_dwordx4 v[244:245], off
	v_lshl_add_u64 v[244:245], s[78:79], 0, v[136:137]
	s_mov_b32 m0, s68
	s_nop 0
	global_load_lds_dwordx4 v[244:245], off
	s_mov_b32 m0, s69
	s_nop 0
	global_load_lds_dwordx4 v[246:247], off
	s_waitcnt vmcnt(8)
	s_waitcnt lgkmcnt(0)
	s_barrier
; #define PG8_STAGE(bufoff, gbase, voff) do { _Pragma("unroll") for (int _i = 0; _i < 2; ++_i) \
;         __builtin_amdgcn_global_load_lds((const unsigned*)((const char*)(gbase) + (voff)[_i]), (LAS unsigned*)(lds + (bufoff) + ldsw + _i * 8192), 16, 0, 0); } while (0)
; #define PG8_LDA(dst, b, h) do { _Pragma("unroll") for (int m = 0; m < 4; ++m) _Pragma("unroll") for (int k = 0; k < 2; ++k) dst[m][k] = *(const LAS bf16x8*)(lds + PG8_SA(b, h) + aoff + m * 2048 + k * 1024); } while (0)
; #define PG8_LDB(dst, b, h) do { _Pragma("unroll") for (int n = 0; n < 2; ++n) _Pragma("unroll") for (int k = 0; k < 2; ++k) dst[n][k] = *(const LAS bf16x8*)(lds + PG8_SB(b, h) + boff + n * 2048 + k * 1024); } while (0)
; #define PG8_MMA(ai, bj, At, Bt) do { __builtin_amdgcn_s_setprio(3); _Pragma("unroll") for (int m = 0; m < 4; ++m) _Pragma("unroll") for (int n = 0; n < 2; ++n) _Pragma("unroll") for (int k = 0; k < 2; ++k) \
;         acc[ai][bj][m][n] = __builtin_amdgcn_mfma_f32_16x16x32_bf16(Bt[n][k], At[m][k], acc[ai][bj][m][n], 0, 0, 0); __builtin_amdgcn_s_setprio(0); } while (0)
; #define PG8_WAIT_V(n) asm volatile("s_waitcnt vmcnt(" #n ")" ::: "memory")
; #define PG8_WAIT_L(n) asm volatile("s_waitcnt lgkmcnt(" #n ")" ::: "memory")
; #define PG8_BAR __builtin_amdgcn_s_barrier()
; #define PG8_SCHED __builtin_amdgcn_sched_barrier(0)
;     ...
;             PG8_WAIT_V(8); PG8_WAIT_L(0); PG8_BAR; PG8_MMA(1, 0, At, B0); PG8_MMA(1, 1, At, B1); PG8_BAR; PG8_SCHED;
;             PG8_LDB(B0, 1, 0); PG8_LDB(B1, 1, 1); PG8_SCHED; PG8_LDA(At, 1, 0); PG8_STAGE(PG8_SA(0, 1), a2 + hstepA, voffA);
;             PG8_WAIT_V(8); PG8_WAIT_L(0); PG8_BAR; PG8_MMA(0, 0, At, B0); PG8_MMA(0, 1, At, B1); PG8_BAR; PG8_SCHED;
;             PG8_LDA(At, 1, 1); PG8_STAGE(PG8_SB(1, 0), b3, voffB); PG8_STAGE(PG8_SB(1, 1), b3 + hstepB, voffB); PG8_STAGE(PG8_SA(1, 0), a3, voffA);
	s_setprio 3
	s_waitcnt lgkmcnt(0)
	v_mfma_f32_16x16x32_bf16 v[62:65], v[142:145], v[208:211], v[62:65]
	v_mfma_f32_16x16x32_bf16 v[58:61], v[170:173], v[208:211], v[58:61]
	v_mfma_f32_16x16x32_bf16 v[46:49], v[142:145], v[216:219], v[46:49]
	v_mfma_f32_16x16x32_bf16 v[42:45], v[170:173], v[216:219], v[42:45]
	v_mfma_f32_16x16x32_bf16 v[30:33], v[142:145], v[224:227], v[30:33]
	v_mfma_f32_16x16x32_bf16 v[26:29], v[170:173], v[224:227], v[26:29]
	v_mfma_f32_16x16x32_bf16 v[14:17], v[142:145], v[232:235], v[14:17]
	v_mfma_f32_16x16x32_bf16 v[10:13], v[170:173], v[232:235], v[10:13]
	v_mfma_f32_16x16x32_bf16 v[62:65], v[166:169], v[212:215], v[62:65]
	v_mfma_f32_16x16x32_bf16 v[58:61], v[174:177], v[212:215], v[58:61]
	v_mfma_f32_16x16x32_bf16 v[46:49], v[166:169], v[220:223], v[46:49]
	v_mfma_f32_16x16x32_bf16 v[42:45], v[174:177], v[220:223], v[42:45]
	v_mfma_f32_16x16x32_bf16 v[30:33], v[166:169], v[228:231], v[30:33]
	v_mfma_f32_16x16x32_bf16 v[26:29], v[174:177], v[228:231], v[26:29]
	v_mfma_f32_16x16x32_bf16 v[14:17], v[166:169], v[236:239], v[14:17]
	v_mfma_f32_16x16x32_bf16 v[10:13], v[174:177], v[236:239], v[10:13]
	v_mfma_f32_16x16x32_bf16 v[54:57], v[192:195], v[208:211], v[54:57]
	v_mfma_f32_16x16x32_bf16 v[50:53], v[200:203], v[208:211], v[50:53]
	v_mfma_f32_16x16x32_bf16 v[38:41], v[192:195], v[216:219], v[38:41]
	v_mfma_f32_16x16x32_bf16 v[34:37], v[200:203], v[216:219], v[34:37]
	v_mfma_f32_16x16x32_bf16 v[22:25], v[192:195], v[224:227], v[22:25]
	v_mfma_f32_16x16x32_bf16 v[18:21], v[200:203], v[224:227], v[18:21]
	v_mfma_f32_16x16x32_bf16 v[6:9], v[192:195], v[232:235], v[6:9]
	v_mfma_f32_16x16x32_bf16 v[2:5], v[200:203], v[232:235], v[2:5]
	v_mfma_f32_16x16x32_bf16 v[54:57], v[196:199], v[212:215], v[54:57]
	v_mfma_f32_16x16x32_bf16 v[50:53], v[204:207], v[212:215], v[50:53]
	v_mfma_f32_16x16x32_bf16 v[38:41], v[196:199], v[220:223], v[38:41]
	v_mfma_f32_16x16x32_bf16 v[34:37], v[204:207], v[220:223], v[34:37]
	v_mfma_f32_16x16x32_bf16 v[22:25], v[196:199], v[228:231], v[22:25]
	v_mfma_f32_16x16x32_bf16 v[18:21], v[204:207], v[228:231], v[18:21]
	v_mfma_f32_16x16x32_bf16 v[6:9], v[196:199], v[236:239], v[6:9]
	v_mfma_f32_16x16x32_bf16 v[2:5], v[204:207], v[236:239], v[2:5]
	s_setprio 0
	s_barrier
	s_add_i32 s87, 0, 0x18000
	v_add_u32_e32 v165, s87, v146
	s_add_i32 s93, 0, 0x1c000
	ds_read_b128 v[142:145], v165
	ds_read_b128 v[166:169], v165 offset:1024
	ds_read_b128 v[170:173], v165 offset:2048
	ds_read_b128 v[174:177], v165 offset:3072
	v_add_u32_e32 v165, s93, v146
	ds_read_b128 v[192:195], v165
	ds_read_b128 v[196:199], v165 offset:1024
	ds_read_b128 v[200:203], v165 offset:2048
	ds_read_b128 v[204:207], v165 offset:3072
	s_add_u32 s74, s78, 0xe0000
	s_addc_u32 s75, s79, 0
	s_mov_b32 m0, s80
	v_lshl_add_u64 v[248:249], s[74:75], 0, v[136:137]
	ds_read_b128 v[208:211], v164 offset:32768
	ds_read_b128 v[212:215], v164 offset:33792
	ds_read_b128 v[216:219], v164 offset:34816
	ds_read_b128 v[220:223], v164 offset:35840
	ds_read_b128 v[224:227], v164 offset:36864
	ds_read_b128 v[228:231], v164 offset:37888
	ds_read_b128 v[232:235], v164 offset:38912
	ds_read_b128 v[236:239], v164 offset:39936
	global_load_lds_dwordx4 v[248:249], off
	v_lshl_add_u64 v[248:249], s[74:75], 0, v[132:133]
	s_mov_b32 m0, s81
	s_nop 0
	global_load_lds_dwordx4 v[248:249], off
	s_waitcnt vmcnt(8)
	s_waitcnt lgkmcnt(0)
	s_barrier
	s_setprio 3
	s_waitcnt lgkmcnt(0)
	v_mfma_f32_16x16x32_bf16 v[126:129], v[142:145], v[208:211], v[126:129]
	v_mfma_f32_16x16x32_bf16 v[122:125], v[170:173], v[208:211], v[122:125]
	v_mfma_f32_16x16x32_bf16 v[110:113], v[142:145], v[216:219], v[110:113]
	v_mfma_f32_16x16x32_bf16 v[106:109], v[170:173], v[216:219], v[106:109]
	v_mfma_f32_16x16x32_bf16 v[94:97], v[142:145], v[224:227], v[94:97]
	v_mfma_f32_16x16x32_bf16 v[90:93], v[170:173], v[224:227], v[90:93]
	v_mfma_f32_16x16x32_bf16 v[78:81], v[142:145], v[232:235], v[78:81]
	v_mfma_f32_16x16x32_bf16 v[74:77], v[170:173], v[232:235], v[74:77]
	v_mfma_f32_16x16x32_bf16 v[126:129], v[166:169], v[212:215], v[126:129]
	v_mfma_f32_16x16x32_bf16 v[122:125], v[174:177], v[212:215], v[122:125]
	v_mfma_f32_16x16x32_bf16 v[110:113], v[166:169], v[220:223], v[110:113]
	v_mfma_f32_16x16x32_bf16 v[106:109], v[174:177], v[220:223], v[106:109]
	v_mfma_f32_16x16x32_bf16 v[94:97], v[166:169], v[228:231], v[94:97]
	v_mfma_f32_16x16x32_bf16 v[90:93], v[174:177], v[228:231], v[90:93]
	v_mfma_f32_16x16x32_bf16 v[78:81], v[166:169], v[236:239], v[78:81]
	v_mfma_f32_16x16x32_bf16 v[74:77], v[174:177], v[236:239], v[74:77]
	v_mfma_f32_16x16x32_bf16 v[118:121], v[192:195], v[208:211], v[118:121]
	v_mfma_f32_16x16x32_bf16 v[114:117], v[200:203], v[208:211], v[114:117]
	v_mfma_f32_16x16x32_bf16 v[102:105], v[192:195], v[216:219], v[102:105]
	v_mfma_f32_16x16x32_bf16 v[98:101], v[200:203], v[216:219], v[98:101]
	v_mfma_f32_16x16x32_bf16 v[86:89], v[192:195], v[224:227], v[86:89]
	v_mfma_f32_16x16x32_bf16 v[82:85], v[200:203], v[224:227], v[82:85]
	v_mfma_f32_16x16x32_bf16 v[70:73], v[192:195], v[232:235], v[70:73]
	v_mfma_f32_16x16x32_bf16 v[66:69], v[200:203], v[232:235], v[66:69]
	v_mfma_f32_16x16x32_bf16 v[118:121], v[196:199], v[212:215], v[118:121]
	v_mfma_f32_16x16x32_bf16 v[114:117], v[204:207], v[212:215], v[114:117]
	v_mfma_f32_16x16x32_bf16 v[102:105], v[196:199], v[220:223], v[102:105]
	v_mfma_f32_16x16x32_bf16 v[98:101], v[204:207], v[220:223], v[98:101]
	v_mfma_f32_16x16x32_bf16 v[86:89], v[196:199], v[228:231], v[86:89]
	v_mfma_f32_16x16x32_bf16 v[82:85], v[204:207], v[228:231], v[82:85]
	v_mfma_f32_16x16x32_bf16 v[70:73], v[196:199], v[236:239], v[70:73]
	v_mfma_f32_16x16x32_bf16 v[66:69], v[204:207], v[236:239], v[66:69]
	s_setprio 0
	s_barrier
; #define PG8_STAGE(bufoff, gbase, voff) do { _Pragma("unroll") for (int _i = 0; _i < 2; ++_i) \
;         __builtin_amdgcn_global_load_lds((const unsigned*)((const char*)(gbase) + (voff)[_i]), (LAS unsigned*)(lds + (bufoff) + ldsw + _i * 8192), 16, 0, 0); } while (0)
; #define PG8_LDA(dst, b, h) do { _Pragma("unroll") for (int m = 0; m < 4; ++m) _Pragma("unroll") for (int k = 0; k < 2; ++k) dst[m][k] = *(const LAS bf16x8*)(lds + PG8_SA(b, h) + aoff + m * 2048 + k * 1024); } while (0)
; #define PG8_LDB(dst, b, h) do { _Pragma("unroll") for (int n = 0; n < 2; ++n) _Pragma("unroll") for (int k = 0; k < 2; ++k) dst[n][k] = *(const LAS bf16x8*)(lds + PG8_SB(b, h) + boff + n * 2048 + k * 1024); } while (0)
; #define PG8_BAR __builtin_amdgcn_s_barrier()
;     ...
;             PG8_LDA(At, 1, 1); PG8_STAGE(PG8_SB(1, 0), b3, voffB); PG8_STAGE(PG8_SB(1, 1), b3 + hstepB, voffB); PG8_STAGE(PG8_SA(1, 0), a3, voffA);
;             PG8_WAIT_V(8); PG8_WAIT_L(0); PG8_BAR; PG8_MMA(1, 0, At, B0); PG8_MMA(1, 1, At, B1); PG8_BAR; PG8_SCHED;
;             } else {
;             PG8_LDB(B0, 0, 0); PG8_SCHED; PG8_LDA(At, 0, 0); PG8_STAGE(PG8_SA(1, 1), a1 + hstepA, voffA);
;             PG8_WAIT_L(8); PG8_BAR; PG8_WAIT_L(0); PG8_MMA(0, 0, At, B0); PG8_BAR; PG8_SCHED;
;             PG8_LDB(B1, 0, 1); PG8_STAGE(PG8_SB(0, 0), b2, voffB);
;             PG8_BAR; PG8_WAIT_L(0); PG8_MMA(0, 1, At, B1); PG8_BAR;
;             PG8_LDA(At, 0, 1); PG8_STAGE(PG8_SA(0, 0), a2, voffA);
;             PG8_BAR; PG8_WAIT_L(0); PG8_MMA(1, 0, At, B0); PG8_BAR; PG8_SCHED;
;             PG8_STAGE(PG8_SB(0, 1), b2 + hstepB, voffB);
;             PG8_WAIT_V(6); PG8_BAR; PG8_MMA(1, 1, At, B1); PG8_BAR;
;             PG8_LDB(B0, 1, 0); PG8_SCHED; PG8_LDA(At, 1, 0); PG8_STAGE(PG8_SA(0, 1), a2 + hstepA, voffA);
;             PG8_WAIT_L(8); PG8_BAR; PG8_WAIT_L(0); PG8_MMA(0, 0, At, B0); PG8_BAR; PG8_SCHED;
;             PG8_LDB(B1, 1, 1); PG8_STAGE(PG8_SB(1, 0), b3, voffB);
;             PG8_BAR; PG8_WAIT_L(0); PG8_MMA(0, 1, At, B1); PG8_BAR;
;             PG8_LDA(At, 1, 1); PG8_STAGE(PG8_SA(1, 0), a3, voffA);
;             PG8_BAR; PG8_WAIT_L(0); PG8_MMA(1, 0, At, B0); PG8_BAR; PG8_SCHED;
;             PG8_STAGE(PG8_SB(1, 1), b3 + hstepB, voffB);
;             PG8_WAIT_V(6); PG8_BAR; PG8_MMA(1, 1, At, B1); PG8_BAR;
;             }
;         }
;         if constexpr (ALIGN_EPI) { if (wr == 0) PG8_BAR; }
	s_add_i32 s74, s87, s30
	v_lshl_add_u64 v[240:241], v[240:241], 0, s[46:47]
	s_mov_b32 m0, s74
	ds_read_b128 v[208:211], v164 offset:49152
	ds_read_b128 v[212:215], v164 offset:50176
	ds_read_b128 v[216:219], v164 offset:51200
	ds_read_b128 v[220:223], v164 offset:52224
	ds_read_b128 v[224:227], v164 offset:53248
	ds_read_b128 v[228:231], v164 offset:54272
	ds_read_b128 v[232:235], v164 offset:55296
	ds_read_b128 v[236:239], v164 offset:56320
	global_load_lds_dwordx4 v[240:241], off
	s_add_i32 m0, s74, 0x2000
	s_add_u32 s74, s76, 0x10080
	v_lshl_add_u64 v[240:241], v[242:243], 0, s[46:47]
	s_addc_u32 s75, s77, 0
	s_add_i32 s76, s93, s30
	global_load_lds_dwordx4 v[240:241], off
	v_lshl_add_u64 v[240:241], s[74:75], 0, v[134:135]
	s_mov_b32 m0, s76
	s_nop 0
	global_load_lds_dwordx4 v[240:241], off
	v_lshl_add_u64 v[240:241], s[74:75], 0, v[130:131]
	s_add_i32 m0, s76, 0x2000
	s_nop 0
	global_load_lds_dwordx4 v[240:241], off
	v_lshl_add_u64 v[240:241], v[244:245], 0, s[46:47]
	s_mov_b32 m0, s82
	s_nop 0
	global_load_lds_dwordx4 v[240:241], off
	v_lshl_add_u64 v[240:241], v[246:247], 0, s[46:47]
	s_mov_b32 m0, s83
	s_nop 0
	global_load_lds_dwordx4 v[240:241], off
	s_waitcnt vmcnt(8)
	s_waitcnt lgkmcnt(0)
	s_barrier
	s_setprio 3
	s_waitcnt lgkmcnt(0)
	v_mfma_f32_16x16x32_bf16 v[62:65], v[142:145], v[208:211], v[62:65]
	v_mfma_f32_16x16x32_bf16 v[58:61], v[170:173], v[208:211], v[58:61]
	v_mfma_f32_16x16x32_bf16 v[46:49], v[142:145], v[216:219], v[46:49]
	v_mfma_f32_16x16x32_bf16 v[42:45], v[170:173], v[216:219], v[42:45]
	v_mfma_f32_16x16x32_bf16 v[30:33], v[142:145], v[224:227], v[30:33]
	v_mfma_f32_16x16x32_bf16 v[26:29], v[170:173], v[224:227], v[26:29]
	v_mfma_f32_16x16x32_bf16 v[14:17], v[142:145], v[232:235], v[14:17]
	v_mfma_f32_16x16x32_bf16 v[10:13], v[170:173], v[232:235], v[10:13]
	v_mfma_f32_16x16x32_bf16 v[62:65], v[166:169], v[212:215], v[62:65]
	v_mfma_f32_16x16x32_bf16 v[58:61], v[174:177], v[212:215], v[58:61]
	v_mfma_f32_16x16x32_bf16 v[46:49], v[166:169], v[220:223], v[46:49]
	v_mfma_f32_16x16x32_bf16 v[42:45], v[174:177], v[220:223], v[42:45]
	v_mfma_f32_16x16x32_bf16 v[30:33], v[166:169], v[228:231], v[30:33]
	v_mfma_f32_16x16x32_bf16 v[26:29], v[174:177], v[228:231], v[26:29]
	v_mfma_f32_16x16x32_bf16 v[14:17], v[166:169], v[236:239], v[14:17]
	v_mfma_f32_16x16x32_bf16 v[10:13], v[174:177], v[236:239], v[10:13]
	v_mfma_f32_16x16x32_bf16 v[54:57], v[192:195], v[208:211], v[54:57]
	v_mfma_f32_16x16x32_bf16 v[50:53], v[200:203], v[208:211], v[50:53]
	v_mfma_f32_16x16x32_bf16 v[38:41], v[192:195], v[216:219], v[38:41]
	v_mfma_f32_16x16x32_bf16 v[34:37], v[200:203], v[216:219], v[34:37]
	v_mfma_f32_16x16x32_bf16 v[22:25], v[192:195], v[224:227], v[22:25]
	v_mfma_f32_16x16x32_bf16 v[18:21], v[200:203], v[224:227], v[18:21]
	v_mfma_f32_16x16x32_bf16 v[6:9], v[192:195], v[232:235], v[6:9]
	v_mfma_f32_16x16x32_bf16 v[2:5], v[200:203], v[232:235], v[2:5]
	v_mfma_f32_16x16x32_bf16 v[54:57], v[196:199], v[212:215], v[54:57]
	v_mfma_f32_16x16x32_bf16 v[50:53], v[204:207], v[212:215], v[50:53]
	v_mfma_f32_16x16x32_bf16 v[38:41], v[196:199], v[220:223], v[38:41]
	v_mfma_f32_16x16x32_bf16 v[34:37], v[204:207], v[220:223], v[34:37]
	v_mfma_f32_16x16x32_bf16 v[22:25], v[196:199], v[228:231], v[22:25]
	v_mfma_f32_16x16x32_bf16 v[18:21], v[204:207], v[228:231], v[18:21]
	v_mfma_f32_16x16x32_bf16 v[6:9], v[196:199], v[236:239], v[6:9]
	v_mfma_f32_16x16x32_bf16 v[2:5], v[204:207], v[236:239], v[2:5]
	s_setprio 0
	s_barrier
	s_add_i32 s86, s86, 2
	s_add_u32 s60, s60, 0x100
	s_addc_u32 s61, s61, 0
	s_cmp_gt_u32 s86, 13
	s_mov_b64 s[74:75], s[4:5]
	s_cbranch_scc0 .LBB0_42
	s_and_b64 vcc, exec, s[8:9]
	s_mov_b32 s42, 0x11808
	s_cbranch_vccz .LBB0_45
	s_barrier

; #define PG8_STAGE(bufoff, gbase, voff) do { _Pragma("unroll") for (int _i = 0; _i < 2; ++_i) \
;         __builtin_amdgcn_global_load_lds((const unsigned*)((const char*)(gbase) + (voff)[_i]), (LAS unsigned*)(lds + (bufoff) + ldsw + _i * 8192), 16, 0, 0); } while (0)
; #define PG8_LDA(dst, b, h) do { _Pragma("unroll") for (int m = 0; m < 4; ++m) _Pragma("unroll") for (int k = 0; k < 2; ++k) dst[m][k] = *(const LAS bf16x8*)(lds + PG8_SA(b, h) + aoff + m * 2048 + k * 1024); } while (0)
; #define PG8_LDB(dst, b, h) do { _Pragma("unroll") for (int n = 0; n < 2; ++n) _Pragma("unroll") for (int k = 0; k < 2; ++k) dst[n][k] = *(const LAS bf16x8*)(lds + PG8_SB(b, h) + boff + n * 2048 + k * 1024); } while (0)
; #define PG8_MMA(ai, bj, At, Bt) do { __builtin_amdgcn_s_setprio(3); _Pragma("unroll") for (int m = 0; m < 4; ++m) _Pragma("unroll") for (int n = 0; n < 2; ++n) _Pragma("unroll") for (int k = 0; k < 2; ++k) \
;         acc[ai][bj][m][n] = __builtin_amdgcn_mfma_f32_16x16x32_bf16(Bt[n][k], At[m][k], acc[ai][bj][m][n], 0, 0, 0); __builtin_amdgcn_s_setprio(0); } while (0)
; #define PG8_WAIT_V(n) asm volatile("s_waitcnt vmcnt(" #n ")" ::: "memory")
; #define PG8_WAIT_L(n) asm volatile("s_waitcnt lgkmcnt(" #n ")" ::: "memory")
; #define PG8_BAR __builtin_amdgcn_s_barrier()
; #define PG8_SCHED __builtin_amdgcn_sched_barrier(0)
;     ...
;             PG8_LDB(B0, 0, 0); PG8_LDB(B1, 0, 1); PG8_SCHED; PG8_LDA(At, 0, 0); PG8_STAGE(PG8_SA(1, 1), a1 + hstepA, voffA);
;             PG8_WAIT_V(8); PG8_WAIT_L(0); PG8_BAR; PG8_MMA(0, 0, At, B0); PG8_MMA(0, 1, At, B1); PG8_BAR; PG8_SCHED;
;             PG8_LDA(At, 0, 1); PG8_STAGE(PG8_SB(0, 0), b2, voffB); PG8_STAGE(PG8_SB(0, 1), b2 + hstepB, voffB); PG8_STAGE(PG8_SA(0, 0), a2, voffA);
;             PG8_WAIT_V(8); PG8_WAIT_L(0); PG8_BAR; PG8_MMA(1, 0, At, B0); PG8_MMA(1, 1, At, B1); PG8_BAR; PG8_SCHED;
.LBB0_58:
	s_add_u32 s75, s76, 0xfffc0080
	s_addc_u32 s78, s77, -1
	s_add_i32 s86, 0, 0x10000
	s_cmp_eq_u32 s61, 12
	s_cselect_b32 s81, s11, s78
	s_cselect_b32 s80, s34, s75
	v_add_u32_e32 v144, s86, v146
	s_cselect_b32 s79, s9, s60
	s_cselect_b32 s78, s35, s42
	s_add_i32 s75, 0, 0x14000
	ds_read_b128 v[166:169], v144
	ds_read_b128 v[170:173], v144 offset:1024
	ds_read_b128 v[174:177], v144 offset:2048
	ds_read_b128 v[192:195], v144 offset:3072
	v_add_u32_e32 v144, s75, v146
	ds_read_b128 v[196:199], v144
	ds_read_b128 v[200:203], v144 offset:1024
	ds_read_b128 v[204:207], v144 offset:2048
	ds_read_b128 v[208:211], v144 offset:3072
	v_lshl_add_u64 v[144:145], s[76:77], 0, v[142:143]
	s_add_i32 m0, s30, 0xc000
	ds_read_b128 v[212:215], v164
	ds_read_b128 v[216:219], v164 offset:1024
	ds_read_b128 v[220:223], v164 offset:2048
	ds_read_b128 v[224:227], v164 offset:3072
	ds_read_b128 v[228:231], v164 offset:4096
	ds_read_b128 v[232:235], v164 offset:5120
	ds_read_b128 v[236:239], v164 offset:6144
	ds_read_b128 v[240:243], v164 offset:7168
	global_load_lds_dwordx4 v[144:145], off
	v_lshl_add_u64 v[144:145], s[76:77], 0, v[140:141]
	s_add_i32 m0, s30, 0xe000
	s_nop 0
	global_load_lds_dwordx4 v[144:145], off
	s_waitcnt vmcnt(8)
	s_waitcnt lgkmcnt(0)
	s_barrier
	s_setprio 3
	s_waitcnt lgkmcnt(0)
	v_mfma_f32_16x16x32_bf16 v[126:129], v[166:169], v[212:215], v[126:129]
	v_mfma_f32_16x16x32_bf16 v[122:125], v[174:177], v[212:215], v[122:125]
	v_mfma_f32_16x16x32_bf16 v[110:113], v[166:169], v[220:223], v[110:113]
	v_mfma_f32_16x16x32_bf16 v[106:109], v[174:177], v[220:223], v[106:109]
	v_mfma_f32_16x16x32_bf16 v[94:97], v[166:169], v[228:231], v[94:97]
	v_mfma_f32_16x16x32_bf16 v[90:93], v[174:177], v[228:231], v[90:93]
	v_mfma_f32_16x16x32_bf16 v[78:81], v[166:169], v[236:239], v[78:81]
	v_mfma_f32_16x16x32_bf16 v[74:77], v[174:177], v[236:239], v[74:77]
	v_mfma_f32_16x16x32_bf16 v[126:129], v[170:173], v[216:219], v[126:129]
	v_mfma_f32_16x16x32_bf16 v[122:125], v[192:195], v[216:219], v[122:125]
	v_mfma_f32_16x16x32_bf16 v[110:113], v[170:173], v[224:227], v[110:113]
	v_mfma_f32_16x16x32_bf16 v[106:109], v[192:195], v[224:227], v[106:109]
	v_mfma_f32_16x16x32_bf16 v[94:97], v[170:173], v[232:235], v[94:97]
	v_mfma_f32_16x16x32_bf16 v[90:93], v[192:195], v[232:235], v[90:93]
	v_mfma_f32_16x16x32_bf16 v[78:81], v[170:173], v[240:243], v[78:81]
	v_mfma_f32_16x16x32_bf16 v[74:77], v[192:195], v[240:243], v[74:77]
	v_mfma_f32_16x16x32_bf16 v[118:121], v[196:199], v[212:215], v[118:121]
	v_mfma_f32_16x16x32_bf16 v[114:117], v[204:207], v[212:215], v[114:117]
	v_mfma_f32_16x16x32_bf16 v[102:105], v[196:199], v[220:223], v[102:105]
	v_mfma_f32_16x16x32_bf16 v[98:101], v[204:207], v[220:223], v[98:101]
	v_mfma_f32_16x16x32_bf16 v[86:89], v[196:199], v[228:231], v[86:89]
	v_mfma_f32_16x16x32_bf16 v[82:85], v[204:207], v[228:231], v[82:85]
	v_mfma_f32_16x16x32_bf16 v[70:73], v[196:199], v[236:239], v[70:73]
	v_mfma_f32_16x16x32_bf16 v[66:69], v[204:207], v[236:239], v[66:69]
	v_mfma_f32_16x16x32_bf16 v[118:121], v[200:203], v[216:219], v[118:121]
	v_mfma_f32_16x16x32_bf16 v[114:117], v[208:211], v[216:219], v[114:117]
	v_mfma_f32_16x16x32_bf16 v[102:105], v[200:203], v[224:227], v[102:105]
	v_mfma_f32_16x16x32_bf16 v[98:101], v[208:211], v[224:227], v[98:101]
	v_mfma_f32_16x16x32_bf16 v[86:89], v[200:203], v[232:235], v[86:89]
	v_mfma_f32_16x16x32_bf16 v[82:85], v[208:211], v[232:235], v[82:85]
	v_mfma_f32_16x16x32_bf16 v[70:73], v[200:203], v[240:243], v[70:73]
	v_mfma_f32_16x16x32_bf16 v[66:69], v[208:211], v[240:243], v[66:69]
	s_setprio 0
	s_barrier
	s_add_i32 s86, s86, s17
	v_lshl_add_u64 v[144:145], s[78:79], 0, v[134:135]
	s_mov_b32 m0, s86
	ds_read_b128 v[212:215], v164 offset:16384
	ds_read_b128 v[216:219], v164 offset:17408
	ds_read_b128 v[220:223], v164 offset:18432
	ds_read_b128 v[224:227], v164 offset:19456
	ds_read_b128 v[228:231], v164 offset:20480
	ds_read_b128 v[232:235], v164 offset:21504
	ds_read_b128 v[236:239], v164 offset:22528
	ds_read_b128 v[240:243], v164 offset:23552
	global_load_lds_dwordx4 v[144:145], off
	s_add_i32 m0, s86, 0x2000
	s_add_u32 s86, s78, 0x10000
	v_lshl_add_u64 v[244:245], s[78:79], 0, v[130:131]
	s_addc_u32 s87, s79, 0
	s_add_i32 s75, s75, s17
	global_load_lds_dwordx4 v[244:245], off
	v_lshl_add_u64 v[246:247], s[86:87], 0, v[134:135]
	s_mov_b32 m0, s75
	v_lshl_add_u64 v[248:249], s[80:81], 0, v[132:133]
	global_load_lds_dwordx4 v[246:247], off
	v_lshl_add_u64 v[246:247], s[86:87], 0, v[130:131]
	s_add_i32 m0, s75, 0x2000
	s_nop 0
	global_load_lds_dwordx4 v[246:247], off
	v_lshl_add_u64 v[246:247], s[80:81], 0, v[136:137]
	s_mov_b32 m0, s30
	s_nop 0
	global_load_lds_dwordx4 v[246:247], off
	s_mov_b32 m0, s31
	s_nop 0
	global_load_lds_dwordx4 v[248:249], off
	s_waitcnt vmcnt(8)
	s_waitcnt lgkmcnt(0)
	s_barrier
; #define PG8_STAGE(bufoff, gbase, voff) do { _Pragma("unroll") for (int _i = 0; _i < 2; ++_i) \
;         __builtin_amdgcn_global_load_lds((const unsigned*)((const char*)(gbase) + (voff)[_i]), (LAS unsigned*)(lds + (bufoff) + ldsw + _i * 8192), 16, 0, 0); } while (0)
; #define PG8_LDA(dst, b, h) do { _Pragma("unroll") for (int m = 0; m < 4; ++m) _Pragma("unroll") for (int k = 0; k < 2; ++k) dst[m][k] = *(const LAS bf16x8*)(lds + PG8_SA(b, h) + aoff + m * 2048 + k * 1024); } while (0)
; #define PG8_LDB(dst, b, h) do { _Pragma("unroll") for (int n = 0; n < 2; ++n) _Pragma("unroll") for (int k = 0; k < 2; ++k) dst[n][k] = *(const LAS bf16x8*)(lds + PG8_SB(b, h) + boff + n * 2048 + k * 1024); } while (0)
; #define PG8_MMA(ai, bj, At, Bt) do { __builtin_amdgcn_s_setprio(3); _Pragma("unroll") for (int m = 0; m < 4; ++m) _Pragma("unroll") for (int n = 0; n < 2; ++n) _Pragma("unroll") for (int k = 0; k < 2; ++k) \
;         acc[ai][bj][m][n] = __builtin_amdgcn_mfma_f32_16x16x32_bf16(Bt[n][k], At[m][k], acc[ai][bj][m][n], 0, 0, 0); __builtin_amdgcn_s_setprio(0); } while (0)
; #define PG8_WAIT_V(n) asm volatile("s_waitcnt vmcnt(" #n ")" ::: "memory")
; #define PG8_WAIT_L(n) asm volatile("s_waitcnt lgkmcnt(" #n ")" ::: "memory")
; #define PG8_BAR __builtin_amdgcn_s_barrier()
; #define PG8_SCHED __builtin_amdgcn_sched_barrier(0)
;     ...
;             PG8_WAIT_V(8); PG8_WAIT_L(0); PG8_BAR; PG8_MMA(1, 0, At, B0); PG8_MMA(1, 1, At, B1); PG8_BAR; PG8_SCHED;
;             PG8_LDB(B0, 1, 0); PG8_LDB(B1, 1, 1); PG8_SCHED; PG8_LDA(At, 1, 0); PG8_STAGE(PG8_SA(0, 1), a2 + hstepA, voffA);
;             PG8_WAIT_V(8); PG8_WAIT_L(0); PG8_BAR; PG8_MMA(0, 0, At, B0); PG8_MMA(0, 1, At, B1); PG8_BAR; PG8_SCHED;
;             PG8_LDA(At, 1, 1); PG8_STAGE(PG8_SB(1, 0), b3, voffB); PG8_STAGE(PG8_SB(1, 1), b3 + hstepB, voffB); PG8_STAGE(PG8_SA(1, 0), a3, voffA);
;             PG8_WAIT_V(8); PG8_WAIT_L(0); PG8_BAR; PG8_MMA(1, 0, At, B0); PG8_MMA(1, 1, At, B1); PG8_BAR; PG8_SCHED;
	s_setprio 3
	s_waitcnt lgkmcnt(0)
	v_mfma_f32_16x16x32_bf16 v[62:65], v[166:169], v[212:215], v[62:65]
	v_mfma_f32_16x16x32_bf16 v[58:61], v[174:177], v[212:215], v[58:61]
	v_mfma_f32_16x16x32_bf16 v[46:49], v[166:169], v[220:223], v[46:49]
	v_mfma_f32_16x16x32_bf16 v[42:45], v[174:177], v[220:223], v[42:45]
	v_mfma_f32_16x16x32_bf16 v[30:33], v[166:169], v[228:231], v[30:33]
	v_mfma_f32_16x16x32_bf16 v[26:29], v[174:177], v[228:231], v[26:29]
	v_mfma_f32_16x16x32_bf16 v[14:17], v[166:169], v[236:239], v[14:17]
	v_mfma_f32_16x16x32_bf16 v[10:13], v[174:177], v[236:239], v[10:13]
	v_mfma_f32_16x16x32_bf16 v[62:65], v[170:173], v[216:219], v[62:65]
	v_mfma_f32_16x16x32_bf16 v[58:61], v[192:195], v[216:219], v[58:61]
	v_mfma_f32_16x16x32_bf16 v[46:49], v[170:173], v[224:227], v[46:49]
	v_mfma_f32_16x16x32_bf16 v[42:45], v[192:195], v[224:227], v[42:45]
	v_mfma_f32_16x16x32_bf16 v[30:33], v[170:173], v[232:235], v[30:33]
	v_mfma_f32_16x16x32_bf16 v[26:29], v[192:195], v[232:235], v[26:29]
	v_mfma_f32_16x16x32_bf16 v[14:17], v[170:173], v[240:243], v[14:17]
	v_mfma_f32_16x16x32_bf16 v[10:13], v[192:195], v[240:243], v[10:13]
	v_mfma_f32_16x16x32_bf16 v[54:57], v[196:199], v[212:215], v[54:57]
	v_mfma_f32_16x16x32_bf16 v[50:53], v[204:207], v[212:215], v[50:53]
	v_mfma_f32_16x16x32_bf16 v[38:41], v[196:199], v[220:223], v[38:41]
	v_mfma_f32_16x16x32_bf16 v[34:37], v[204:207], v[220:223], v[34:37]
	v_mfma_f32_16x16x32_bf16 v[22:25], v[196:199], v[228:231], v[22:25]
	v_mfma_f32_16x16x32_bf16 v[18:21], v[204:207], v[228:231], v[18:21]
	v_mfma_f32_16x16x32_bf16 v[6:9], v[196:199], v[236:239], v[6:9]
	v_mfma_f32_16x16x32_bf16 v[2:5], v[204:207], v[236:239], v[2:5]
	v_mfma_f32_16x16x32_bf16 v[54:57], v[200:203], v[216:219], v[54:57]
	v_mfma_f32_16x16x32_bf16 v[50:53], v[208:211], v[216:219], v[50:53]
	v_mfma_f32_16x16x32_bf16 v[38:41], v[200:203], v[224:227], v[38:41]
	v_mfma_f32_16x16x32_bf16 v[34:37], v[208:211], v[224:227], v[34:37]
	v_mfma_f32_16x16x32_bf16 v[22:25], v[200:203], v[232:235], v[22:25]
	v_mfma_f32_16x16x32_bf16 v[18:21], v[208:211], v[232:235], v[18:21]
	v_mfma_f32_16x16x32_bf16 v[6:9], v[200:203], v[240:243], v[6:9]
	v_mfma_f32_16x16x32_bf16 v[2:5], v[208:211], v[240:243], v[2:5]
	s_setprio 0
	s_barrier
	s_add_i32 s75, 0, 0x18000
	v_add_u32_e32 v165, s75, v146
	s_add_i32 s86, 0, 0x1c000
	ds_read_b128 v[166:169], v165
	ds_read_b128 v[170:173], v165 offset:1024
	ds_read_b128 v[174:177], v165 offset:2048
	ds_read_b128 v[192:195], v165 offset:3072
	v_add_u32_e32 v165, s86, v146
	ds_read_b128 v[196:199], v165
	ds_read_b128 v[200:203], v165 offset:1024
	ds_read_b128 v[204:207], v165 offset:2048
	ds_read_b128 v[208:211], v165 offset:3072
	s_add_u32 s80, s80, 0x40000
	s_addc_u32 s81, s81, 0
	s_mov_b32 m0, s68
	v_lshl_add_u64 v[250:251], s[80:81], 0, v[136:137]
	ds_read_b128 v[212:215], v164 offset:32768
	ds_read_b128 v[216:219], v164 offset:33792
	ds_read_b128 v[220:223], v164 offset:34816
	ds_read_b128 v[224:227], v164 offset:35840
	ds_read_b128 v[228:231], v164 offset:36864
	ds_read_b128 v[232:235], v164 offset:37888
	ds_read_b128 v[236:239], v164 offset:38912
	ds_read_b128 v[240:243], v164 offset:39936
	global_load_lds_dwordx4 v[250:251], off
	v_lshl_add_u64 v[250:251], s[80:81], 0, v[132:133]
	s_mov_b32 m0, s69
	s_nop 0
	global_load_lds_dwordx4 v[250:251], off
	s_waitcnt vmcnt(8)
	s_waitcnt lgkmcnt(0)
	s_barrier
	s_setprio 3
	s_waitcnt lgkmcnt(0)
	v_mfma_f32_16x16x32_bf16 v[126:129], v[166:169], v[212:215], v[126:129]
	v_mfma_f32_16x16x32_bf16 v[122:125], v[174:177], v[212:215], v[122:125]
	v_mfma_f32_16x16x32_bf16 v[110:113], v[166:169], v[220:223], v[110:113]
	v_mfma_f32_16x16x32_bf16 v[106:109], v[174:177], v[220:223], v[106:109]
	v_mfma_f32_16x16x32_bf16 v[94:97], v[166:169], v[228:231], v[94:97]
	v_mfma_f32_16x16x32_bf16 v[90:93], v[174:177], v[228:231], v[90:93]
	v_mfma_f32_16x16x32_bf16 v[78:81], v[166:169], v[236:239], v[78:81]
	v_mfma_f32_16x16x32_bf16 v[74:77], v[174:177], v[236:239], v[74:77]
	v_mfma_f32_16x16x32_bf16 v[126:129], v[170:173], v[216:219], v[126:129]
	v_mfma_f32_16x16x32_bf16 v[122:125], v[192:195], v[216:219], v[122:125]
	v_mfma_f32_16x16x32_bf16 v[110:113], v[170:173], v[224:227], v[110:113]
	v_mfma_f32_16x16x32_bf16 v[106:109], v[192:195], v[224:227], v[106:109]
	v_mfma_f32_16x16x32_bf16 v[94:97], v[170:173], v[232:235], v[94:97]
	v_mfma_f32_16x16x32_bf16 v[90:93], v[192:195], v[232:235], v[90:93]
	v_mfma_f32_16x16x32_bf16 v[78:81], v[170:173], v[240:243], v[78:81]
	v_mfma_f32_16x16x32_bf16 v[74:77], v[192:195], v[240:243], v[74:77]
	v_mfma_f32_16x16x32_bf16 v[118:121], v[196:199], v[212:215], v[118:121]
	v_mfma_f32_16x16x32_bf16 v[114:117], v[204:207], v[212:215], v[114:117]
	v_mfma_f32_16x16x32_bf16 v[102:105], v[196:199], v[220:223], v[102:105]
	v_mfma_f32_16x16x32_bf16 v[98:101], v[204:207], v[220:223], v[98:101]
	v_mfma_f32_16x16x32_bf16 v[86:89], v[196:199], v[228:231], v[86:89]
	v_mfma_f32_16x16x32_bf16 v[82:85], v[204:207], v[228:231], v[82:85]
	v_mfma_f32_16x16x32_bf16 v[70:73], v[196:199], v[236:239], v[70:73]
	v_mfma_f32_16x16x32_bf16 v[66:69], v[204:207], v[236:239], v[66:69]
	v_mfma_f32_16x16x32_bf16 v[118:121], v[200:203], v[216:219], v[118:121]
	v_mfma_f32_16x16x32_bf16 v[114:117], v[208:211], v[216:219], v[114:117]
	v_mfma_f32_16x16x32_bf16 v[102:105], v[200:203], v[224:227], v[102:105]
	v_mfma_f32_16x16x32_bf16 v[98:101], v[208:211], v[224:227], v[98:101]
	v_mfma_f32_16x16x32_bf16 v[86:89], v[200:203], v[232:235], v[86:89]
	v_mfma_f32_16x16x32_bf16 v[82:85], v[208:211], v[232:235], v[82:85]
	v_mfma_f32_16x16x32_bf16 v[70:73], v[200:203], v[240:243], v[70:73]
	v_mfma_f32_16x16x32_bf16 v[66:69], v[208:211], v[240:243], v[66:69]
	s_setprio 0
	s_barrier
; #define PG8_STAGE(bufoff, gbase, voff) do { _Pragma("unroll") for (int _i = 0; _i < 2; ++_i) \
;         __builtin_amdgcn_global_load_lds((const unsigned*)((const char*)(gbase) + (voff)[_i]), (LAS unsigned*)(lds + (bufoff) + ldsw + _i * 8192), 16, 0, 0); } while (0)
; #define PG8_LDA(dst, b, h) do { _Pragma("unroll") for (int m = 0; m < 4; ++m) _Pragma("unroll") for (int k = 0; k < 2; ++k) dst[m][k] = *(const LAS bf16x8*)(lds + PG8_SA(b, h) + aoff + m * 2048 + k * 1024); } while (0)
; #define PG8_MMA(ai, bj, At, Bt) do { __builtin_amdgcn_s_setprio(3); _Pragma("unroll") for (int m = 0; m < 4; ++m) _Pragma("unroll") for (int n = 0; n < 2; ++n) _Pragma("unroll") for (int k = 0; k < 2; ++k) \
;         acc[ai][bj][m][n] = __builtin_amdgcn_mfma_f32_16x16x32_bf16(Bt[n][k], At[m][k], acc[ai][bj][m][n], 0, 0, 0); __builtin_amdgcn_s_setprio(0); } while (0)
; #define PG8_WAIT_V(n) asm volatile("s_waitcnt vmcnt(" #n ")" ::: "memory")
; #define PG8_WAIT_L(n) asm volatile("s_waitcnt lgkmcnt(" #n ")" ::: "memory")
; #define PG8_BAR __builtin_amdgcn_s_barrier()
; #define PG8_SCHED __builtin_amdgcn_sched_barrier(0)
; __device__ __forceinline__ float row_rs4(const float* ssq, int row, int fq) {
;     const f32x4 a = *(const f32x4*)(ssq + (size_t)row * 16 + fq * 4);
;     float s = (a[0] + a[1]) + (a[2] + a[3]);
;     s += __shfl_xor(s, 16); s += __shfl_xor(s, 32);
;     ...
;             PG8_LDA(At, 1, 1); PG8_STAGE(PG8_SB(1, 0), b3, voffB); PG8_STAGE(PG8_SB(1, 1), b3 + hstepB, voffB); PG8_STAGE(PG8_SA(1, 0), a3, voffA);
;             PG8_WAIT_V(8); PG8_WAIT_L(0); PG8_BAR; PG8_MMA(1, 0, At, B0); PG8_MMA(1, 1, At, B1); PG8_BAR; PG8_SCHED;
	s_add_i32 s75, s75, s17
	v_lshl_add_u64 v[144:145], v[144:145], 0, s[46:47]
	s_mov_b32 m0, s75
	ds_read_b128 v[212:215], v164 offset:49152
	ds_read_b128 v[216:219], v164 offset:50176
	ds_read_b128 v[220:223], v164 offset:51200
	ds_read_b128 v[224:227], v164 offset:52224
	ds_read_b128 v[228:231], v164 offset:53248
	ds_read_b128 v[232:235], v164 offset:54272
	ds_read_b128 v[236:239], v164 offset:55296
	ds_read_b128 v[240:243], v164 offset:56320
	global_load_lds_dwordx4 v[144:145], off
	s_add_i32 m0, s75, 0x2000
	s_add_u32 s78, s78, 0x10080
	v_lshl_add_u64 v[144:145], v[244:245], 0, s[46:47]
	s_addc_u32 s79, s79, 0
	s_add_i32 s75, s86, s17
	global_load_lds_dwordx4 v[144:145], off
	v_lshl_add_u64 v[144:145], s[78:79], 0, v[134:135]
	s_mov_b32 m0, s75
	s_nop 0
	global_load_lds_dwordx4 v[144:145], off
	v_lshl_add_u64 v[144:145], s[78:79], 0, v[130:131]
	s_add_i32 m0, s75, 0x2000
	s_nop 0
	global_load_lds_dwordx4 v[144:145], off
	v_lshl_add_u64 v[144:145], v[246:247], 0, s[46:47]
	s_mov_b32 m0, s82
	s_nop 0
	global_load_lds_dwordx4 v[144:145], off
	v_lshl_add_u64 v[144:145], v[248:249], 0, s[46:47]
	s_mov_b32 m0, s83
	s_nop 0
	global_load_lds_dwordx4 v[144:145], off
	s_waitcnt vmcnt(8)
	s_waitcnt lgkmcnt(0)
	s_barrier
	s_setprio 3
	s_waitcnt lgkmcnt(0)
	v_mfma_f32_16x16x32_bf16 v[62:65], v[166:169], v[212:215], v[62:65]
	v_mfma_f32_16x16x32_bf16 v[58:61], v[174:177], v[212:215], v[58:61]
	v_mfma_f32_16x16x32_bf16 v[46:49], v[166:169], v[220:223], v[46:49]
	v_mfma_f32_16x16x32_bf16 v[42:45], v[174:177], v[220:223], v[42:45]
	v_mfma_f32_16x16x32_bf16 v[30:33], v[166:169], v[228:231], v[30:33]
	v_mfma_f32_16x16x32_bf16 v[26:29], v[174:177], v[228:231], v[26:29]
	v_mfma_f32_16x16x32_bf16 v[14:17], v[166:169], v[236:239], v[14:17]
	v_mfma_f32_16x16x32_bf16 v[10:13], v[174:177], v[236:239], v[10:13]
	v_mfma_f32_16x16x32_bf16 v[62:65], v[170:173], v[216:219], v[62:65]
	v_mfma_f32_16x16x32_bf16 v[58:61], v[192:195], v[216:219], v[58:61]
	v_mfma_f32_16x16x32_bf16 v[46:49], v[170:173], v[224:227], v[46:49]
	v_mfma_f32_16x16x32_bf16 v[42:45], v[192:195], v[224:227], v[42:45]
	v_mfma_f32_16x16x32_bf16 v[30:33], v[170:173], v[232:235], v[30:33]
	v_mfma_f32_16x16x32_bf16 v[26:29], v[192:195], v[232:235], v[26:29]
	v_mfma_f32_16x16x32_bf16 v[14:17], v[170:173], v[240:243], v[14:17]
	v_mfma_f32_16x16x32_bf16 v[10:13], v[192:195], v[240:243], v[10:13]
	v_mfma_f32_16x16x32_bf16 v[54:57], v[196:199], v[212:215], v[54:57]
	v_mfma_f32_16x16x32_bf16 v[50:53], v[204:207], v[212:215], v[50:53]
	v_mfma_f32_16x16x32_bf16 v[38:41], v[196:199], v[220:223], v[38:41]
	v_mfma_f32_16x16x32_bf16 v[34:37], v[204:207], v[220:223], v[34:37]
	v_mfma_f32_16x16x32_bf16 v[22:25], v[196:199], v[228:231], v[22:25]
	v_mfma_f32_16x16x32_bf16 v[18:21], v[204:207], v[228:231], v[18:21]
	v_mfma_f32_16x16x32_bf16 v[6:9], v[196:199], v[236:239], v[6:9]
	v_mfma_f32_16x16x32_bf16 v[2:5], v[204:207], v[236:239], v[2:5]
	v_mfma_f32_16x16x32_bf16 v[54:57], v[200:203], v[216:219], v[54:57]
	v_mfma_f32_16x16x32_bf16 v[50:53], v[208:211], v[216:219], v[50:53]
	v_mfma_f32_16x16x32_bf16 v[38:41], v[200:203], v[224:227], v[38:41]
	v_mfma_f32_16x16x32_bf16 v[34:37], v[208:211], v[224:227], v[34:37]
	v_mfma_f32_16x16x32_bf16 v[22:25], v[200:203], v[232:235], v[22:25]
	v_mfma_f32_16x16x32_bf16 v[18:21], v[208:211], v[232:235], v[18:21]
	v_mfma_f32_16x16x32_bf16 v[6:9], v[200:203], v[240:243], v[6:9]
	v_mfma_f32_16x16x32_bf16 v[2:5], v[208:211], v[240:243], v[2:5]
	s_setprio 0
	s_barrier
	s_add_i32 s61, s61, 2
	s_add_u32 s42, s42, 0x100
	s_addc_u32 s60, s60, 0
	s_add_u32 s76, s76, 0x100
	s_addc_u32 s77, s77, 0
	s_cmp_gt_u32 s61, 13
	s_cbranch_scc0 .LBB0_58
	v_lshl_add_u32 v232, s74, 8, v1
	v_ashrrev_i32_e32 v233, 31, v232
	v_lshlrev_b64 v[234:235], 6, v[232:233]
	v_lshl_add_u64 v[234:235], v[138:139], 0, v[234:235]
	global_load_dwordx4 v[192:195], v[234:235], off
	global_load_dwordx4 v[196:199], v[234:235], off offset:1024
	global_load_dwordx4 v[200:203], v[234:235], off offset:2048
	global_load_dwordx4 v[204:207], v[234:235], off offset:3072
	v_add_u32_e32 v232, 0x80, v232
	v_ashrrev_i32_e32 v233, 31, v232
	v_lshlrev_b64 v[234:235], 6, v[232:233]
	v_lshl_add_u64 v[234:235], v[138:139], 0, v[234:235]
	global_load_dwordx4 v[208:211], v[234:235], off
	global_load_dwordx4 v[212:215], v[234:235], off offset:1024
	global_load_dwordx4 v[216:219], v[234:235], off offset:2048
	global_load_dwordx4 v[220:223], v[234:235], off offset:3072
	v_xor_b32_e32 v176, 16, v182
	v_xor_b32_e32 v177, 32, v182
	v_lshlrev_b32_e32 v176, 2, v176
	v_lshlrev_b32_e32 v177, 2, v177
	s_and_b64 vcc, exec, s[6:7]
	s_cbranch_vccz .LBB0_61
	s_barrier

; #define PG8_STAGE(bufoff, gbase, voff) do { _Pragma("unroll") for (int _i = 0; _i < 2; ++_i) \
;         __builtin_amdgcn_global_load_lds((const unsigned*)((const char*)(gbase) + (voff)[_i]), (LAS unsigned*)(lds + (bufoff) + ldsw + _i * 8192), 16, 0, 0); } while (0)
; #define PG8_LDA(dst, b, h) do { _Pragma("unroll") for (int m = 0; m < 4; ++m) _Pragma("unroll") for (int k = 0; k < 2; ++k) dst[m][k] = *(const LAS bf16x8*)(lds + PG8_SA(b, h) + aoff + m * 2048 + k * 1024); } while (0)
; #define PG8_LDB(dst, b, h) do { _Pragma("unroll") for (int n = 0; n < 2; ++n) _Pragma("unroll") for (int k = 0; k < 2; ++k) dst[n][k] = *(const LAS bf16x8*)(lds + PG8_SB(b, h) + boff + n * 2048 + k * 1024); } while (0)
; #define PG8_MMA(ai, bj, At, Bt) do { __builtin_amdgcn_s_setprio(3); _Pragma("unroll") for (int m = 0; m < 4; ++m) _Pragma("unroll") for (int n = 0; n < 2; ++n) _Pragma("unroll") for (int k = 0; k < 2; ++k) \
;         acc[ai][bj][m][n] = __builtin_amdgcn_mfma_f32_16x16x32_bf16(Bt[n][k], At[m][k], acc[ai][bj][m][n], 0, 0, 0); __builtin_amdgcn_s_setprio(0); } while (0)
; #define PG8_WAIT_V(n) asm volatile("s_waitcnt vmcnt(" #n ")" ::: "memory")
; #define PG8_WAIT_L(n) asm volatile("s_waitcnt lgkmcnt(" #n ")" ::: "memory")
; #define PG8_BAR __builtin_amdgcn_s_barrier()
; #define PG8_SCHED __builtin_amdgcn_sched_barrier(0)
;     ...
;             PG8_LDB(B0, 0, 0); PG8_LDB(B1, 0, 1); PG8_SCHED; PG8_LDA(At, 0, 0); PG8_STAGE(PG8_SA(1, 1), a1 + hstepA, voffA);
;             PG8_WAIT_V(8); PG8_WAIT_L(0); PG8_BAR; PG8_MMA(0, 0, At, B0); PG8_MMA(0, 1, At, B1); PG8_BAR; PG8_SCHED;
;             PG8_LDA(At, 0, 1); PG8_STAGE(PG8_SB(0, 0), b2, voffB); PG8_STAGE(PG8_SB(0, 1), b2 + hstepB, voffB); PG8_STAGE(PG8_SA(0, 0), a2, voffA);
;             PG8_WAIT_V(8); PG8_WAIT_L(0); PG8_BAR; PG8_MMA(1, 0, At, B0); PG8_MMA(1, 1, At, B1); PG8_BAR; PG8_SCHED;
.LBB0_79:
	s_add_u32 s60, s80, 0xfffc0080
	s_addc_u32 s61, s81, -1
	s_add_i32 s73, 0, 0x10000
	s_cmp_eq_u32 s42, 12
	s_cselect_b32 s85, s5, s61
	s_cselect_b32 s84, s19, s60
	v_add_u32_e32 v168, s73, v170
	s_cselect_b32 s83, s11, s40
	s_cselect_b32 s82, s34, s35
	s_add_i32 s79, 0, 0x14000
	ds_read_b128 v[144:147], v168
	ds_read_b128 v[164:167], v168 offset:1024
	ds_read_b128 v[174:177], v168 offset:2048
	ds_read_b128 v[192:195], v168 offset:3072
	v_add_u32_e32 v168, s79, v170
	ds_read_b128 v[196:199], v168
	ds_read_b128 v[200:203], v168 offset:1024
	ds_read_b128 v[204:207], v168 offset:2048
	ds_read_b128 v[208:211], v168 offset:3072
	v_lshl_add_u64 v[168:169], s[80:81], 0, v[142:143]
	s_add_i32 m0, s71, 0xc000
	ds_read_b128 v[212:215], v172
	ds_read_b128 v[216:219], v172 offset:1024
	ds_read_b128 v[220:223], v172 offset:2048
	ds_read_b128 v[224:227], v172 offset:3072
	ds_read_b128 v[228:231], v172 offset:4096
	ds_read_b128 v[232:235], v172 offset:5120
	ds_read_b128 v[236:239], v172 offset:6144
	ds_read_b128 v[240:243], v172 offset:7168
	global_load_lds_dwordx4 v[168:169], off
	v_lshl_add_u64 v[168:169], s[80:81], 0, v[140:141]
	s_add_i32 m0, s71, 0xe000
	s_nop 0
	global_load_lds_dwordx4 v[168:169], off
	s_waitcnt vmcnt(8)
	s_waitcnt lgkmcnt(0)
	s_barrier
	s_setprio 3
	s_waitcnt lgkmcnt(0)
	v_mfma_f32_16x16x32_bf16 v[126:129], v[144:147], v[212:215], v[126:129]
	v_mfma_f32_16x16x32_bf16 v[122:125], v[174:177], v[212:215], v[122:125]
	v_mfma_f32_16x16x32_bf16 v[110:113], v[144:147], v[220:223], v[110:113]
	v_mfma_f32_16x16x32_bf16 v[106:109], v[174:177], v[220:223], v[106:109]
	v_mfma_f32_16x16x32_bf16 v[94:97], v[144:147], v[228:231], v[94:97]
	v_mfma_f32_16x16x32_bf16 v[90:93], v[174:177], v[228:231], v[90:93]
	v_mfma_f32_16x16x32_bf16 v[78:81], v[144:147], v[236:239], v[78:81]
	v_mfma_f32_16x16x32_bf16 v[74:77], v[174:177], v[236:239], v[74:77]
	v_mfma_f32_16x16x32_bf16 v[126:129], v[164:167], v[216:219], v[126:129]
	v_mfma_f32_16x16x32_bf16 v[122:125], v[192:195], v[216:219], v[122:125]
	v_mfma_f32_16x16x32_bf16 v[110:113], v[164:167], v[224:227], v[110:113]
	v_mfma_f32_16x16x32_bf16 v[106:109], v[192:195], v[224:227], v[106:109]
	v_mfma_f32_16x16x32_bf16 v[94:97], v[164:167], v[232:235], v[94:97]
	v_mfma_f32_16x16x32_bf16 v[90:93], v[192:195], v[232:235], v[90:93]
	v_mfma_f32_16x16x32_bf16 v[78:81], v[164:167], v[240:243], v[78:81]
	v_mfma_f32_16x16x32_bf16 v[74:77], v[192:195], v[240:243], v[74:77]
	v_mfma_f32_16x16x32_bf16 v[118:121], v[196:199], v[212:215], v[118:121]
	v_mfma_f32_16x16x32_bf16 v[114:117], v[204:207], v[212:215], v[114:117]
	v_mfma_f32_16x16x32_bf16 v[102:105], v[196:199], v[220:223], v[102:105]
	v_mfma_f32_16x16x32_bf16 v[98:101], v[204:207], v[220:223], v[98:101]
	v_mfma_f32_16x16x32_bf16 v[86:89], v[196:199], v[228:231], v[86:89]
	v_mfma_f32_16x16x32_bf16 v[82:85], v[204:207], v[228:231], v[82:85]
	v_mfma_f32_16x16x32_bf16 v[70:73], v[196:199], v[236:239], v[70:73]
	v_mfma_f32_16x16x32_bf16 v[66:69], v[204:207], v[236:239], v[66:69]
	v_mfma_f32_16x16x32_bf16 v[118:121], v[200:203], v[216:219], v[118:121]
	v_mfma_f32_16x16x32_bf16 v[114:117], v[208:211], v[216:219], v[114:117]
	v_mfma_f32_16x16x32_bf16 v[102:105], v[200:203], v[224:227], v[102:105]
	v_mfma_f32_16x16x32_bf16 v[98:101], v[208:211], v[224:227], v[98:101]
	v_mfma_f32_16x16x32_bf16 v[86:89], v[200:203], v[232:235], v[86:89]
	v_mfma_f32_16x16x32_bf16 v[82:85], v[208:211], v[232:235], v[82:85]
	v_mfma_f32_16x16x32_bf16 v[70:73], v[200:203], v[240:243], v[70:73]
	v_mfma_f32_16x16x32_bf16 v[66:69], v[208:211], v[240:243], v[66:69]
	s_setprio 0
	s_barrier
	s_add_i32 s60, s73, s70
	v_lshl_add_u64 v[168:169], s[82:83], 0, v[132:133]
	s_mov_b32 m0, s60
	ds_read_b128 v[212:215], v172 offset:16384
	ds_read_b128 v[216:219], v172 offset:17408
	ds_read_b128 v[220:223], v172 offset:18432
	ds_read_b128 v[224:227], v172 offset:19456
	ds_read_b128 v[228:231], v172 offset:20480
	ds_read_b128 v[232:235], v172 offset:21504
	ds_read_b128 v[236:239], v172 offset:22528
	ds_read_b128 v[240:243], v172 offset:23552
	global_load_lds_dwordx4 v[168:169], off
	s_add_i32 m0, s60, 0x2000
	s_add_u32 s60, s82, 0x10000
	v_lshl_add_u64 v[244:245], s[82:83], 0, v[136:137]
	s_addc_u32 s61, s83, 0
	s_add_i32 s73, s79, s70
	global_load_lds_dwordx4 v[244:245], off
	v_lshl_add_u64 v[246:247], s[60:61], 0, v[132:133]
	s_mov_b32 m0, s73
	v_lshl_add_u64 v[248:249], s[84:85], 0, v[134:135]
	global_load_lds_dwordx4 v[246:247], off
	v_lshl_add_u64 v[246:247], s[60:61], 0, v[136:137]
	s_add_i32 m0, s73, 0x2000
	s_nop 0
	global_load_lds_dwordx4 v[246:247], off
	v_lshl_add_u64 v[246:247], s[84:85], 0, v[130:131]
	s_mov_b32 m0, s71
	s_nop 0
	global_load_lds_dwordx4 v[246:247], off
	s_mov_b32 m0, s6
	s_nop 0
	global_load_lds_dwordx4 v[248:249], off
	s_waitcnt vmcnt(8)
	s_waitcnt lgkmcnt(0)
	s_barrier
; #define PG8_STAGE(bufoff, gbase, voff) do { _Pragma("unroll") for (int _i = 0; _i < 2; ++_i) \
;         __builtin_amdgcn_global_load_lds((const unsigned*)((const char*)(gbase) + (voff)[_i]), (LAS unsigned*)(lds + (bufoff) + ldsw + _i * 8192), 16, 0, 0); } while (0)
; #define PG8_LDA(dst, b, h) do { _Pragma("unroll") for (int m = 0; m < 4; ++m) _Pragma("unroll") for (int k = 0; k < 2; ++k) dst[m][k] = *(const LAS bf16x8*)(lds + PG8_SA(b, h) + aoff + m * 2048 + k * 1024); } while (0)
; #define PG8_LDB(dst, b, h) do { _Pragma("unroll") for (int n = 0; n < 2; ++n) _Pragma("unroll") for (int k = 0; k < 2; ++k) dst[n][k] = *(const LAS bf16x8*)(lds + PG8_SB(b, h) + boff + n * 2048 + k * 1024); } while (0)
; #define PG8_MMA(ai, bj, At, Bt) do { __builtin_amdgcn_s_setprio(3); _Pragma("unroll") for (int m = 0; m < 4; ++m) _Pragma("unroll") for (int n = 0; n < 2; ++n) _Pragma("unroll") for (int k = 0; k < 2; ++k) \
;         acc[ai][bj][m][n] = __builtin_amdgcn_mfma_f32_16x16x32_bf16(Bt[n][k], At[m][k], acc[ai][bj][m][n], 0, 0, 0); __builtin_amdgcn_s_setprio(0); } while (0)
; #define PG8_WAIT_V(n) asm volatile("s_waitcnt vmcnt(" #n ")" ::: "memory")
; #define PG8_WAIT_L(n) asm volatile("s_waitcnt lgkmcnt(" #n ")" ::: "memory")
; #define PG8_BAR __builtin_amdgcn_s_barrier()
; #define PG8_SCHED __builtin_amdgcn_sched_barrier(0)
;     ...
;             PG8_WAIT_V(8); PG8_WAIT_L(0); PG8_BAR; PG8_MMA(1, 0, At, B0); PG8_MMA(1, 1, At, B1); PG8_BAR; PG8_SCHED;
;             PG8_LDB(B0, 1, 0); PG8_LDB(B1, 1, 1); PG8_SCHED; PG8_LDA(At, 1, 0); PG8_STAGE(PG8_SA(0, 1), a2 + hstepA, voffA);
;             PG8_WAIT_V(8); PG8_WAIT_L(0); PG8_BAR; PG8_MMA(0, 0, At, B0); PG8_MMA(0, 1, At, B1); PG8_BAR; PG8_SCHED;
	s_setprio 3
	s_waitcnt lgkmcnt(0)
	v_mfma_f32_16x16x32_bf16 v[62:65], v[144:147], v[212:215], v[62:65]
	v_mfma_f32_16x16x32_bf16 v[58:61], v[174:177], v[212:215], v[58:61]
	v_mfma_f32_16x16x32_bf16 v[46:49], v[144:147], v[220:223], v[46:49]
	v_mfma_f32_16x16x32_bf16 v[42:45], v[174:177], v[220:223], v[42:45]
	v_mfma_f32_16x16x32_bf16 v[30:33], v[144:147], v[228:231], v[30:33]
	v_mfma_f32_16x16x32_bf16 v[26:29], v[174:177], v[228:231], v[26:29]
	v_mfma_f32_16x16x32_bf16 v[14:17], v[144:147], v[236:239], v[14:17]
	v_mfma_f32_16x16x32_bf16 v[10:13], v[174:177], v[236:239], v[10:13]
	v_mfma_f32_16x16x32_bf16 v[62:65], v[164:167], v[216:219], v[62:65]
	v_mfma_f32_16x16x32_bf16 v[58:61], v[192:195], v[216:219], v[58:61]
	v_mfma_f32_16x16x32_bf16 v[46:49], v[164:167], v[224:227], v[46:49]
	v_mfma_f32_16x16x32_bf16 v[42:45], v[192:195], v[224:227], v[42:45]
	v_mfma_f32_16x16x32_bf16 v[30:33], v[164:167], v[232:235], v[30:33]
	v_mfma_f32_16x16x32_bf16 v[26:29], v[192:195], v[232:235], v[26:29]
	v_mfma_f32_16x16x32_bf16 v[14:17], v[164:167], v[240:243], v[14:17]
	v_mfma_f32_16x16x32_bf16 v[10:13], v[192:195], v[240:243], v[10:13]
	v_mfma_f32_16x16x32_bf16 v[54:57], v[196:199], v[212:215], v[54:57]
	v_mfma_f32_16x16x32_bf16 v[50:53], v[204:207], v[212:215], v[50:53]
	v_mfma_f32_16x16x32_bf16 v[38:41], v[196:199], v[220:223], v[38:41]
	v_mfma_f32_16x16x32_bf16 v[34:37], v[204:207], v[220:223], v[34:37]
	v_mfma_f32_16x16x32_bf16 v[22:25], v[196:199], v[228:231], v[22:25]
	v_mfma_f32_16x16x32_bf16 v[18:21], v[204:207], v[228:231], v[18:21]
	v_mfma_f32_16x16x32_bf16 v[6:9], v[196:199], v[236:239], v[6:9]
	v_mfma_f32_16x16x32_bf16 v[2:5], v[204:207], v[236:239], v[2:5]
	v_mfma_f32_16x16x32_bf16 v[54:57], v[200:203], v[216:219], v[54:57]
	v_mfma_f32_16x16x32_bf16 v[50:53], v[208:211], v[216:219], v[50:53]
	v_mfma_f32_16x16x32_bf16 v[38:41], v[200:203], v[224:227], v[38:41]
	v_mfma_f32_16x16x32_bf16 v[34:37], v[208:211], v[224:227], v[34:37]
	v_mfma_f32_16x16x32_bf16 v[22:25], v[200:203], v[232:235], v[22:25]
	v_mfma_f32_16x16x32_bf16 v[18:21], v[208:211], v[232:235], v[18:21]
	v_mfma_f32_16x16x32_bf16 v[6:9], v[200:203], v[240:243], v[6:9]
	v_mfma_f32_16x16x32_bf16 v[2:5], v[208:211], v[240:243], v[2:5]
	s_setprio 0
	s_barrier
	s_add_i32 s73, 0, 0x18000
	v_add_u32_e32 v173, s73, v170
	s_add_i32 s79, 0, 0x1c000
	ds_read_b128 v[144:147], v173
	ds_read_b128 v[164:167], v173 offset:1024
	ds_read_b128 v[174:177], v173 offset:2048
	ds_read_b128 v[192:195], v173 offset:3072
	v_add_u32_e32 v173, s79, v170
	ds_read_b128 v[196:199], v173
	ds_read_b128 v[200:203], v173 offset:1024
	ds_read_b128 v[204:207], v173 offset:2048
	ds_read_b128 v[208:211], v173 offset:3072
	s_add_u32 s60, s84, 0x40000
	s_addc_u32 s61, s85, 0
	s_mov_b32 m0, s7
	v_lshl_add_u64 v[250:251], s[60:61], 0, v[130:131]
	ds_read_b128 v[212:215], v172 offset:32768
	ds_read_b128 v[216:219], v172 offset:33792
	ds_read_b128 v[220:223], v172 offset:34816
	ds_read_b128 v[224:227], v172 offset:35840
	ds_read_b128 v[228:231], v172 offset:36864
	ds_read_b128 v[232:235], v172 offset:37888
	ds_read_b128 v[236:239], v172 offset:38912
	ds_read_b128 v[240:243], v172 offset:39936
	global_load_lds_dwordx4 v[250:251], off
	v_lshl_add_u64 v[250:251], s[60:61], 0, v[134:135]
	s_mov_b32 m0, s18
	s_nop 0
	global_load_lds_dwordx4 v[250:251], off
	s_waitcnt vmcnt(8)
	s_waitcnt lgkmcnt(0)
	s_barrier
	s_setprio 3
	s_waitcnt lgkmcnt(0)
	v_mfma_f32_16x16x32_bf16 v[126:129], v[144:147], v[212:215], v[126:129]
	v_mfma_f32_16x16x32_bf16 v[122:125], v[174:177], v[212:215], v[122:125]
	v_mfma_f32_16x16x32_bf16 v[110:113], v[144:147], v[220:223], v[110:113]
	v_mfma_f32_16x16x32_bf16 v[106:109], v[174:177], v[220:223], v[106:109]
	v_mfma_f32_16x16x32_bf16 v[94:97], v[144:147], v[228:231], v[94:97]
	v_mfma_f32_16x16x32_bf16 v[90:93], v[174:177], v[228:231], v[90:93]
	v_mfma_f32_16x16x32_bf16 v[78:81], v[144:147], v[236:239], v[78:81]
	v_mfma_f32_16x16x32_bf16 v[74:77], v[174:177], v[236:239], v[74:77]
	v_mfma_f32_16x16x32_bf16 v[126:129], v[164:167], v[216:219], v[126:129]
	v_mfma_f32_16x16x32_bf16 v[122:125], v[192:195], v[216:219], v[122:125]
	v_mfma_f32_16x16x32_bf16 v[110:113], v[164:167], v[224:227], v[110:113]
	v_mfma_f32_16x16x32_bf16 v[106:109], v[192:195], v[224:227], v[106:109]
	v_mfma_f32_16x16x32_bf16 v[94:97], v[164:167], v[232:235], v[94:97]
	v_mfma_f32_16x16x32_bf16 v[90:93], v[192:195], v[232:235], v[90:93]
	v_mfma_f32_16x16x32_bf16 v[78:81], v[164:167], v[240:243], v[78:81]
	v_mfma_f32_16x16x32_bf16 v[74:77], v[192:195], v[240:243], v[74:77]
	v_mfma_f32_16x16x32_bf16 v[118:121], v[196:199], v[212:215], v[118:121]
	v_mfma_f32_16x16x32_bf16 v[114:117], v[204:207], v[212:215], v[114:117]
	v_mfma_f32_16x16x32_bf16 v[102:105], v[196:199], v[220:223], v[102:105]
	v_mfma_f32_16x16x32_bf16 v[98:101], v[204:207], v[220:223], v[98:101]
	v_mfma_f32_16x16x32_bf16 v[86:89], v[196:199], v[228:231], v[86:89]
	v_mfma_f32_16x16x32_bf16 v[82:85], v[204:207], v[228:231], v[82:85]
	v_mfma_f32_16x16x32_bf16 v[70:73], v[196:199], v[236:239], v[70:73]
	v_mfma_f32_16x16x32_bf16 v[66:69], v[204:207], v[236:239], v[66:69]
	v_mfma_f32_16x16x32_bf16 v[118:121], v[200:203], v[216:219], v[118:121]
	v_mfma_f32_16x16x32_bf16 v[114:117], v[208:211], v[216:219], v[114:117]
	v_mfma_f32_16x16x32_bf16 v[102:105], v[200:203], v[224:227], v[102:105]
	v_mfma_f32_16x16x32_bf16 v[98:101], v[208:211], v[224:227], v[98:101]
	v_mfma_f32_16x16x32_bf16 v[86:89], v[200:203], v[232:235], v[86:89]
	v_mfma_f32_16x16x32_bf16 v[82:85], v[208:211], v[232:235], v[82:85]
	v_mfma_f32_16x16x32_bf16 v[70:73], v[200:203], v[240:243], v[70:73]
	v_mfma_f32_16x16x32_bf16 v[66:69], v[208:211], v[240:243], v[66:69]
	s_setprio 0
	s_barrier
; #define PG8_STAGE(bufoff, gbase, voff) do { _Pragma("unroll") for (int _i = 0; _i < 2; ++_i) \
;         __builtin_amdgcn_global_load_lds((const unsigned*)((const char*)(gbase) + (voff)[_i]), (LAS unsigned*)(lds + (bufoff) + ldsw + _i * 8192), 16, 0, 0); } while (0)
; #define PG8_LDA(dst, b, h) do { _Pragma("unroll") for (int m = 0; m < 4; ++m) _Pragma("unroll") for (int k = 0; k < 2; ++k) dst[m][k] = *(const LAS bf16x8*)(lds + PG8_SA(b, h) + aoff + m * 2048 + k * 1024); } while (0)
; #define PG8_MMA(ai, bj, At, Bt) do { __builtin_amdgcn_s_setprio(3); _Pragma("unroll") for (int m = 0; m < 4; ++m) _Pragma("unroll") for (int n = 0; n < 2; ++n) _Pragma("unroll") for (int k = 0; k < 2; ++k) \
;         acc[ai][bj][m][n] = __builtin_amdgcn_mfma_f32_16x16x32_bf16(Bt[n][k], At[m][k], acc[ai][bj][m][n], 0, 0, 0); __builtin_amdgcn_s_setprio(0); } while (0)
; #define PG8_WAIT_V(n) asm volatile("s_waitcnt vmcnt(" #n ")" ::: "memory")
; #define PG8_WAIT_L(n) asm volatile("s_waitcnt lgkmcnt(" #n ")" ::: "memory")
; #define PG8_BAR __builtin_amdgcn_s_barrier()
; #define PG8_SCHED __builtin_amdgcn_sched_barrier(0)
;     ...
;             PG8_LDA(At, 1, 1); PG8_STAGE(PG8_SB(1, 0), b3, voffB); PG8_STAGE(PG8_SB(1, 1), b3 + hstepB, voffB); PG8_STAGE(PG8_SA(1, 0), a3, voffA);
;             PG8_WAIT_V(8); PG8_WAIT_L(0); PG8_BAR; PG8_MMA(1, 0, At, B0); PG8_MMA(1, 1, At, B1); PG8_BAR; PG8_SCHED;
;     ...
;         if constexpr (ALIGN_EPI) { if (wr == 0) PG8_BAR; }
	s_add_i32 s60, s73, s70
	v_lshl_add_u64 v[168:169], v[168:169], 0, s[46:47]
	s_mov_b32 m0, s60
	ds_read_b128 v[212:215], v172 offset:49152
	ds_read_b128 v[216:219], v172 offset:50176
	ds_read_b128 v[220:223], v172 offset:51200
	ds_read_b128 v[224:227], v172 offset:52224
	ds_read_b128 v[228:231], v172 offset:53248
	ds_read_b128 v[232:235], v172 offset:54272
	ds_read_b128 v[236:239], v172 offset:55296
	ds_read_b128 v[240:243], v172 offset:56320
	global_load_lds_dwordx4 v[168:169], off
	s_add_i32 m0, s60, 0x2000
	s_add_u32 s60, s82, 0x10080
	v_lshl_add_u64 v[168:169], v[244:245], 0, s[46:47]
	s_addc_u32 s61, s83, 0
	s_add_i32 s73, s79, s70
	global_load_lds_dwordx4 v[168:169], off
	v_lshl_add_u64 v[168:169], s[60:61], 0, v[132:133]
	s_mov_b32 m0, s73
	s_nop 0
	global_load_lds_dwordx4 v[168:169], off
	v_lshl_add_u64 v[168:169], s[60:61], 0, v[136:137]
	s_add_i32 m0, s73, 0x2000
	s_nop 0
	global_load_lds_dwordx4 v[168:169], off
	v_lshl_add_u64 v[168:169], v[246:247], 0, s[46:47]
	s_mov_b32 m0, s13
	s_nop 0
	global_load_lds_dwordx4 v[168:169], off
	v_lshl_add_u64 v[168:169], v[248:249], 0, s[46:47]
	s_mov_b32 m0, s86
	s_nop 0
	global_load_lds_dwordx4 v[168:169], off
	s_waitcnt vmcnt(8)
	s_waitcnt lgkmcnt(0)
	s_barrier
	s_setprio 3
	s_waitcnt lgkmcnt(0)
	v_mfma_f32_16x16x32_bf16 v[62:65], v[144:147], v[212:215], v[62:65]
	v_mfma_f32_16x16x32_bf16 v[58:61], v[174:177], v[212:215], v[58:61]
	v_mfma_f32_16x16x32_bf16 v[46:49], v[144:147], v[220:223], v[46:49]
	v_mfma_f32_16x16x32_bf16 v[42:45], v[174:177], v[220:223], v[42:45]
	v_mfma_f32_16x16x32_bf16 v[30:33], v[144:147], v[228:231], v[30:33]
	v_mfma_f32_16x16x32_bf16 v[26:29], v[174:177], v[228:231], v[26:29]
	v_mfma_f32_16x16x32_bf16 v[14:17], v[144:147], v[236:239], v[14:17]
	v_mfma_f32_16x16x32_bf16 v[10:13], v[174:177], v[236:239], v[10:13]
	v_mfma_f32_16x16x32_bf16 v[62:65], v[164:167], v[216:219], v[62:65]
	v_mfma_f32_16x16x32_bf16 v[58:61], v[192:195], v[216:219], v[58:61]
	v_mfma_f32_16x16x32_bf16 v[46:49], v[164:167], v[224:227], v[46:49]
	v_mfma_f32_16x16x32_bf16 v[42:45], v[192:195], v[224:227], v[42:45]
	v_mfma_f32_16x16x32_bf16 v[30:33], v[164:167], v[232:235], v[30:33]
	v_mfma_f32_16x16x32_bf16 v[26:29], v[192:195], v[232:235], v[26:29]
	v_mfma_f32_16x16x32_bf16 v[14:17], v[164:167], v[240:243], v[14:17]
	v_mfma_f32_16x16x32_bf16 v[10:13], v[192:195], v[240:243], v[10:13]
	v_mfma_f32_16x16x32_bf16 v[54:57], v[196:199], v[212:215], v[54:57]
	v_mfma_f32_16x16x32_bf16 v[50:53], v[204:207], v[212:215], v[50:53]
	v_mfma_f32_16x16x32_bf16 v[38:41], v[196:199], v[220:223], v[38:41]
	v_mfma_f32_16x16x32_bf16 v[34:37], v[204:207], v[220:223], v[34:37]
	v_mfma_f32_16x16x32_bf16 v[22:25], v[196:199], v[228:231], v[22:25]
	v_mfma_f32_16x16x32_bf16 v[18:21], v[204:207], v[228:231], v[18:21]
	v_mfma_f32_16x16x32_bf16 v[6:9], v[196:199], v[236:239], v[6:9]
	v_mfma_f32_16x16x32_bf16 v[2:5], v[204:207], v[236:239], v[2:5]
	v_mfma_f32_16x16x32_bf16 v[54:57], v[200:203], v[216:219], v[54:57]
	v_mfma_f32_16x16x32_bf16 v[50:53], v[208:211], v[216:219], v[50:53]
	v_mfma_f32_16x16x32_bf16 v[38:41], v[200:203], v[224:227], v[38:41]
	v_mfma_f32_16x16x32_bf16 v[34:37], v[208:211], v[224:227], v[34:37]
	v_mfma_f32_16x16x32_bf16 v[22:25], v[200:203], v[232:235], v[22:25]
	v_mfma_f32_16x16x32_bf16 v[18:21], v[208:211], v[232:235], v[18:21]
	v_mfma_f32_16x16x32_bf16 v[6:9], v[200:203], v[240:243], v[6:9]
	v_mfma_f32_16x16x32_bf16 v[2:5], v[208:211], v[240:243], v[2:5]
	s_setprio 0
	s_barrier
	s_add_i32 s42, s42, 2
	s_add_u32 s35, s35, 0x100
	s_addc_u32 s40, s40, 0
	s_add_u32 s80, s80, 0x100
	s_addc_u32 s81, s81, 0
	s_cmp_gt_u32 s42, 13
	s_cbranch_scc0 .LBB0_79
	s_and_b64 vcc, exec, s[8:9]
	s_cbranch_vccz .LBB0_82
	s_barrier

; #define PG8_STAGE(bufoff, gbase, voff) do { _Pragma("unroll") for (int _i = 0; _i < 2; ++_i) \
;         __builtin_amdgcn_global_load_lds((const unsigned*)((const char*)(gbase) + (voff)[_i]), (LAS unsigned*)(lds + (bufoff) + ldsw + _i * 8192), 16, 0, 0); } while (0)
; #define PG8_LDA(dst, b, h) do { _Pragma("unroll") for (int m = 0; m < 4; ++m) _Pragma("unroll") for (int k = 0; k < 2; ++k) dst[m][k] = *(const LAS bf16x8*)(lds + PG8_SA(b, h) + aoff + m * 2048 + k * 1024); } while (0)
; #define PG8_LDB(dst, b, h) do { _Pragma("unroll") for (int n = 0; n < 2; ++n) _Pragma("unroll") for (int k = 0; k < 2; ++k) dst[n][k] = *(const LAS bf16x8*)(lds + PG8_SB(b, h) + boff + n * 2048 + k * 1024); } while (0)
; #define PG8_MMA(ai, bj, At, Bt) do { __builtin_amdgcn_s_setprio(3); _Pragma("unroll") for (int m = 0; m < 4; ++m) _Pragma("unroll") for (int n = 0; n < 2; ++n) _Pragma("unroll") for (int k = 0; k < 2; ++k) \
;         acc[ai][bj][m][n] = __builtin_amdgcn_mfma_f32_16x16x32_bf16(Bt[n][k], At[m][k], acc[ai][bj][m][n], 0, 0, 0); __builtin_amdgcn_s_setprio(0); } while (0)
; #define PG8_WAIT_V(n) asm volatile("s_waitcnt vmcnt(" #n ")" ::: "memory")
; #define PG8_WAIT_L(n) asm volatile("s_waitcnt lgkmcnt(" #n ")" ::: "memory")
; #define PG8_BAR __builtin_amdgcn_s_barrier()
; #define PG8_SCHED __builtin_amdgcn_sched_barrier(0)
;     ...
;             PG8_LDB(B0, 0, 0); PG8_LDB(B1, 0, 1); PG8_SCHED; PG8_LDA(At, 0, 0); PG8_STAGE(PG8_SA(1, 1), a1 + hstepA, voffA);
;             PG8_WAIT_V(8); PG8_WAIT_L(0); PG8_BAR; PG8_MMA(0, 0, At, B0); PG8_MMA(0, 1, At, B1); PG8_BAR; PG8_SCHED;
;             PG8_LDA(At, 0, 1); PG8_STAGE(PG8_SB(0, 0), b2, voffB); PG8_STAGE(PG8_SB(0, 1), b2 + hstepB, voffB); PG8_STAGE(PG8_SA(0, 0), a2, voffA);
;             PG8_WAIT_V(8); PG8_WAIT_L(0); PG8_BAR; PG8_MMA(1, 0, At, B0); PG8_MMA(1, 1, At, B1); PG8_BAR; PG8_SCHED;
.LBB0_285:
	s_add_u32 s73, s76, 0xfffc0080
	s_addc_u32 s78, s77, -1
	s_add_i32 s87, 0, 0x10000
	s_cmp_eq_u32 s61, 12
	s_cselect_b32 s81, s11, s78
	s_cselect_b32 s80, s34, s73
	v_add_u32_e32 v167, s87, v164
	s_cselect_b32 s79, s9, s60
	s_cselect_b32 s78, s35, s42
	s_add_i32 s73, 0, 0x14000
	ds_read_b128 v[144:147], v167
	ds_read_b128 v[168:171], v167 offset:1024
	ds_read_b128 v[172:175], v167 offset:2048
	ds_read_b128 v[192:195], v167 offset:3072
	v_add_u32_e32 v167, s73, v164
	ds_read_b128 v[196:199], v167
	ds_read_b128 v[200:203], v167 offset:1024
	ds_read_b128 v[204:207], v167 offset:2048
	ds_read_b128 v[208:211], v167 offset:3072
	v_lshl_add_u64 v[176:177], s[76:77], 0, v[142:143]
	s_add_i32 m0, s68, 0xc000
	ds_read_b128 v[212:215], v166
	ds_read_b128 v[216:219], v166 offset:1024
	ds_read_b128 v[220:223], v166 offset:2048
	ds_read_b128 v[224:227], v166 offset:3072
	ds_read_b128 v[228:231], v166 offset:4096
	ds_read_b128 v[232:235], v166 offset:5120
	ds_read_b128 v[236:239], v166 offset:6144
	ds_read_b128 v[240:243], v166 offset:7168
	global_load_lds_dwordx4 v[176:177], off
	v_lshl_add_u64 v[176:177], s[76:77], 0, v[140:141]
	s_add_i32 m0, s68, 0xe000
	s_nop 0
	global_load_lds_dwordx4 v[176:177], off
	s_waitcnt vmcnt(8)
	s_waitcnt lgkmcnt(0)
	s_barrier
	s_setprio 3
	s_waitcnt lgkmcnt(0)
	v_mfma_f32_16x16x32_bf16 v[126:129], v[144:147], v[212:215], v[126:129]
	v_mfma_f32_16x16x32_bf16 v[122:125], v[172:175], v[212:215], v[122:125]
	v_mfma_f32_16x16x32_bf16 v[110:113], v[144:147], v[220:223], v[110:113]
	v_mfma_f32_16x16x32_bf16 v[106:109], v[172:175], v[220:223], v[106:109]
	v_mfma_f32_16x16x32_bf16 v[94:97], v[144:147], v[228:231], v[94:97]
	v_mfma_f32_16x16x32_bf16 v[90:93], v[172:175], v[228:231], v[90:93]
	v_mfma_f32_16x16x32_bf16 v[78:81], v[144:147], v[236:239], v[78:81]
	v_mfma_f32_16x16x32_bf16 v[74:77], v[172:175], v[236:239], v[74:77]
	v_mfma_f32_16x16x32_bf16 v[126:129], v[168:171], v[216:219], v[126:129]
	v_mfma_f32_16x16x32_bf16 v[122:125], v[192:195], v[216:219], v[122:125]
	v_mfma_f32_16x16x32_bf16 v[110:113], v[168:171], v[224:227], v[110:113]
	v_mfma_f32_16x16x32_bf16 v[106:109], v[192:195], v[224:227], v[106:109]
	v_mfma_f32_16x16x32_bf16 v[94:97], v[168:171], v[232:235], v[94:97]
	v_mfma_f32_16x16x32_bf16 v[90:93], v[192:195], v[232:235], v[90:93]
	v_mfma_f32_16x16x32_bf16 v[78:81], v[168:171], v[240:243], v[78:81]
	v_mfma_f32_16x16x32_bf16 v[74:77], v[192:195], v[240:243], v[74:77]
	v_mfma_f32_16x16x32_bf16 v[118:121], v[196:199], v[212:215], v[118:121]
	v_mfma_f32_16x16x32_bf16 v[114:117], v[204:207], v[212:215], v[114:117]
	v_mfma_f32_16x16x32_bf16 v[102:105], v[196:199], v[220:223], v[102:105]
	v_mfma_f32_16x16x32_bf16 v[98:101], v[204:207], v[220:223], v[98:101]
	v_mfma_f32_16x16x32_bf16 v[86:89], v[196:199], v[228:231], v[86:89]
	v_mfma_f32_16x16x32_bf16 v[82:85], v[204:207], v[228:231], v[82:85]
	v_mfma_f32_16x16x32_bf16 v[70:73], v[196:199], v[236:239], v[70:73]
	v_mfma_f32_16x16x32_bf16 v[66:69], v[204:207], v[236:239], v[66:69]
	v_mfma_f32_16x16x32_bf16 v[118:121], v[200:203], v[216:219], v[118:121]
	v_mfma_f32_16x16x32_bf16 v[114:117], v[208:211], v[216:219], v[114:117]
	v_mfma_f32_16x16x32_bf16 v[102:105], v[200:203], v[224:227], v[102:105]
	v_mfma_f32_16x16x32_bf16 v[98:101], v[208:211], v[224:227], v[98:101]
	v_mfma_f32_16x16x32_bf16 v[86:89], v[200:203], v[232:235], v[86:89]
	v_mfma_f32_16x16x32_bf16 v[82:85], v[208:211], v[232:235], v[82:85]
	v_mfma_f32_16x16x32_bf16 v[70:73], v[200:203], v[240:243], v[70:73]
	v_mfma_f32_16x16x32_bf16 v[66:69], v[208:211], v[240:243], v[66:69]
	s_setprio 0
	s_barrier
	s_add_i32 s87, s87, s30
	v_lshl_add_u64 v[176:177], s[78:79], 0, v[134:135]
	s_mov_b32 m0, s87
	ds_read_b128 v[212:215], v166 offset:16384
	ds_read_b128 v[216:219], v166 offset:17408
	ds_read_b128 v[220:223], v166 offset:18432
	ds_read_b128 v[224:227], v166 offset:19456
	ds_read_b128 v[228:231], v166 offset:20480
	ds_read_b128 v[232:235], v166 offset:21504
	ds_read_b128 v[236:239], v166 offset:22528
	ds_read_b128 v[240:243], v166 offset:23552
	global_load_lds_dwordx4 v[176:177], off
	s_add_i32 m0, s87, 0x2000
	s_add_u32 s94, s78, 0x10000
	v_lshl_add_u64 v[244:245], s[78:79], 0, v[130:131]
	s_addc_u32 s95, s79, 0
	s_add_i32 s73, s73, s30
	global_load_lds_dwordx4 v[244:245], off
	v_lshl_add_u64 v[246:247], s[94:95], 0, v[134:135]
	s_mov_b32 m0, s73
	v_lshl_add_u64 v[248:249], s[80:81], 0, v[132:133]
	global_load_lds_dwordx4 v[246:247], off
	v_lshl_add_u64 v[246:247], s[94:95], 0, v[130:131]
	s_add_i32 m0, s73, 0x2000
	s_nop 0
	global_load_lds_dwordx4 v[246:247], off
	v_lshl_add_u64 v[246:247], s[80:81], 0, v[136:137]
	s_mov_b32 m0, s68
	s_nop 0
	global_load_lds_dwordx4 v[246:247], off
	s_mov_b32 m0, s69
	s_nop 0
	global_load_lds_dwordx4 v[248:249], off
	s_waitcnt vmcnt(8)
	s_waitcnt lgkmcnt(0)
	s_barrier
; #define PG8_STAGE(bufoff, gbase, voff) do { _Pragma("unroll") for (int _i = 0; _i < 2; ++_i) \
;         __builtin_amdgcn_global_load_lds((const unsigned*)((const char*)(gbase) + (voff)[_i]), (LAS unsigned*)(lds + (bufoff) + ldsw + _i * 8192), 16, 0, 0); } while (0)
; #define PG8_LDA(dst, b, h) do { _Pragma("unroll") for (int m = 0; m < 4; ++m) _Pragma("unroll") for (int k = 0; k < 2; ++k) dst[m][k] = *(const LAS bf16x8*)(lds + PG8_SA(b, h) + aoff + m * 2048 + k * 1024); } while (0)
; #define PG8_LDB(dst, b, h) do { _Pragma("unroll") for (int n = 0; n < 2; ++n) _Pragma("unroll") for (int k = 0; k < 2; ++k) dst[n][k] = *(const LAS bf16x8*)(lds + PG8_SB(b, h) + boff + n * 2048 + k * 1024); } while (0)
; #define PG8_MMA(ai, bj, At, Bt) do { __builtin_amdgcn_s_setprio(3); _Pragma("unroll") for (int m = 0; m < 4; ++m) _Pragma("unroll") for (int n = 0; n < 2; ++n) _Pragma("unroll") for (int k = 0; k < 2; ++k) \
;         acc[ai][bj][m][n] = __builtin_amdgcn_mfma_f32_16x16x32_bf16(Bt[n][k], At[m][k], acc[ai][bj][m][n], 0, 0, 0); __builtin_amdgcn_s_setprio(0); } while (0)
; #define PG8_WAIT_V(n) asm volatile("s_waitcnt vmcnt(" #n ")" ::: "memory")
; #define PG8_WAIT_L(n) asm volatile("s_waitcnt lgkmcnt(" #n ")" ::: "memory")
; #define PG8_BAR __builtin_amdgcn_s_barrier()
; #define PG8_SCHED __builtin_amdgcn_sched_barrier(0)
;     ...
;             PG8_WAIT_V(8); PG8_WAIT_L(0); PG8_BAR; PG8_MMA(1, 0, At, B0); PG8_MMA(1, 1, At, B1); PG8_BAR; PG8_SCHED;
;             PG8_LDB(B0, 1, 0); PG8_LDB(B1, 1, 1); PG8_SCHED; PG8_LDA(At, 1, 0); PG8_STAGE(PG8_SA(0, 1), a2 + hstepA, voffA);
;             PG8_WAIT_V(8); PG8_WAIT_L(0); PG8_BAR; PG8_MMA(0, 0, At, B0); PG8_MMA(0, 1, At, B1); PG8_BAR; PG8_SCHED;
	s_setprio 3
	s_waitcnt lgkmcnt(0)
	v_mfma_f32_16x16x32_bf16 v[62:65], v[144:147], v[212:215], v[62:65]
	v_mfma_f32_16x16x32_bf16 v[58:61], v[172:175], v[212:215], v[58:61]
	v_mfma_f32_16x16x32_bf16 v[46:49], v[144:147], v[220:223], v[46:49]
	v_mfma_f32_16x16x32_bf16 v[42:45], v[172:175], v[220:223], v[42:45]
	v_mfma_f32_16x16x32_bf16 v[30:33], v[144:147], v[228:231], v[30:33]
	v_mfma_f32_16x16x32_bf16 v[26:29], v[172:175], v[228:231], v[26:29]
	v_mfma_f32_16x16x32_bf16 v[14:17], v[144:147], v[236:239], v[14:17]
	v_mfma_f32_16x16x32_bf16 v[10:13], v[172:175], v[236:239], v[10:13]
	v_mfma_f32_16x16x32_bf16 v[62:65], v[168:171], v[216:219], v[62:65]
	v_mfma_f32_16x16x32_bf16 v[58:61], v[192:195], v[216:219], v[58:61]
	v_mfma_f32_16x16x32_bf16 v[46:49], v[168:171], v[224:227], v[46:49]
	v_mfma_f32_16x16x32_bf16 v[42:45], v[192:195], v[224:227], v[42:45]
	v_mfma_f32_16x16x32_bf16 v[30:33], v[168:171], v[232:235], v[30:33]
	v_mfma_f32_16x16x32_bf16 v[26:29], v[192:195], v[232:235], v[26:29]
	v_mfma_f32_16x16x32_bf16 v[14:17], v[168:171], v[240:243], v[14:17]
	v_mfma_f32_16x16x32_bf16 v[10:13], v[192:195], v[240:243], v[10:13]
	v_mfma_f32_16x16x32_bf16 v[54:57], v[196:199], v[212:215], v[54:57]
	v_mfma_f32_16x16x32_bf16 v[50:53], v[204:207], v[212:215], v[50:53]
	v_mfma_f32_16x16x32_bf16 v[38:41], v[196:199], v[220:223], v[38:41]
	v_mfma_f32_16x16x32_bf16 v[34:37], v[204:207], v[220:223], v[34:37]
	v_mfma_f32_16x16x32_bf16 v[22:25], v[196:199], v[228:231], v[22:25]
	v_mfma_f32_16x16x32_bf16 v[18:21], v[204:207], v[228:231], v[18:21]
	v_mfma_f32_16x16x32_bf16 v[6:9], v[196:199], v[236:239], v[6:9]
	v_mfma_f32_16x16x32_bf16 v[2:5], v[204:207], v[236:239], v[2:5]
	v_mfma_f32_16x16x32_bf16 v[54:57], v[200:203], v[216:219], v[54:57]
	v_mfma_f32_16x16x32_bf16 v[50:53], v[208:211], v[216:219], v[50:53]
	v_mfma_f32_16x16x32_bf16 v[38:41], v[200:203], v[224:227], v[38:41]
	v_mfma_f32_16x16x32_bf16 v[34:37], v[208:211], v[224:227], v[34:37]
	v_mfma_f32_16x16x32_bf16 v[22:25], v[200:203], v[232:235], v[22:25]
	v_mfma_f32_16x16x32_bf16 v[18:21], v[208:211], v[232:235], v[18:21]
	v_mfma_f32_16x16x32_bf16 v[6:9], v[200:203], v[240:243], v[6:9]
	v_mfma_f32_16x16x32_bf16 v[2:5], v[208:211], v[240:243], v[2:5]
	s_setprio 0
	s_barrier
	s_add_i32 s73, 0, 0x18000
	v_add_u32_e32 v167, s73, v164
	s_add_i32 s87, 0, 0x1c000
	ds_read_b128 v[144:147], v167
	ds_read_b128 v[168:171], v167 offset:1024
	ds_read_b128 v[172:175], v167 offset:2048
	ds_read_b128 v[192:195], v167 offset:3072
	v_add_u32_e32 v167, s87, v164
	ds_read_b128 v[196:199], v167
	ds_read_b128 v[200:203], v167 offset:1024
	ds_read_b128 v[204:207], v167 offset:2048
	ds_read_b128 v[208:211], v167 offset:3072
	s_add_u32 s80, s80, 0x40000
	s_addc_u32 s81, s81, 0
	s_mov_b32 m0, s70
	v_lshl_add_u64 v[250:251], s[80:81], 0, v[136:137]
	ds_read_b128 v[212:215], v166 offset:32768
	ds_read_b128 v[216:219], v166 offset:33792
	ds_read_b128 v[220:223], v166 offset:34816
	ds_read_b128 v[224:227], v166 offset:35840
	ds_read_b128 v[228:231], v166 offset:36864
	ds_read_b128 v[232:235], v166 offset:37888
	ds_read_b128 v[236:239], v166 offset:38912
	ds_read_b128 v[240:243], v166 offset:39936
	global_load_lds_dwordx4 v[250:251], off
	v_lshl_add_u64 v[250:251], s[80:81], 0, v[132:133]
	s_mov_b32 m0, s71
	s_nop 0
	global_load_lds_dwordx4 v[250:251], off
	s_waitcnt vmcnt(8)
	s_waitcnt lgkmcnt(0)
	s_barrier
	s_setprio 3
	s_waitcnt lgkmcnt(0)
	v_mfma_f32_16x16x32_bf16 v[126:129], v[144:147], v[212:215], v[126:129]
	v_mfma_f32_16x16x32_bf16 v[122:125], v[172:175], v[212:215], v[122:125]
	v_mfma_f32_16x16x32_bf16 v[110:113], v[144:147], v[220:223], v[110:113]
	v_mfma_f32_16x16x32_bf16 v[106:109], v[172:175], v[220:223], v[106:109]
	v_mfma_f32_16x16x32_bf16 v[94:97], v[144:147], v[228:231], v[94:97]
	v_mfma_f32_16x16x32_bf16 v[90:93], v[172:175], v[228:231], v[90:93]
	v_mfma_f32_16x16x32_bf16 v[78:81], v[144:147], v[236:239], v[78:81]
	v_mfma_f32_16x16x32_bf16 v[74:77], v[172:175], v[236:239], v[74:77]
	v_mfma_f32_16x16x32_bf16 v[126:129], v[168:171], v[216:219], v[126:129]
	v_mfma_f32_16x16x32_bf16 v[122:125], v[192:195], v[216:219], v[122:125]
	v_mfma_f32_16x16x32_bf16 v[110:113], v[168:171], v[224:227], v[110:113]
	v_mfma_f32_16x16x32_bf16 v[106:109], v[192:195], v[224:227], v[106:109]
	v_mfma_f32_16x16x32_bf16 v[94:97], v[168:171], v[232:235], v[94:97]
	v_mfma_f32_16x16x32_bf16 v[90:93], v[192:195], v[232:235], v[90:93]
	v_mfma_f32_16x16x32_bf16 v[78:81], v[168:171], v[240:243], v[78:81]
	v_mfma_f32_16x16x32_bf16 v[74:77], v[192:195], v[240:243], v[74:77]
	v_mfma_f32_16x16x32_bf16 v[118:121], v[196:199], v[212:215], v[118:121]
	v_mfma_f32_16x16x32_bf16 v[114:117], v[204:207], v[212:215], v[114:117]
	v_mfma_f32_16x16x32_bf16 v[102:105], v[196:199], v[220:223], v[102:105]
	v_mfma_f32_16x16x32_bf16 v[98:101], v[204:207], v[220:223], v[98:101]
	v_mfma_f32_16x16x32_bf16 v[86:89], v[196:199], v[228:231], v[86:89]
	v_mfma_f32_16x16x32_bf16 v[82:85], v[204:207], v[228:231], v[82:85]
	v_mfma_f32_16x16x32_bf16 v[70:73], v[196:199], v[236:239], v[70:73]
	v_mfma_f32_16x16x32_bf16 v[66:69], v[204:207], v[236:239], v[66:69]
	v_mfma_f32_16x16x32_bf16 v[118:121], v[200:203], v[216:219], v[118:121]
	v_mfma_f32_16x16x32_bf16 v[114:117], v[208:211], v[216:219], v[114:117]
	v_mfma_f32_16x16x32_bf16 v[102:105], v[200:203], v[224:227], v[102:105]
	v_mfma_f32_16x16x32_bf16 v[98:101], v[208:211], v[224:227], v[98:101]
	v_mfma_f32_16x16x32_bf16 v[86:89], v[200:203], v[232:235], v[86:89]
	v_mfma_f32_16x16x32_bf16 v[82:85], v[208:211], v[232:235], v[82:85]
	v_mfma_f32_16x16x32_bf16 v[70:73], v[200:203], v[240:243], v[70:73]
	v_mfma_f32_16x16x32_bf16 v[66:69], v[208:211], v[240:243], v[66:69]
	s_setprio 0
	s_barrier
; #define PG8_STAGE(bufoff, gbase, voff) do { _Pragma("unroll") for (int _i = 0; _i < 2; ++_i) \
;         __builtin_amdgcn_global_load_lds((const unsigned*)((const char*)(gbase) + (voff)[_i]), (LAS unsigned*)(lds + (bufoff) + ldsw + _i * 8192), 16, 0, 0); } while (0)
; #define PG8_LDA(dst, b, h) do { _Pragma("unroll") for (int m = 0; m < 4; ++m) _Pragma("unroll") for (int k = 0; k < 2; ++k) dst[m][k] = *(const LAS bf16x8*)(lds + PG8_SA(b, h) + aoff + m * 2048 + k * 1024); } while (0)
; #define PG8_MMA(ai, bj, At, Bt) do { __builtin_amdgcn_s_setprio(3); _Pragma("unroll") for (int m = 0; m < 4; ++m) _Pragma("unroll") for (int n = 0; n < 2; ++n) _Pragma("unroll") for (int k = 0; k < 2; ++k) \
;         acc[ai][bj][m][n] = __builtin_amdgcn_mfma_f32_16x16x32_bf16(Bt[n][k], At[m][k], acc[ai][bj][m][n], 0, 0, 0); __builtin_amdgcn_s_setprio(0); } while (0)
; #define PG8_WAIT_V(n) asm volatile("s_waitcnt vmcnt(" #n ")" ::: "memory")
; #define PG8_WAIT_L(n) asm volatile("s_waitcnt lgkmcnt(" #n ")" ::: "memory")
; #define PG8_BAR __builtin_amdgcn_s_barrier()
; #define PG8_SCHED __builtin_amdgcn_sched_barrier(0)
;     ...
;             PG8_LDA(At, 1, 1); PG8_STAGE(PG8_SB(1, 0), b3, voffB); PG8_STAGE(PG8_SB(1, 1), b3 + hstepB, voffB); PG8_STAGE(PG8_SA(1, 0), a3, voffA);
;             PG8_WAIT_V(8); PG8_WAIT_L(0); PG8_BAR; PG8_MMA(1, 0, At, B0); PG8_MMA(1, 1, At, B1); PG8_BAR; PG8_SCHED;
;     ...
;         if constexpr (ALIGN_EPI) { if (wr == 0) PG8_BAR; }
	s_add_i32 s73, s73, s30
	v_lshl_add_u64 v[176:177], v[176:177], 0, s[46:47]
	s_mov_b32 m0, s73
	ds_read_b128 v[212:215], v166 offset:49152
	ds_read_b128 v[216:219], v166 offset:50176
	ds_read_b128 v[220:223], v166 offset:51200
	ds_read_b128 v[224:227], v166 offset:52224
	ds_read_b128 v[228:231], v166 offset:53248
	ds_read_b128 v[232:235], v166 offset:54272
	ds_read_b128 v[236:239], v166 offset:55296
	ds_read_b128 v[240:243], v166 offset:56320
	global_load_lds_dwordx4 v[176:177], off
	s_add_i32 m0, s73, 0x2000
	s_add_u32 s78, s78, 0x10080
	v_lshl_add_u64 v[176:177], v[244:245], 0, s[46:47]
	s_addc_u32 s79, s79, 0
	s_add_i32 s73, s87, s30
	global_load_lds_dwordx4 v[176:177], off
	v_lshl_add_u64 v[176:177], s[78:79], 0, v[134:135]
	s_mov_b32 m0, s73
	s_nop 0
	global_load_lds_dwordx4 v[176:177], off
	v_lshl_add_u64 v[176:177], s[78:79], 0, v[130:131]
	s_add_i32 m0, s73, 0x2000
	s_nop 0
	global_load_lds_dwordx4 v[176:177], off
	v_lshl_add_u64 v[176:177], v[246:247], 0, s[46:47]
	s_mov_b32 m0, s82
	s_nop 0
	global_load_lds_dwordx4 v[176:177], off
	v_lshl_add_u64 v[176:177], v[248:249], 0, s[46:47]
	s_mov_b32 m0, s83
	s_nop 0
	global_load_lds_dwordx4 v[176:177], off
	s_waitcnt vmcnt(8)
	s_waitcnt lgkmcnt(0)
	s_barrier
	s_setprio 3
	s_waitcnt lgkmcnt(0)
	v_mfma_f32_16x16x32_bf16 v[62:65], v[144:147], v[212:215], v[62:65]
	v_mfma_f32_16x16x32_bf16 v[58:61], v[172:175], v[212:215], v[58:61]
	v_mfma_f32_16x16x32_bf16 v[46:49], v[144:147], v[220:223], v[46:49]
	v_mfma_f32_16x16x32_bf16 v[42:45], v[172:175], v[220:223], v[42:45]
	v_mfma_f32_16x16x32_bf16 v[30:33], v[144:147], v[228:231], v[30:33]
	v_mfma_f32_16x16x32_bf16 v[26:29], v[172:175], v[228:231], v[26:29]
	v_mfma_f32_16x16x32_bf16 v[14:17], v[144:147], v[236:239], v[14:17]
	v_mfma_f32_16x16x32_bf16 v[10:13], v[172:175], v[236:239], v[10:13]
	v_mfma_f32_16x16x32_bf16 v[62:65], v[168:171], v[216:219], v[62:65]
	v_mfma_f32_16x16x32_bf16 v[58:61], v[192:195], v[216:219], v[58:61]
	v_mfma_f32_16x16x32_bf16 v[46:49], v[168:171], v[224:227], v[46:49]
	v_mfma_f32_16x16x32_bf16 v[42:45], v[192:195], v[224:227], v[42:45]
	v_mfma_f32_16x16x32_bf16 v[30:33], v[168:171], v[232:235], v[30:33]
	v_mfma_f32_16x16x32_bf16 v[26:29], v[192:195], v[232:235], v[26:29]
	v_mfma_f32_16x16x32_bf16 v[14:17], v[168:171], v[240:243], v[14:17]
	v_mfma_f32_16x16x32_bf16 v[10:13], v[192:195], v[240:243], v[10:13]
	v_mfma_f32_16x16x32_bf16 v[54:57], v[196:199], v[212:215], v[54:57]
	v_mfma_f32_16x16x32_bf16 v[50:53], v[204:207], v[212:215], v[50:53]
	v_mfma_f32_16x16x32_bf16 v[38:41], v[196:199], v[220:223], v[38:41]
	v_mfma_f32_16x16x32_bf16 v[34:37], v[204:207], v[220:223], v[34:37]
	v_mfma_f32_16x16x32_bf16 v[22:25], v[196:199], v[228:231], v[22:25]
	v_mfma_f32_16x16x32_bf16 v[18:21], v[204:207], v[228:231], v[18:21]
	v_mfma_f32_16x16x32_bf16 v[6:9], v[196:199], v[236:239], v[6:9]
	v_mfma_f32_16x16x32_bf16 v[2:5], v[204:207], v[236:239], v[2:5]
	v_mfma_f32_16x16x32_bf16 v[54:57], v[200:203], v[216:219], v[54:57]
	v_mfma_f32_16x16x32_bf16 v[50:53], v[208:211], v[216:219], v[50:53]
	v_mfma_f32_16x16x32_bf16 v[38:41], v[200:203], v[224:227], v[38:41]
	v_mfma_f32_16x16x32_bf16 v[34:37], v[208:211], v[224:227], v[34:37]
	v_mfma_f32_16x16x32_bf16 v[22:25], v[200:203], v[232:235], v[22:25]
	v_mfma_f32_16x16x32_bf16 v[18:21], v[208:211], v[232:235], v[18:21]
	v_mfma_f32_16x16x32_bf16 v[6:9], v[200:203], v[240:243], v[6:9]
	v_mfma_f32_16x16x32_bf16 v[2:5], v[208:211], v[240:243], v[2:5]
	s_setprio 0
	s_barrier
	s_add_i32 s61, s61, 2
	s_add_u32 s42, s42, 0x100
	s_addc_u32 s60, s60, 0
	s_add_u32 s76, s76, 0x100
	s_addc_u32 s77, s77, 0
	s_cmp_gt_u32 s61, 13
	s_cbranch_scc0 .LBB0_285
	s_and_b64 vcc, exec, s[6:7]
	s_cbranch_vccz .LBB0_288
	s_barrier

; #define PG8_STAGE(bufoff, gbase, voff) do { _Pragma("unroll") for (int _i = 0; _i < 2; ++_i) \
;         __builtin_amdgcn_global_load_lds((const unsigned*)((const char*)(gbase) + (voff)[_i]), (LAS unsigned*)(lds + (bufoff) + ldsw + _i * 8192), 16, 0, 0); } while (0)
; #define PG8_LDA(dst, b, h) do { _Pragma("unroll") for (int m = 0; m < 4; ++m) _Pragma("unroll") for (int k = 0; k < 2; ++k) dst[m][k] = *(const LAS bf16x8*)(lds + PG8_SA(b, h) + aoff + m * 2048 + k * 1024); } while (0)
; #define PG8_LDB(dst, b, h) do { _Pragma("unroll") for (int n = 0; n < 2; ++n) _Pragma("unroll") for (int k = 0; k < 2; ++k) dst[n][k] = *(const LAS bf16x8*)(lds + PG8_SB(b, h) + boff + n * 2048 + k * 1024); } while (0)
; #define PG8_MMA(ai, bj, At, Bt) do { __builtin_amdgcn_s_setprio(3); _Pragma("unroll") for (int m = 0; m < 4; ++m) _Pragma("unroll") for (int n = 0; n < 2; ++n) _Pragma("unroll") for (int k = 0; k < 2; ++k) \
;         acc[ai][bj][m][n] = __builtin_amdgcn_mfma_f32_16x16x32_bf16(Bt[n][k], At[m][k], acc[ai][bj][m][n], 0, 0, 0); __builtin_amdgcn_s_setprio(0); } while (0)
; #define PG8_WAIT_V(n) asm volatile("s_waitcnt vmcnt(" #n ")" ::: "memory")
; #define PG8_WAIT_L(n) asm volatile("s_waitcnt lgkmcnt(" #n ")" ::: "memory")
; #define PG8_BAR __builtin_amdgcn_s_barrier()
; #define PG8_SCHED __builtin_amdgcn_sched_barrier(0)
;     ...
;             PG8_LDB(B0, 0, 0); PG8_LDB(B1, 0, 1); PG8_SCHED; PG8_LDA(At, 0, 0); PG8_STAGE(PG8_SA(1, 1), a1 + hstepA, voffA);
;             PG8_WAIT_V(8); PG8_WAIT_L(0); PG8_BAR; PG8_MMA(0, 0, At, B0); PG8_MMA(0, 1, At, B1); PG8_BAR; PG8_SCHED;
;             PG8_LDA(At, 0, 1); PG8_STAGE(PG8_SB(0, 0), b2, voffB); PG8_STAGE(PG8_SB(0, 1), b2 + hstepB, voffB); PG8_STAGE(PG8_SA(0, 0), a2, voffA);
;             PG8_WAIT_V(8); PG8_WAIT_L(0); PG8_BAR; PG8_MMA(1, 0, At, B0); PG8_MMA(1, 1, At, B1); PG8_BAR; PG8_SCHED;
.LBB0_451:
	s_add_u32 s77, s78, 0xfffc0080
	s_addc_u32 s80, s79, -1
	s_add_i32 s87, 0, 0x10000
	s_cmp_eq_u32 s61, 12
	s_cselect_b32 s83, s11, s80
	s_cselect_b32 s82, s34, s77
	v_add_u32_e32 v167, s87, v164
	s_cselect_b32 s81, s9, s60
	s_cselect_b32 s80, s35, s42
	s_add_i32 s77, 0, 0x14000
	ds_read_b128 v[144:147], v167
	ds_read_b128 v[168:171], v167 offset:1024
	ds_read_b128 v[172:175], v167 offset:2048
	ds_read_b128 v[192:195], v167 offset:3072
	v_add_u32_e32 v167, s77, v164
	ds_read_b128 v[196:199], v167
	ds_read_b128 v[200:203], v167 offset:1024
	ds_read_b128 v[204:207], v167 offset:2048
	ds_read_b128 v[208:211], v167 offset:3072
	v_lshl_add_u64 v[176:177], s[78:79], 0, v[142:143]
	s_add_i32 m0, s69, 0xc000
	ds_read_b128 v[212:215], v166
	ds_read_b128 v[216:219], v166 offset:1024
	ds_read_b128 v[220:223], v166 offset:2048
	ds_read_b128 v[224:227], v166 offset:3072
	ds_read_b128 v[228:231], v166 offset:4096
	ds_read_b128 v[232:235], v166 offset:5120
	ds_read_b128 v[236:239], v166 offset:6144
	ds_read_b128 v[240:243], v166 offset:7168
	global_load_lds_dwordx4 v[176:177], off
	v_lshl_add_u64 v[176:177], s[78:79], 0, v[140:141]
	s_add_i32 m0, s69, 0xe000
	s_nop 0
	global_load_lds_dwordx4 v[176:177], off
	s_waitcnt vmcnt(8)
	s_waitcnt lgkmcnt(0)
	s_barrier
	s_setprio 3
	s_waitcnt lgkmcnt(0)
	v_mfma_f32_16x16x32_bf16 v[126:129], v[144:147], v[212:215], v[126:129]
	v_mfma_f32_16x16x32_bf16 v[122:125], v[172:175], v[212:215], v[122:125]
	v_mfma_f32_16x16x32_bf16 v[110:113], v[144:147], v[220:223], v[110:113]
	v_mfma_f32_16x16x32_bf16 v[106:109], v[172:175], v[220:223], v[106:109]
	v_mfma_f32_16x16x32_bf16 v[94:97], v[144:147], v[228:231], v[94:97]
	v_mfma_f32_16x16x32_bf16 v[90:93], v[172:175], v[228:231], v[90:93]
	v_mfma_f32_16x16x32_bf16 v[78:81], v[144:147], v[236:239], v[78:81]
	v_mfma_f32_16x16x32_bf16 v[74:77], v[172:175], v[236:239], v[74:77]
	v_mfma_f32_16x16x32_bf16 v[126:129], v[168:171], v[216:219], v[126:129]
	v_mfma_f32_16x16x32_bf16 v[122:125], v[192:195], v[216:219], v[122:125]
	v_mfma_f32_16x16x32_bf16 v[110:113], v[168:171], v[224:227], v[110:113]
	v_mfma_f32_16x16x32_bf16 v[106:109], v[192:195], v[224:227], v[106:109]
	v_mfma_f32_16x16x32_bf16 v[94:97], v[168:171], v[232:235], v[94:97]
	v_mfma_f32_16x16x32_bf16 v[90:93], v[192:195], v[232:235], v[90:93]
	v_mfma_f32_16x16x32_bf16 v[78:81], v[168:171], v[240:243], v[78:81]
	v_mfma_f32_16x16x32_bf16 v[74:77], v[192:195], v[240:243], v[74:77]
	v_mfma_f32_16x16x32_bf16 v[118:121], v[196:199], v[212:215], v[118:121]
	v_mfma_f32_16x16x32_bf16 v[114:117], v[204:207], v[212:215], v[114:117]
	v_mfma_f32_16x16x32_bf16 v[102:105], v[196:199], v[220:223], v[102:105]
	v_mfma_f32_16x16x32_bf16 v[98:101], v[204:207], v[220:223], v[98:101]
	v_mfma_f32_16x16x32_bf16 v[86:89], v[196:199], v[228:231], v[86:89]
	v_mfma_f32_16x16x32_bf16 v[82:85], v[204:207], v[228:231], v[82:85]
	v_mfma_f32_16x16x32_bf16 v[70:73], v[196:199], v[236:239], v[70:73]
	v_mfma_f32_16x16x32_bf16 v[66:69], v[204:207], v[236:239], v[66:69]
	v_mfma_f32_16x16x32_bf16 v[118:121], v[200:203], v[216:219], v[118:121]
	v_mfma_f32_16x16x32_bf16 v[114:117], v[208:211], v[216:219], v[114:117]
	v_mfma_f32_16x16x32_bf16 v[102:105], v[200:203], v[224:227], v[102:105]
	v_mfma_f32_16x16x32_bf16 v[98:101], v[208:211], v[224:227], v[98:101]
	v_mfma_f32_16x16x32_bf16 v[86:89], v[200:203], v[232:235], v[86:89]
	v_mfma_f32_16x16x32_bf16 v[82:85], v[208:211], v[232:235], v[82:85]
	v_mfma_f32_16x16x32_bf16 v[70:73], v[200:203], v[240:243], v[70:73]
	v_mfma_f32_16x16x32_bf16 v[66:69], v[208:211], v[240:243], v[66:69]
	s_setprio 0
	s_barrier
	s_add_i32 s87, s87, s31
	v_lshl_add_u64 v[176:177], s[80:81], 0, v[134:135]
	s_mov_b32 m0, s87
	ds_read_b128 v[212:215], v166 offset:16384
	ds_read_b128 v[216:219], v166 offset:17408
	ds_read_b128 v[220:223], v166 offset:18432
	ds_read_b128 v[224:227], v166 offset:19456
	ds_read_b128 v[228:231], v166 offset:20480
	ds_read_b128 v[232:235], v166 offset:21504
	ds_read_b128 v[236:239], v166 offset:22528
	ds_read_b128 v[240:243], v166 offset:23552
	global_load_lds_dwordx4 v[176:177], off
	s_add_i32 m0, s87, 0x2000
	s_add_u32 s94, s80, 0x10000
	v_lshl_add_u64 v[244:245], s[80:81], 0, v[130:131]
	s_addc_u32 s95, s81, 0
	s_add_i32 s77, s77, s31
	global_load_lds_dwordx4 v[244:245], off
	v_lshl_add_u64 v[246:247], s[94:95], 0, v[134:135]
	s_mov_b32 m0, s77
	v_lshl_add_u64 v[248:249], s[82:83], 0, v[132:133]
	global_load_lds_dwordx4 v[246:247], off
	v_lshl_add_u64 v[246:247], s[94:95], 0, v[130:131]
	s_add_i32 m0, s77, 0x2000
	s_nop 0
	global_load_lds_dwordx4 v[246:247], off
	v_lshl_add_u64 v[246:247], s[82:83], 0, v[136:137]
	s_mov_b32 m0, s69
	s_nop 0
	global_load_lds_dwordx4 v[246:247], off
	s_mov_b32 m0, s70
	s_nop 0
	global_load_lds_dwordx4 v[248:249], off
	s_waitcnt vmcnt(8)
	s_waitcnt lgkmcnt(0)
	s_barrier
; #define PG8_STAGE(bufoff, gbase, voff) do { _Pragma("unroll") for (int _i = 0; _i < 2; ++_i) \
;         __builtin_amdgcn_global_load_lds((const unsigned*)((const char*)(gbase) + (voff)[_i]), (LAS unsigned*)(lds + (bufoff) + ldsw + _i * 8192), 16, 0, 0); } while (0)
; #define PG8_LDA(dst, b, h) do { _Pragma("unroll") for (int m = 0; m < 4; ++m) _Pragma("unroll") for (int k = 0; k < 2; ++k) dst[m][k] = *(const LAS bf16x8*)(lds + PG8_SA(b, h) + aoff + m * 2048 + k * 1024); } while (0)
; #define PG8_LDB(dst, b, h) do { _Pragma("unroll") for (int n = 0; n < 2; ++n) _Pragma("unroll") for (int k = 0; k < 2; ++k) dst[n][k] = *(const LAS bf16x8*)(lds + PG8_SB(b, h) + boff + n * 2048 + k * 1024); } while (0)
; #define PG8_MMA(ai, bj, At, Bt) do { __builtin_amdgcn_s_setprio(3); _Pragma("unroll") for (int m = 0; m < 4; ++m) _Pragma("unroll") for (int n = 0; n < 2; ++n) _Pragma("unroll") for (int k = 0; k < 2; ++k) \
;         acc[ai][bj][m][n] = __builtin_amdgcn_mfma_f32_16x16x32_bf16(Bt[n][k], At[m][k], acc[ai][bj][m][n], 0, 0, 0); __builtin_amdgcn_s_setprio(0); } while (0)
; #define PG8_WAIT_V(n) asm volatile("s_waitcnt vmcnt(" #n ")" ::: "memory")
; #define PG8_WAIT_L(n) asm volatile("s_waitcnt lgkmcnt(" #n ")" ::: "memory")
; #define PG8_BAR __builtin_amdgcn_s_barrier()
; #define PG8_SCHED __builtin_amdgcn_sched_barrier(0)
;     ...
;             PG8_WAIT_V(8); PG8_WAIT_L(0); PG8_BAR; PG8_MMA(1, 0, At, B0); PG8_MMA(1, 1, At, B1); PG8_BAR; PG8_SCHED;
;             PG8_LDB(B0, 1, 0); PG8_LDB(B1, 1, 1); PG8_SCHED; PG8_LDA(At, 1, 0); PG8_STAGE(PG8_SA(0, 1), a2 + hstepA, voffA);
;             PG8_WAIT_V(8); PG8_WAIT_L(0); PG8_BAR; PG8_MMA(0, 0, At, B0); PG8_MMA(0, 1, At, B1); PG8_BAR; PG8_SCHED;
	s_setprio 3
	s_waitcnt lgkmcnt(0)
	v_mfma_f32_16x16x32_bf16 v[62:65], v[144:147], v[212:215], v[62:65]
	v_mfma_f32_16x16x32_bf16 v[58:61], v[172:175], v[212:215], v[58:61]
	v_mfma_f32_16x16x32_bf16 v[46:49], v[144:147], v[220:223], v[46:49]
	v_mfma_f32_16x16x32_bf16 v[42:45], v[172:175], v[220:223], v[42:45]
	v_mfma_f32_16x16x32_bf16 v[30:33], v[144:147], v[228:231], v[30:33]
	v_mfma_f32_16x16x32_bf16 v[26:29], v[172:175], v[228:231], v[26:29]
	v_mfma_f32_16x16x32_bf16 v[14:17], v[144:147], v[236:239], v[14:17]
	v_mfma_f32_16x16x32_bf16 v[10:13], v[172:175], v[236:239], v[10:13]
	v_mfma_f32_16x16x32_bf16 v[62:65], v[168:171], v[216:219], v[62:65]
	v_mfma_f32_16x16x32_bf16 v[58:61], v[192:195], v[216:219], v[58:61]
	v_mfma_f32_16x16x32_bf16 v[46:49], v[168:171], v[224:227], v[46:49]
	v_mfma_f32_16x16x32_bf16 v[42:45], v[192:195], v[224:227], v[42:45]
	v_mfma_f32_16x16x32_bf16 v[30:33], v[168:171], v[232:235], v[30:33]
	v_mfma_f32_16x16x32_bf16 v[26:29], v[192:195], v[232:235], v[26:29]
	v_mfma_f32_16x16x32_bf16 v[14:17], v[168:171], v[240:243], v[14:17]
	v_mfma_f32_16x16x32_bf16 v[10:13], v[192:195], v[240:243], v[10:13]
	v_mfma_f32_16x16x32_bf16 v[54:57], v[196:199], v[212:215], v[54:57]
	v_mfma_f32_16x16x32_bf16 v[50:53], v[204:207], v[212:215], v[50:53]
	v_mfma_f32_16x16x32_bf16 v[38:41], v[196:199], v[220:223], v[38:41]
	v_mfma_f32_16x16x32_bf16 v[34:37], v[204:207], v[220:223], v[34:37]
	v_mfma_f32_16x16x32_bf16 v[22:25], v[196:199], v[228:231], v[22:25]
	v_mfma_f32_16x16x32_bf16 v[18:21], v[204:207], v[228:231], v[18:21]
	v_mfma_f32_16x16x32_bf16 v[6:9], v[196:199], v[236:239], v[6:9]
	v_mfma_f32_16x16x32_bf16 v[2:5], v[204:207], v[236:239], v[2:5]
	v_mfma_f32_16x16x32_bf16 v[54:57], v[200:203], v[216:219], v[54:57]
	v_mfma_f32_16x16x32_bf16 v[50:53], v[208:211], v[216:219], v[50:53]
	v_mfma_f32_16x16x32_bf16 v[38:41], v[200:203], v[224:227], v[38:41]
	v_mfma_f32_16x16x32_bf16 v[34:37], v[208:211], v[224:227], v[34:37]
	v_mfma_f32_16x16x32_bf16 v[22:25], v[200:203], v[232:235], v[22:25]
	v_mfma_f32_16x16x32_bf16 v[18:21], v[208:211], v[232:235], v[18:21]
	v_mfma_f32_16x16x32_bf16 v[6:9], v[200:203], v[240:243], v[6:9]
	v_mfma_f32_16x16x32_bf16 v[2:5], v[208:211], v[240:243], v[2:5]
	s_setprio 0
	s_barrier
	s_add_i32 s77, 0, 0x18000
	v_add_u32_e32 v167, s77, v164
	s_add_i32 s87, 0, 0x1c000
	ds_read_b128 v[144:147], v167
	ds_read_b128 v[168:171], v167 offset:1024
	ds_read_b128 v[172:175], v167 offset:2048
	ds_read_b128 v[192:195], v167 offset:3072
	v_add_u32_e32 v167, s87, v164
	ds_read_b128 v[196:199], v167
	ds_read_b128 v[200:203], v167 offset:1024
	ds_read_b128 v[204:207], v167 offset:2048
	ds_read_b128 v[208:211], v167 offset:3072
	s_add_u32 s82, s82, 0x40000
	s_addc_u32 s83, s83, 0
	s_mov_b32 m0, s71
	v_lshl_add_u64 v[250:251], s[82:83], 0, v[136:137]
	ds_read_b128 v[212:215], v166 offset:32768
	ds_read_b128 v[216:219], v166 offset:33792
	ds_read_b128 v[220:223], v166 offset:34816
	ds_read_b128 v[224:227], v166 offset:35840
	ds_read_b128 v[228:231], v166 offset:36864
	ds_read_b128 v[232:235], v166 offset:37888
	ds_read_b128 v[236:239], v166 offset:38912
	ds_read_b128 v[240:243], v166 offset:39936
	global_load_lds_dwordx4 v[250:251], off
	v_lshl_add_u64 v[250:251], s[82:83], 0, v[132:133]
	s_mov_b32 m0, s86
	s_nop 0
	global_load_lds_dwordx4 v[250:251], off
	s_waitcnt vmcnt(8)
	s_waitcnt lgkmcnt(0)
	s_barrier
	s_setprio 3
	s_waitcnt lgkmcnt(0)
	v_mfma_f32_16x16x32_bf16 v[126:129], v[144:147], v[212:215], v[126:129]
	v_mfma_f32_16x16x32_bf16 v[122:125], v[172:175], v[212:215], v[122:125]
	v_mfma_f32_16x16x32_bf16 v[110:113], v[144:147], v[220:223], v[110:113]
	v_mfma_f32_16x16x32_bf16 v[106:109], v[172:175], v[220:223], v[106:109]
	v_mfma_f32_16x16x32_bf16 v[94:97], v[144:147], v[228:231], v[94:97]
	v_mfma_f32_16x16x32_bf16 v[90:93], v[172:175], v[228:231], v[90:93]
	v_mfma_f32_16x16x32_bf16 v[78:81], v[144:147], v[236:239], v[78:81]
	v_mfma_f32_16x16x32_bf16 v[74:77], v[172:175], v[236:239], v[74:77]
	v_mfma_f32_16x16x32_bf16 v[126:129], v[168:171], v[216:219], v[126:129]
	v_mfma_f32_16x16x32_bf16 v[122:125], v[192:195], v[216:219], v[122:125]
	v_mfma_f32_16x16x32_bf16 v[110:113], v[168:171], v[224:227], v[110:113]
	v_mfma_f32_16x16x32_bf16 v[106:109], v[192:195], v[224:227], v[106:109]
	v_mfma_f32_16x16x32_bf16 v[94:97], v[168:171], v[232:235], v[94:97]
	v_mfma_f32_16x16x32_bf16 v[90:93], v[192:195], v[232:235], v[90:93]
	v_mfma_f32_16x16x32_bf16 v[78:81], v[168:171], v[240:243], v[78:81]
	v_mfma_f32_16x16x32_bf16 v[74:77], v[192:195], v[240:243], v[74:77]
	v_mfma_f32_16x16x32_bf16 v[118:121], v[196:199], v[212:215], v[118:121]
	v_mfma_f32_16x16x32_bf16 v[114:117], v[204:207], v[212:215], v[114:117]
	v_mfma_f32_16x16x32_bf16 v[102:105], v[196:199], v[220:223], v[102:105]
	v_mfma_f32_16x16x32_bf16 v[98:101], v[204:207], v[220:223], v[98:101]
	v_mfma_f32_16x16x32_bf16 v[86:89], v[196:199], v[228:231], v[86:89]
	v_mfma_f32_16x16x32_bf16 v[82:85], v[204:207], v[228:231], v[82:85]
	v_mfma_f32_16x16x32_bf16 v[70:73], v[196:199], v[236:239], v[70:73]
	v_mfma_f32_16x16x32_bf16 v[66:69], v[204:207], v[236:239], v[66:69]
	v_mfma_f32_16x16x32_bf16 v[118:121], v[200:203], v[216:219], v[118:121]
	v_mfma_f32_16x16x32_bf16 v[114:117], v[208:211], v[216:219], v[114:117]
	v_mfma_f32_16x16x32_bf16 v[102:105], v[200:203], v[224:227], v[102:105]
	v_mfma_f32_16x16x32_bf16 v[98:101], v[208:211], v[224:227], v[98:101]
	v_mfma_f32_16x16x32_bf16 v[86:89], v[200:203], v[232:235], v[86:89]
	v_mfma_f32_16x16x32_bf16 v[82:85], v[208:211], v[232:235], v[82:85]
	v_mfma_f32_16x16x32_bf16 v[70:73], v[200:203], v[240:243], v[70:73]
	v_mfma_f32_16x16x32_bf16 v[66:69], v[208:211], v[240:243], v[66:69]
	s_setprio 0
	s_barrier
; #define PG8_STAGE(bufoff, gbase, voff) do { _Pragma("unroll") for (int _i = 0; _i < 2; ++_i) \
;         __builtin_amdgcn_global_load_lds((const unsigned*)((const char*)(gbase) + (voff)[_i]), (LAS unsigned*)(lds + (bufoff) + ldsw + _i * 8192), 16, 0, 0); } while (0)
; #define PG8_LDA(dst, b, h) do { _Pragma("unroll") for (int m = 0; m < 4; ++m) _Pragma("unroll") for (int k = 0; k < 2; ++k) dst[m][k] = *(const LAS bf16x8*)(lds + PG8_SA(b, h) + aoff + m * 2048 + k * 1024); } while (0)
; #define PG8_MMA(ai, bj, At, Bt) do { __builtin_amdgcn_s_setprio(3); _Pragma("unroll") for (int m = 0; m < 4; ++m) _Pragma("unroll") for (int n = 0; n < 2; ++n) _Pragma("unroll") for (int k = 0; k < 2; ++k) \
;         acc[ai][bj][m][n] = __builtin_amdgcn_mfma_f32_16x16x32_bf16(Bt[n][k], At[m][k], acc[ai][bj][m][n], 0, 0, 0); __builtin_amdgcn_s_setprio(0); } while (0)
; #define PG8_WAIT_V(n) asm volatile("s_waitcnt vmcnt(" #n ")" ::: "memory")
; #define PG8_WAIT_L(n) asm volatile("s_waitcnt lgkmcnt(" #n ")" ::: "memory")
; #define PG8_BAR __builtin_amdgcn_s_barrier()
; #define PG8_SCHED __builtin_amdgcn_sched_barrier(0)
; __device__ __forceinline__ float row_rs4(const float* ssq, int row, int fq) {
;     const f32x4 a = *(const f32x4*)(ssq + (size_t)row * 16 + fq * 4);
;     float s = (a[0] + a[1]) + (a[2] + a[3]);
;     s += __shfl_xor(s, 16); s += __shfl_xor(s, 32);
;     ...
;             PG8_LDA(At, 1, 1); PG8_STAGE(PG8_SB(1, 0), b3, voffB); PG8_STAGE(PG8_SB(1, 1), b3 + hstepB, voffB); PG8_STAGE(PG8_SA(1, 0), a3, voffA);
;             PG8_WAIT_V(8); PG8_WAIT_L(0); PG8_BAR; PG8_MMA(1, 0, At, B0); PG8_MMA(1, 1, At, B1); PG8_BAR; PG8_SCHED;
	s_add_i32 s77, s77, s31
	v_lshl_add_u64 v[176:177], v[176:177], 0, s[46:47]
	s_mov_b32 m0, s77
	ds_read_b128 v[212:215], v166 offset:49152
	ds_read_b128 v[216:219], v166 offset:50176
	ds_read_b128 v[220:223], v166 offset:51200
	ds_read_b128 v[224:227], v166 offset:52224
	ds_read_b128 v[228:231], v166 offset:53248
	ds_read_b128 v[232:235], v166 offset:54272
	ds_read_b128 v[236:239], v166 offset:55296
	ds_read_b128 v[240:243], v166 offset:56320
	global_load_lds_dwordx4 v[176:177], off
	s_add_i32 m0, s77, 0x2000
	s_add_u32 s80, s80, 0x10080
	v_lshl_add_u64 v[176:177], v[244:245], 0, s[46:47]
	s_addc_u32 s81, s81, 0
	s_add_i32 s77, s87, s31
	global_load_lds_dwordx4 v[176:177], off
	v_lshl_add_u64 v[176:177], s[80:81], 0, v[134:135]
	s_mov_b32 m0, s77
	s_nop 0
	global_load_lds_dwordx4 v[176:177], off
	v_lshl_add_u64 v[176:177], s[80:81], 0, v[130:131]
	s_add_i32 m0, s77, 0x2000
	s_nop 0
	global_load_lds_dwordx4 v[176:177], off
	v_lshl_add_u64 v[176:177], v[246:247], 0, s[46:47]
	s_mov_b32 m0, s40
	s_nop 0
	global_load_lds_dwordx4 v[176:177], off
	v_lshl_add_u64 v[176:177], v[248:249], 0, s[46:47]
	s_mov_b32 m0, s4
	s_nop 0
	global_load_lds_dwordx4 v[176:177], off
	s_waitcnt vmcnt(8)
	s_waitcnt lgkmcnt(0)
	s_barrier
	s_setprio 3
	s_waitcnt lgkmcnt(0)
	v_mfma_f32_16x16x32_bf16 v[62:65], v[144:147], v[212:215], v[62:65]
	v_mfma_f32_16x16x32_bf16 v[58:61], v[172:175], v[212:215], v[58:61]
	v_mfma_f32_16x16x32_bf16 v[46:49], v[144:147], v[220:223], v[46:49]
	v_mfma_f32_16x16x32_bf16 v[42:45], v[172:175], v[220:223], v[42:45]
	v_mfma_f32_16x16x32_bf16 v[30:33], v[144:147], v[228:231], v[30:33]
	v_mfma_f32_16x16x32_bf16 v[26:29], v[172:175], v[228:231], v[26:29]
	v_mfma_f32_16x16x32_bf16 v[14:17], v[144:147], v[236:239], v[14:17]
	v_mfma_f32_16x16x32_bf16 v[10:13], v[172:175], v[236:239], v[10:13]
	v_mfma_f32_16x16x32_bf16 v[62:65], v[168:171], v[216:219], v[62:65]
	v_mfma_f32_16x16x32_bf16 v[58:61], v[192:195], v[216:219], v[58:61]
	v_mfma_f32_16x16x32_bf16 v[46:49], v[168:171], v[224:227], v[46:49]
	v_mfma_f32_16x16x32_bf16 v[42:45], v[192:195], v[224:227], v[42:45]
	v_mfma_f32_16x16x32_bf16 v[30:33], v[168:171], v[232:235], v[30:33]
	v_mfma_f32_16x16x32_bf16 v[26:29], v[192:195], v[232:235], v[26:29]
	v_mfma_f32_16x16x32_bf16 v[14:17], v[168:171], v[240:243], v[14:17]
	v_mfma_f32_16x16x32_bf16 v[10:13], v[192:195], v[240:243], v[10:13]
	v_mfma_f32_16x16x32_bf16 v[54:57], v[196:199], v[212:215], v[54:57]
	v_mfma_f32_16x16x32_bf16 v[50:53], v[204:207], v[212:215], v[50:53]
	v_mfma_f32_16x16x32_bf16 v[38:41], v[196:199], v[220:223], v[38:41]
	v_mfma_f32_16x16x32_bf16 v[34:37], v[204:207], v[220:223], v[34:37]
	v_mfma_f32_16x16x32_bf16 v[22:25], v[196:199], v[228:231], v[22:25]
	v_mfma_f32_16x16x32_bf16 v[18:21], v[204:207], v[228:231], v[18:21]
	v_mfma_f32_16x16x32_bf16 v[6:9], v[196:199], v[236:239], v[6:9]
	v_mfma_f32_16x16x32_bf16 v[2:5], v[204:207], v[236:239], v[2:5]
	v_mfma_f32_16x16x32_bf16 v[54:57], v[200:203], v[216:219], v[54:57]
	v_mfma_f32_16x16x32_bf16 v[50:53], v[208:211], v[216:219], v[50:53]
	v_mfma_f32_16x16x32_bf16 v[38:41], v[200:203], v[224:227], v[38:41]
	v_mfma_f32_16x16x32_bf16 v[34:37], v[208:211], v[224:227], v[34:37]
	v_mfma_f32_16x16x32_bf16 v[22:25], v[200:203], v[232:235], v[22:25]
	v_mfma_f32_16x16x32_bf16 v[18:21], v[208:211], v[232:235], v[18:21]
	v_mfma_f32_16x16x32_bf16 v[6:9], v[200:203], v[240:243], v[6:9]
	v_mfma_f32_16x16x32_bf16 v[2:5], v[208:211], v[240:243], v[2:5]
	s_setprio 0
	s_barrier
	s_add_i32 s61, s61, 2
	s_add_u32 s42, s42, 0x100
	s_addc_u32 s60, s60, 0
	s_add_u32 s78, s78, 0x100
	s_addc_u32 s79, s79, 0
	s_cmp_gt_u32 s61, 13
	s_cbranch_scc0 .LBB0_451
	v_lshl_add_u32 v232, s76, 8, v1
	v_ashrrev_i32_e32 v233, 31, v232
	v_lshlrev_b64 v[234:235], 6, v[232:233]
	v_lshl_add_u64 v[234:235], v[138:139], 0, v[234:235]
	global_load_dwordx4 v[192:195], v[234:235], off
	global_load_dwordx4 v[196:199], v[234:235], off offset:1024
	global_load_dwordx4 v[200:203], v[234:235], off offset:2048
	global_load_dwordx4 v[204:207], v[234:235], off offset:3072
	v_add_u32_e32 v232, 0x80, v232
	v_ashrrev_i32_e32 v233, 31, v232
	v_lshlrev_b64 v[234:235], 6, v[232:233]
	v_lshl_add_u64 v[234:235], v[138:139], 0, v[234:235]
	global_load_dwordx4 v[208:211], v[234:235], off
	global_load_dwordx4 v[212:215], v[234:235], off offset:1024
	global_load_dwordx4 v[216:219], v[234:235], off offset:2048
	global_load_dwordx4 v[220:223], v[234:235], off offset:3072
	v_xor_b32_e32 v176, 16, v182
	v_xor_b32_e32 v177, 32, v182
	v_lshlrev_b32_e32 v176, 2, v176
	v_lshlrev_b32_e32 v177, 2, v177
	s_and_b64 vcc, exec, s[6:7]
	s_cbranch_vccz .LBB0_454
	s_barrier

; #define PG8_STAGE(bufoff, gbase, voff) do { _Pragma("unroll") for (int _i = 0; _i < 2; ++_i) \
;         __builtin_amdgcn_global_load_lds((const unsigned*)((const char*)(gbase) + (voff)[_i]), (LAS unsigned*)(lds + (bufoff) + ldsw + _i * 8192), 16, 0, 0); } while (0)
; #define PG8_LDA(dst, b, h) do { _Pragma("unroll") for (int m = 0; m < 4; ++m) _Pragma("unroll") for (int k = 0; k < 2; ++k) dst[m][k] = *(const LAS bf16x8*)(lds + PG8_SA(b, h) + aoff + m * 2048 + k * 1024); } while (0)
; #define PG8_LDB(dst, b, h) do { _Pragma("unroll") for (int n = 0; n < 2; ++n) _Pragma("unroll") for (int k = 0; k < 2; ++k) dst[n][k] = *(const LAS bf16x8*)(lds + PG8_SB(b, h) + boff + n * 2048 + k * 1024); } while (0)
; #define PG8_MMA(ai, bj, At, Bt) do { __builtin_amdgcn_s_setprio(3); _Pragma("unroll") for (int m = 0; m < 4; ++m) _Pragma("unroll") for (int n = 0; n < 2; ++n) _Pragma("unroll") for (int k = 0; k < 2; ++k) \
;         acc[ai][bj][m][n] = __builtin_amdgcn_mfma_f32_16x16x32_bf16(Bt[n][k], At[m][k], acc[ai][bj][m][n], 0, 0, 0); __builtin_amdgcn_s_setprio(0); } while (0)
; #define PG8_WAIT_V(n) asm volatile("s_waitcnt vmcnt(" #n ")" ::: "memory")
; #define PG8_WAIT_L(n) asm volatile("s_waitcnt lgkmcnt(" #n ")" ::: "memory")
; #define PG8_BAR __builtin_amdgcn_s_barrier()
; #define PG8_SCHED __builtin_amdgcn_sched_barrier(0)
;     ...
;             PG8_LDB(B0, 0, 0); PG8_LDB(B1, 0, 1); PG8_SCHED; PG8_LDA(At, 0, 0); PG8_STAGE(PG8_SA(1, 1), a1 + hstepA, voffA);
;             PG8_WAIT_V(8); PG8_WAIT_L(0); PG8_BAR; PG8_MMA(0, 0, At, B0); PG8_MMA(0, 1, At, B1); PG8_BAR; PG8_SCHED;
;             PG8_LDA(At, 0, 1); PG8_STAGE(PG8_SB(0, 0), b2, voffB); PG8_STAGE(PG8_SB(0, 1), b2 + hstepB, voffB); PG8_STAGE(PG8_SA(0, 0), a2, voffA);
;             PG8_WAIT_V(8); PG8_WAIT_L(0); PG8_BAR; PG8_MMA(1, 0, At, B0); PG8_MMA(1, 1, At, B1); PG8_BAR; PG8_SCHED;
.LBB0_811:
	s_add_u32 s73, s74, 0xfffc0080
	s_addc_u32 s76, s75, -1
	s_add_i32 s86, 0, 0x10000
	s_cmp_eq_u32 s61, 12
	s_cselect_b32 s79, s11, s76
	s_cselect_b32 s78, s34, s73
	v_add_u32_e32 v167, s86, v164
	s_cselect_b32 s77, s9, s60
	s_cselect_b32 s76, s35, s42
	s_add_i32 s73, 0, 0x14000
	ds_read_b128 v[144:147], v167
	ds_read_b128 v[168:171], v167 offset:1024
	ds_read_b128 v[172:175], v167 offset:2048
	ds_read_b128 v[192:195], v167 offset:3072
	v_add_u32_e32 v167, s73, v164
	ds_read_b128 v[196:199], v167
	ds_read_b128 v[200:203], v167 offset:1024
	ds_read_b128 v[204:207], v167 offset:2048
	ds_read_b128 v[208:211], v167 offset:3072
	v_lshl_add_u64 v[176:177], s[74:75], 0, v[142:143]
	s_add_i32 m0, s69, 0xc000
	ds_read_b128 v[212:215], v166
	ds_read_b128 v[216:219], v166 offset:1024
	ds_read_b128 v[220:223], v166 offset:2048
	ds_read_b128 v[224:227], v166 offset:3072
	ds_read_b128 v[228:231], v166 offset:4096
	ds_read_b128 v[232:235], v166 offset:5120
	ds_read_b128 v[236:239], v166 offset:6144
	ds_read_b128 v[240:243], v166 offset:7168
	global_load_lds_dwordx4 v[176:177], off
	v_lshl_add_u64 v[176:177], s[74:75], 0, v[140:141]
	s_add_i32 m0, s69, 0xe000
	s_nop 0
	global_load_lds_dwordx4 v[176:177], off
	s_waitcnt vmcnt(8)
	s_waitcnt lgkmcnt(0)
	s_barrier
	s_setprio 3
	s_waitcnt lgkmcnt(0)
	v_mfma_f32_16x16x32_bf16 v[126:129], v[144:147], v[212:215], v[126:129]
	v_mfma_f32_16x16x32_bf16 v[122:125], v[172:175], v[212:215], v[122:125]
	v_mfma_f32_16x16x32_bf16 v[110:113], v[144:147], v[220:223], v[110:113]
	v_mfma_f32_16x16x32_bf16 v[106:109], v[172:175], v[220:223], v[106:109]
	v_mfma_f32_16x16x32_bf16 v[94:97], v[144:147], v[228:231], v[94:97]
	v_mfma_f32_16x16x32_bf16 v[90:93], v[172:175], v[228:231], v[90:93]
	v_mfma_f32_16x16x32_bf16 v[78:81], v[144:147], v[236:239], v[78:81]
	v_mfma_f32_16x16x32_bf16 v[74:77], v[172:175], v[236:239], v[74:77]
	v_mfma_f32_16x16x32_bf16 v[126:129], v[168:171], v[216:219], v[126:129]
	v_mfma_f32_16x16x32_bf16 v[122:125], v[192:195], v[216:219], v[122:125]
	v_mfma_f32_16x16x32_bf16 v[110:113], v[168:171], v[224:227], v[110:113]
	v_mfma_f32_16x16x32_bf16 v[106:109], v[192:195], v[224:227], v[106:109]
	v_mfma_f32_16x16x32_bf16 v[94:97], v[168:171], v[232:235], v[94:97]
	v_mfma_f32_16x16x32_bf16 v[90:93], v[192:195], v[232:235], v[90:93]
	v_mfma_f32_16x16x32_bf16 v[78:81], v[168:171], v[240:243], v[78:81]
	v_mfma_f32_16x16x32_bf16 v[74:77], v[192:195], v[240:243], v[74:77]
	v_mfma_f32_16x16x32_bf16 v[118:121], v[196:199], v[212:215], v[118:121]
	v_mfma_f32_16x16x32_bf16 v[114:117], v[204:207], v[212:215], v[114:117]
	v_mfma_f32_16x16x32_bf16 v[102:105], v[196:199], v[220:223], v[102:105]
	v_mfma_f32_16x16x32_bf16 v[98:101], v[204:207], v[220:223], v[98:101]
	v_mfma_f32_16x16x32_bf16 v[86:89], v[196:199], v[228:231], v[86:89]
	v_mfma_f32_16x16x32_bf16 v[82:85], v[204:207], v[228:231], v[82:85]
	v_mfma_f32_16x16x32_bf16 v[70:73], v[196:199], v[236:239], v[70:73]
	v_mfma_f32_16x16x32_bf16 v[66:69], v[204:207], v[236:239], v[66:69]
	v_mfma_f32_16x16x32_bf16 v[118:121], v[200:203], v[216:219], v[118:121]
	v_mfma_f32_16x16x32_bf16 v[114:117], v[208:211], v[216:219], v[114:117]
	v_mfma_f32_16x16x32_bf16 v[102:105], v[200:203], v[224:227], v[102:105]
	v_mfma_f32_16x16x32_bf16 v[98:101], v[208:211], v[224:227], v[98:101]
	v_mfma_f32_16x16x32_bf16 v[86:89], v[200:203], v[232:235], v[86:89]
	v_mfma_f32_16x16x32_bf16 v[82:85], v[208:211], v[232:235], v[82:85]
	v_mfma_f32_16x16x32_bf16 v[70:73], v[200:203], v[240:243], v[70:73]
	v_mfma_f32_16x16x32_bf16 v[66:69], v[208:211], v[240:243], v[66:69]
	s_setprio 0
	s_barrier
	s_add_i32 s86, s86, s40
	v_lshl_add_u64 v[176:177], s[76:77], 0, v[134:135]
	s_mov_b32 m0, s86
	ds_read_b128 v[212:215], v166 offset:16384
	ds_read_b128 v[216:219], v166 offset:17408
	ds_read_b128 v[220:223], v166 offset:18432
	ds_read_b128 v[224:227], v166 offset:19456
	ds_read_b128 v[228:231], v166 offset:20480
	ds_read_b128 v[232:235], v166 offset:21504
	ds_read_b128 v[236:239], v166 offset:22528
	ds_read_b128 v[240:243], v166 offset:23552
	global_load_lds_dwordx4 v[176:177], off
	s_add_i32 m0, s86, 0x2000
	s_add_u32 s86, s76, 0x10000
	v_lshl_add_u64 v[244:245], s[76:77], 0, v[130:131]
	s_addc_u32 s87, s77, 0
	s_add_i32 s73, s73, s40
	global_load_lds_dwordx4 v[244:245], off
	v_lshl_add_u64 v[246:247], s[86:87], 0, v[134:135]
	s_mov_b32 m0, s73
	v_lshl_add_u64 v[248:249], s[78:79], 0, v[132:133]
	global_load_lds_dwordx4 v[246:247], off
	v_lshl_add_u64 v[246:247], s[86:87], 0, v[130:131]
	s_add_i32 m0, s73, 0x2000
	s_nop 0
	global_load_lds_dwordx4 v[246:247], off
	v_lshl_add_u64 v[246:247], s[78:79], 0, v[136:137]
	s_mov_b32 m0, s69
	s_nop 0
	global_load_lds_dwordx4 v[246:247], off
	s_mov_b32 m0, s70
	s_nop 0
	global_load_lds_dwordx4 v[248:249], off
	s_waitcnt vmcnt(8)
	s_waitcnt lgkmcnt(0)
	s_barrier
; #define PG8_STAGE(bufoff, gbase, voff) do { _Pragma("unroll") for (int _i = 0; _i < 2; ++_i) \
;         __builtin_amdgcn_global_load_lds((const unsigned*)((const char*)(gbase) + (voff)[_i]), (LAS unsigned*)(lds + (bufoff) + ldsw + _i * 8192), 16, 0, 0); } while (0)
; #define PG8_LDA(dst, b, h) do { _Pragma("unroll") for (int m = 0; m < 4; ++m) _Pragma("unroll") for (int k = 0; k < 2; ++k) dst[m][k] = *(const LAS bf16x8*)(lds + PG8_SA(b, h) + aoff + m * 2048 + k * 1024); } while (0)
; #define PG8_LDB(dst, b, h) do { _Pragma("unroll") for (int n = 0; n < 2; ++n) _Pragma("unroll") for (int k = 0; k < 2; ++k) dst[n][k] = *(const LAS bf16x8*)(lds + PG8_SB(b, h) + boff + n * 2048 + k * 1024); } while (0)
; #define PG8_MMA(ai, bj, At, Bt) do { __builtin_amdgcn_s_setprio(3); _Pragma("unroll") for (int m = 0; m < 4; ++m) _Pragma("unroll") for (int n = 0; n < 2; ++n) _Pragma("unroll") for (int k = 0; k < 2; ++k) \
;         acc[ai][bj][m][n] = __builtin_amdgcn_mfma_f32_16x16x32_bf16(Bt[n][k], At[m][k], acc[ai][bj][m][n], 0, 0, 0); __builtin_amdgcn_s_setprio(0); } while (0)
; #define PG8_WAIT_V(n) asm volatile("s_waitcnt vmcnt(" #n ")" ::: "memory")
; #define PG8_WAIT_L(n) asm volatile("s_waitcnt lgkmcnt(" #n ")" ::: "memory")
; #define PG8_BAR __builtin_amdgcn_s_barrier()
; #define PG8_SCHED __builtin_amdgcn_sched_barrier(0)
;     ...
;             PG8_WAIT_V(8); PG8_WAIT_L(0); PG8_BAR; PG8_MMA(1, 0, At, B0); PG8_MMA(1, 1, At, B1); PG8_BAR; PG8_SCHED;
;             PG8_LDB(B0, 1, 0); PG8_LDB(B1, 1, 1); PG8_SCHED; PG8_LDA(At, 1, 0); PG8_STAGE(PG8_SA(0, 1), a2 + hstepA, voffA);
;             PG8_WAIT_V(8); PG8_WAIT_L(0); PG8_BAR; PG8_MMA(0, 0, At, B0); PG8_MMA(0, 1, At, B1); PG8_BAR; PG8_SCHED;
	s_setprio 3
	s_waitcnt lgkmcnt(0)
	v_mfma_f32_16x16x32_bf16 v[62:65], v[144:147], v[212:215], v[62:65]
	v_mfma_f32_16x16x32_bf16 v[58:61], v[172:175], v[212:215], v[58:61]
	v_mfma_f32_16x16x32_bf16 v[46:49], v[144:147], v[220:223], v[46:49]
	v_mfma_f32_16x16x32_bf16 v[42:45], v[172:175], v[220:223], v[42:45]
	v_mfma_f32_16x16x32_bf16 v[30:33], v[144:147], v[228:231], v[30:33]
	v_mfma_f32_16x16x32_bf16 v[26:29], v[172:175], v[228:231], v[26:29]
	v_mfma_f32_16x16x32_bf16 v[14:17], v[144:147], v[236:239], v[14:17]
	v_mfma_f32_16x16x32_bf16 v[10:13], v[172:175], v[236:239], v[10:13]
	v_mfma_f32_16x16x32_bf16 v[62:65], v[168:171], v[216:219], v[62:65]
	v_mfma_f32_16x16x32_bf16 v[58:61], v[192:195], v[216:219], v[58:61]
	v_mfma_f32_16x16x32_bf16 v[46:49], v[168:171], v[224:227], v[46:49]
	v_mfma_f32_16x16x32_bf16 v[42:45], v[192:195], v[224:227], v[42:45]
	v_mfma_f32_16x16x32_bf16 v[30:33], v[168:171], v[232:235], v[30:33]
	v_mfma_f32_16x16x32_bf16 v[26:29], v[192:195], v[232:235], v[26:29]
	v_mfma_f32_16x16x32_bf16 v[14:17], v[168:171], v[240:243], v[14:17]
	v_mfma_f32_16x16x32_bf16 v[10:13], v[192:195], v[240:243], v[10:13]
	v_mfma_f32_16x16x32_bf16 v[54:57], v[196:199], v[212:215], v[54:57]
	v_mfma_f32_16x16x32_bf16 v[50:53], v[204:207], v[212:215], v[50:53]
	v_mfma_f32_16x16x32_bf16 v[38:41], v[196:199], v[220:223], v[38:41]
	v_mfma_f32_16x16x32_bf16 v[34:37], v[204:207], v[220:223], v[34:37]
	v_mfma_f32_16x16x32_bf16 v[22:25], v[196:199], v[228:231], v[22:25]
	v_mfma_f32_16x16x32_bf16 v[18:21], v[204:207], v[228:231], v[18:21]
	v_mfma_f32_16x16x32_bf16 v[6:9], v[196:199], v[236:239], v[6:9]
	v_mfma_f32_16x16x32_bf16 v[2:5], v[204:207], v[236:239], v[2:5]
	v_mfma_f32_16x16x32_bf16 v[54:57], v[200:203], v[216:219], v[54:57]
	v_mfma_f32_16x16x32_bf16 v[50:53], v[208:211], v[216:219], v[50:53]
	v_mfma_f32_16x16x32_bf16 v[38:41], v[200:203], v[224:227], v[38:41]
	v_mfma_f32_16x16x32_bf16 v[34:37], v[208:211], v[224:227], v[34:37]
	v_mfma_f32_16x16x32_bf16 v[22:25], v[200:203], v[232:235], v[22:25]
	v_mfma_f32_16x16x32_bf16 v[18:21], v[208:211], v[232:235], v[18:21]
	v_mfma_f32_16x16x32_bf16 v[6:9], v[200:203], v[240:243], v[6:9]
	v_mfma_f32_16x16x32_bf16 v[2:5], v[208:211], v[240:243], v[2:5]
	s_setprio 0
	s_barrier
	s_add_i32 s73, 0, 0x18000
	v_add_u32_e32 v167, s73, v164
	s_add_i32 s86, 0, 0x1c000
	ds_read_b128 v[144:147], v167
	ds_read_b128 v[168:171], v167 offset:1024
	ds_read_b128 v[172:175], v167 offset:2048
	ds_read_b128 v[192:195], v167 offset:3072
	v_add_u32_e32 v167, s86, v164
	ds_read_b128 v[196:199], v167
	ds_read_b128 v[200:203], v167 offset:1024
	ds_read_b128 v[204:207], v167 offset:2048
	ds_read_b128 v[208:211], v167 offset:3072
	s_add_u32 s78, s78, 0x40000
	s_addc_u32 s79, s79, 0
	s_mov_b32 m0, s71
	v_lshl_add_u64 v[250:251], s[78:79], 0, v[136:137]
	ds_read_b128 v[212:215], v166 offset:32768
	ds_read_b128 v[216:219], v166 offset:33792
	ds_read_b128 v[220:223], v166 offset:34816
	ds_read_b128 v[224:227], v166 offset:35840
	ds_read_b128 v[228:231], v166 offset:36864
	ds_read_b128 v[232:235], v166 offset:37888
	ds_read_b128 v[236:239], v166 offset:38912
	ds_read_b128 v[240:243], v166 offset:39936
	global_load_lds_dwordx4 v[250:251], off
	v_lshl_add_u64 v[250:251], s[78:79], 0, v[132:133]
	s_mov_b32 m0, s80
	s_nop 0
	global_load_lds_dwordx4 v[250:251], off
	s_waitcnt vmcnt(8)
	s_waitcnt lgkmcnt(0)
	s_barrier
	s_setprio 3
	s_waitcnt lgkmcnt(0)
	v_mfma_f32_16x16x32_bf16 v[126:129], v[144:147], v[212:215], v[126:129]
	v_mfma_f32_16x16x32_bf16 v[122:125], v[172:175], v[212:215], v[122:125]
	v_mfma_f32_16x16x32_bf16 v[110:113], v[144:147], v[220:223], v[110:113]
	v_mfma_f32_16x16x32_bf16 v[106:109], v[172:175], v[220:223], v[106:109]
	v_mfma_f32_16x16x32_bf16 v[94:97], v[144:147], v[228:231], v[94:97]
	v_mfma_f32_16x16x32_bf16 v[90:93], v[172:175], v[228:231], v[90:93]
	v_mfma_f32_16x16x32_bf16 v[78:81], v[144:147], v[236:239], v[78:81]
	v_mfma_f32_16x16x32_bf16 v[74:77], v[172:175], v[236:239], v[74:77]
	v_mfma_f32_16x16x32_bf16 v[126:129], v[168:171], v[216:219], v[126:129]
	v_mfma_f32_16x16x32_bf16 v[122:125], v[192:195], v[216:219], v[122:125]
	v_mfma_f32_16x16x32_bf16 v[110:113], v[168:171], v[224:227], v[110:113]
	v_mfma_f32_16x16x32_bf16 v[106:109], v[192:195], v[224:227], v[106:109]
	v_mfma_f32_16x16x32_bf16 v[94:97], v[168:171], v[232:235], v[94:97]
	v_mfma_f32_16x16x32_bf16 v[90:93], v[192:195], v[232:235], v[90:93]
	v_mfma_f32_16x16x32_bf16 v[78:81], v[168:171], v[240:243], v[78:81]
	v_mfma_f32_16x16x32_bf16 v[74:77], v[192:195], v[240:243], v[74:77]
	v_mfma_f32_16x16x32_bf16 v[118:121], v[196:199], v[212:215], v[118:121]
	v_mfma_f32_16x16x32_bf16 v[114:117], v[204:207], v[212:215], v[114:117]
	v_mfma_f32_16x16x32_bf16 v[102:105], v[196:199], v[220:223], v[102:105]
	v_mfma_f32_16x16x32_bf16 v[98:101], v[204:207], v[220:223], v[98:101]
	v_mfma_f32_16x16x32_bf16 v[86:89], v[196:199], v[228:231], v[86:89]
	v_mfma_f32_16x16x32_bf16 v[82:85], v[204:207], v[228:231], v[82:85]
	v_mfma_f32_16x16x32_bf16 v[70:73], v[196:199], v[236:239], v[70:73]
	v_mfma_f32_16x16x32_bf16 v[66:69], v[204:207], v[236:239], v[66:69]
	v_mfma_f32_16x16x32_bf16 v[118:121], v[200:203], v[216:219], v[118:121]
	v_mfma_f32_16x16x32_bf16 v[114:117], v[208:211], v[216:219], v[114:117]
	v_mfma_f32_16x16x32_bf16 v[102:105], v[200:203], v[224:227], v[102:105]
	v_mfma_f32_16x16x32_bf16 v[98:101], v[208:211], v[224:227], v[98:101]
	v_mfma_f32_16x16x32_bf16 v[86:89], v[200:203], v[232:235], v[86:89]
	v_mfma_f32_16x16x32_bf16 v[82:85], v[208:211], v[232:235], v[82:85]
	v_mfma_f32_16x16x32_bf16 v[70:73], v[200:203], v[240:243], v[70:73]
	v_mfma_f32_16x16x32_bf16 v[66:69], v[208:211], v[240:243], v[66:69]
	s_setprio 0
	s_barrier
; #define PG8_STAGE(bufoff, gbase, voff) do { _Pragma("unroll") for (int _i = 0; _i < 2; ++_i) \
;         __builtin_amdgcn_global_load_lds((const unsigned*)((const char*)(gbase) + (voff)[_i]), (LAS unsigned*)(lds + (bufoff) + ldsw + _i * 8192), 16, 0, 0); } while (0)
; #define PG8_LDA(dst, b, h) do { _Pragma("unroll") for (int m = 0; m < 4; ++m) _Pragma("unroll") for (int k = 0; k < 2; ++k) dst[m][k] = *(const LAS bf16x8*)(lds + PG8_SA(b, h) + aoff + m * 2048 + k * 1024); } while (0)
; #define PG8_MMA(ai, bj, At, Bt) do { __builtin_amdgcn_s_setprio(3); _Pragma("unroll") for (int m = 0; m < 4; ++m) _Pragma("unroll") for (int n = 0; n < 2; ++n) _Pragma("unroll") for (int k = 0; k < 2; ++k) \
;         acc[ai][bj][m][n] = __builtin_amdgcn_mfma_f32_16x16x32_bf16(Bt[n][k], At[m][k], acc[ai][bj][m][n], 0, 0, 0); __builtin_amdgcn_s_setprio(0); } while (0)
; #define PG8_WAIT_V(n) asm volatile("s_waitcnt vmcnt(" #n ")" ::: "memory")
; #define PG8_WAIT_L(n) asm volatile("s_waitcnt lgkmcnt(" #n ")" ::: "memory")
; #define PG8_BAR __builtin_amdgcn_s_barrier()
; #define PG8_SCHED __builtin_amdgcn_sched_barrier(0)
; __device__ __forceinline__ float row_rs4(const float* ssq, int row, int fq) {
;     const f32x4 a = *(const f32x4*)(ssq + (size_t)row * 16 + fq * 4);
;     float s = (a[0] + a[1]) + (a[2] + a[3]);
;     s += __shfl_xor(s, 16); s += __shfl_xor(s, 32);
;     ...
;             PG8_LDA(At, 1, 1); PG8_STAGE(PG8_SB(1, 0), b3, voffB); PG8_STAGE(PG8_SB(1, 1), b3 + hstepB, voffB); PG8_STAGE(PG8_SA(1, 0), a3, voffA);
;             PG8_WAIT_V(8); PG8_WAIT_L(0); PG8_BAR; PG8_MMA(1, 0, At, B0); PG8_MMA(1, 1, At, B1); PG8_BAR; PG8_SCHED;
	s_add_i32 s73, s73, s40
	v_lshl_add_u64 v[176:177], v[176:177], 0, s[46:47]
	s_mov_b32 m0, s73
	ds_read_b128 v[212:215], v166 offset:49152
	ds_read_b128 v[216:219], v166 offset:50176
	ds_read_b128 v[220:223], v166 offset:51200
	ds_read_b128 v[224:227], v166 offset:52224
	ds_read_b128 v[228:231], v166 offset:53248
	ds_read_b128 v[232:235], v166 offset:54272
	ds_read_b128 v[236:239], v166 offset:55296
	ds_read_b128 v[240:243], v166 offset:56320
	global_load_lds_dwordx4 v[176:177], off
	s_add_i32 m0, s73, 0x2000
	s_add_u32 s76, s76, 0x10080
	v_lshl_add_u64 v[176:177], v[244:245], 0, s[46:47]
	s_addc_u32 s77, s77, 0
	s_add_i32 s73, s86, s40
	global_load_lds_dwordx4 v[176:177], off
	v_lshl_add_u64 v[176:177], s[76:77], 0, v[134:135]
	s_mov_b32 m0, s73
	s_nop 0
	global_load_lds_dwordx4 v[176:177], off
	v_lshl_add_u64 v[176:177], s[76:77], 0, v[130:131]
	s_add_i32 m0, s73, 0x2000
	s_nop 0
	global_load_lds_dwordx4 v[176:177], off
	v_lshl_add_u64 v[176:177], v[246:247], 0, s[46:47]
	s_mov_b32 m0, s82
	s_nop 0
	global_load_lds_dwordx4 v[176:177], off
	v_lshl_add_u64 v[176:177], v[248:249], 0, s[46:47]
	s_mov_b32 m0, s83
	s_nop 0
	global_load_lds_dwordx4 v[176:177], off
	s_waitcnt vmcnt(8)
	s_waitcnt lgkmcnt(0)
	s_barrier
	s_setprio 3
	s_waitcnt lgkmcnt(0)
	v_mfma_f32_16x16x32_bf16 v[62:65], v[144:147], v[212:215], v[62:65]
	v_mfma_f32_16x16x32_bf16 v[58:61], v[172:175], v[212:215], v[58:61]
	v_mfma_f32_16x16x32_bf16 v[46:49], v[144:147], v[220:223], v[46:49]
	v_mfma_f32_16x16x32_bf16 v[42:45], v[172:175], v[220:223], v[42:45]
	v_mfma_f32_16x16x32_bf16 v[30:33], v[144:147], v[228:231], v[30:33]
	v_mfma_f32_16x16x32_bf16 v[26:29], v[172:175], v[228:231], v[26:29]
	v_mfma_f32_16x16x32_bf16 v[14:17], v[144:147], v[236:239], v[14:17]
	v_mfma_f32_16x16x32_bf16 v[10:13], v[172:175], v[236:239], v[10:13]
	v_mfma_f32_16x16x32_bf16 v[62:65], v[168:171], v[216:219], v[62:65]
	v_mfma_f32_16x16x32_bf16 v[58:61], v[192:195], v[216:219], v[58:61]
	v_mfma_f32_16x16x32_bf16 v[46:49], v[168:171], v[224:227], v[46:49]
	v_mfma_f32_16x16x32_bf16 v[42:45], v[192:195], v[224:227], v[42:45]
	v_mfma_f32_16x16x32_bf16 v[30:33], v[168:171], v[232:235], v[30:33]
	v_mfma_f32_16x16x32_bf16 v[26:29], v[192:195], v[232:235], v[26:29]
	v_mfma_f32_16x16x32_bf16 v[14:17], v[168:171], v[240:243], v[14:17]
	v_mfma_f32_16x16x32_bf16 v[10:13], v[192:195], v[240:243], v[10:13]
	v_mfma_f32_16x16x32_bf16 v[54:57], v[196:199], v[212:215], v[54:57]
	v_mfma_f32_16x16x32_bf16 v[50:53], v[204:207], v[212:215], v[50:53]
	v_mfma_f32_16x16x32_bf16 v[38:41], v[196:199], v[220:223], v[38:41]
	v_mfma_f32_16x16x32_bf16 v[34:37], v[204:207], v[220:223], v[34:37]
	v_mfma_f32_16x16x32_bf16 v[22:25], v[196:199], v[228:231], v[22:25]
	v_mfma_f32_16x16x32_bf16 v[18:21], v[204:207], v[228:231], v[18:21]
	v_mfma_f32_16x16x32_bf16 v[6:9], v[196:199], v[236:239], v[6:9]
	v_mfma_f32_16x16x32_bf16 v[2:5], v[204:207], v[236:239], v[2:5]
	v_mfma_f32_16x16x32_bf16 v[54:57], v[200:203], v[216:219], v[54:57]
	v_mfma_f32_16x16x32_bf16 v[50:53], v[208:211], v[216:219], v[50:53]
	v_mfma_f32_16x16x32_bf16 v[38:41], v[200:203], v[224:227], v[38:41]
	v_mfma_f32_16x16x32_bf16 v[34:37], v[208:211], v[224:227], v[34:37]
	v_mfma_f32_16x16x32_bf16 v[22:25], v[200:203], v[232:235], v[22:25]
	v_mfma_f32_16x16x32_bf16 v[18:21], v[208:211], v[232:235], v[18:21]
	v_mfma_f32_16x16x32_bf16 v[6:9], v[200:203], v[240:243], v[6:9]
	v_mfma_f32_16x16x32_bf16 v[2:5], v[208:211], v[240:243], v[2:5]
	s_setprio 0
	s_barrier
	s_add_i32 s61, s61, 2
	s_add_u32 s42, s42, 0x100
	s_addc_u32 s60, s60, 0
	s_add_u32 s74, s74, 0x100
	s_addc_u32 s75, s75, 0
	s_cmp_gt_u32 s61, 13
	s_cbranch_scc0 .LBB0_811
	v_lshl_add_u32 v232, s72, 8, v1
	v_ashrrev_i32_e32 v233, 31, v232
	v_lshlrev_b64 v[234:235], 6, v[232:233]
	v_lshl_add_u64 v[234:235], v[138:139], 0, v[234:235]
	global_load_dwordx4 v[192:195], v[234:235], off
	global_load_dwordx4 v[196:199], v[234:235], off offset:1024
	global_load_dwordx4 v[200:203], v[234:235], off offset:2048
	global_load_dwordx4 v[204:207], v[234:235], off offset:3072
	v_add_u32_e32 v232, 0x80, v232
	v_ashrrev_i32_e32 v233, 31, v232
	v_lshlrev_b64 v[234:235], 6, v[232:233]
	v_lshl_add_u64 v[234:235], v[138:139], 0, v[234:235]
	global_load_dwordx4 v[208:211], v[234:235], off
	global_load_dwordx4 v[212:215], v[234:235], off offset:1024
	global_load_dwordx4 v[216:219], v[234:235], off offset:2048
	global_load_dwordx4 v[220:223], v[234:235], off offset:3072
	v_xor_b32_e32 v176, 16, v182
	v_xor_b32_e32 v177, 32, v182
	v_lshlrev_b32_e32 v176, 2, v176
	v_lshlrev_b32_e32 v177, 2, v177
	s_and_b64 vcc, exec, s[6:7]
	s_cbranch_vccz .LBB0_814
	s_barrier

; #define PG8_STAGE(bufoff, gbase, voff) do { _Pragma("unroll") for (int _i = 0; _i < 2; ++_i) \
;         __builtin_amdgcn_global_load_lds((const unsigned*)((const char*)(gbase) + (voff)[_i]), (LAS unsigned*)(lds + (bufoff) + ldsw + _i * 8192), 16, 0, 0); } while (0)
; #define PG8_LDA(dst, b, h) do { _Pragma("unroll") for (int m = 0; m < 4; ++m) _Pragma("unroll") for (int k = 0; k < 2; ++k) dst[m][k] = *(const LAS bf16x8*)(lds + PG8_SA(b, h) + aoff + m * 2048 + k * 1024); } while (0)
; #define PG8_LDB(dst, b, h) do { _Pragma("unroll") for (int n = 0; n < 2; ++n) _Pragma("unroll") for (int k = 0; k < 2; ++k) dst[n][k] = *(const LAS bf16x8*)(lds + PG8_SB(b, h) + boff + n * 2048 + k * 1024); } while (0)
; #define PG8_MMA(ai, bj, At, Bt) do { __builtin_amdgcn_s_setprio(3); _Pragma("unroll") for (int m = 0; m < 4; ++m) _Pragma("unroll") for (int n = 0; n < 2; ++n) _Pragma("unroll") for (int k = 0; k < 2; ++k) \
;         acc[ai][bj][m][n] = __builtin_amdgcn_mfma_f32_16x16x32_bf16(Bt[n][k], At[m][k], acc[ai][bj][m][n], 0, 0, 0); __builtin_amdgcn_s_setprio(0); } while (0)
; #define PG8_WAIT_V(n) asm volatile("s_waitcnt vmcnt(" #n ")" ::: "memory")
; #define PG8_WAIT_L(n) asm volatile("s_waitcnt lgkmcnt(" #n ")" ::: "memory")
; #define PG8_BAR __builtin_amdgcn_s_barrier()
; #define PG8_SCHED __builtin_amdgcn_sched_barrier(0)
;     ...
;         const bool has_next = S.next(ui + 1, nxt);
;         const char* nA = has_next ? (const char*)g.A + (size_t)nxt.pm * tstepA : cA; const char* nB = has_next ? (const char*)g.Bt + (size_t)nxt.pn * tstepB : cB;
;         for (int t = 0; t < nt; t += 2) {
;             const bool last = (t == nt - 2);
;             const char* a1 = cA + (size_t)(t + 1) * kstep;
;             const char* a2 = last ? nA : cA + (size_t)(t + 2) * kstep; const char* b2 = last ? nB : cB + (size_t)(t + 2) * kstep;
;             const char* a3 = a2 + kstep; const char* b3 = b2 + kstep;
;             if constexpr (SP2) {
;             PG8_LDB(B0, 0, 0); PG8_LDB(B1, 0, 1); PG8_SCHED; PG8_LDA(At, 0, 0); PG8_STAGE(PG8_SA(1, 1), a1 + hstepA, voffA);
;             PG8_WAIT_V(8); PG8_WAIT_L(0); PG8_BAR; PG8_MMA(0, 0, At, B0); PG8_MMA(0, 1, At, B1); PG8_BAR; PG8_SCHED;
.LBB0_842:
	s_add_i32 vcc_hi, s80, 2
	s_add_u32 s93, s78, 0x80
	s_addc_u32 s81, s79, 0
	s_add_i32 s96, 0, 0x10000
	s_cmp_eq_u32 s34, s80
	s_cselect_b32 s81, s7, s81
	s_cselect_b32 s80, s6, s93
	v_add_u32_e32 v165, s96, v146
	s_cselect_b32 s95, s77, vcc_lo
	s_cselect_b32 s94, s76, s83
	s_add_i32 s93, 0, 0x14000
	ds_read_b128 v[142:145], v165
	ds_read_b128 v[166:169], v165 offset:1024
	ds_read_b128 v[170:173], v165 offset:2048
	ds_read_b128 v[174:177], v165 offset:3072
	v_add_u32_e32 v165, s93, v146
	ds_read_b128 v[192:195], v165
	ds_read_b128 v[196:199], v165 offset:1024
	ds_read_b128 v[200:203], v165 offset:2048
	ds_read_b128 v[204:207], v165 offset:3072
	v_lshl_add_u64 v[240:241], s[78:79], 0, v[140:141]
	s_add_i32 m0, s70, 0xc000
	ds_read_b128 v[208:211], v164
	ds_read_b128 v[212:215], v164 offset:1024
	ds_read_b128 v[216:219], v164 offset:2048
	ds_read_b128 v[220:223], v164 offset:3072
	ds_read_b128 v[224:227], v164 offset:4096
	ds_read_b128 v[228:231], v164 offset:5120
	ds_read_b128 v[232:235], v164 offset:6144
	ds_read_b128 v[236:239], v164 offset:7168
	global_load_lds_dwordx4 v[240:241], off
	v_lshl_add_u64 v[240:241], s[78:79], 0, v[138:139]
	s_add_i32 m0, s70, 0xe000
	s_nop 0
	global_load_lds_dwordx4 v[240:241], off
	s_waitcnt vmcnt(8)
	s_waitcnt lgkmcnt(0)
	s_barrier
	s_setprio 3
	s_waitcnt lgkmcnt(0)
	v_mfma_f32_16x16x32_bf16 v[126:129], v[142:145], v[208:211], v[126:129]
	v_mfma_f32_16x16x32_bf16 v[122:125], v[170:173], v[208:211], v[122:125]
	v_mfma_f32_16x16x32_bf16 v[110:113], v[142:145], v[216:219], v[110:113]
	v_mfma_f32_16x16x32_bf16 v[106:109], v[170:173], v[216:219], v[106:109]
	v_mfma_f32_16x16x32_bf16 v[94:97], v[142:145], v[224:227], v[94:97]
	v_mfma_f32_16x16x32_bf16 v[90:93], v[170:173], v[224:227], v[90:93]
	v_mfma_f32_16x16x32_bf16 v[78:81], v[142:145], v[232:235], v[78:81]
	v_mfma_f32_16x16x32_bf16 v[74:77], v[170:173], v[232:235], v[74:77]
	v_mfma_f32_16x16x32_bf16 v[126:129], v[166:169], v[212:215], v[126:129]
	v_mfma_f32_16x16x32_bf16 v[122:125], v[174:177], v[212:215], v[122:125]
	v_mfma_f32_16x16x32_bf16 v[110:113], v[166:169], v[220:223], v[110:113]
	v_mfma_f32_16x16x32_bf16 v[106:109], v[174:177], v[220:223], v[106:109]
	v_mfma_f32_16x16x32_bf16 v[94:97], v[166:169], v[228:231], v[94:97]
	v_mfma_f32_16x16x32_bf16 v[90:93], v[174:177], v[228:231], v[90:93]
	v_mfma_f32_16x16x32_bf16 v[78:81], v[166:169], v[236:239], v[78:81]
	v_mfma_f32_16x16x32_bf16 v[74:77], v[174:177], v[236:239], v[74:77]
	v_mfma_f32_16x16x32_bf16 v[118:121], v[192:195], v[208:211], v[118:121]
	v_mfma_f32_16x16x32_bf16 v[114:117], v[200:203], v[208:211], v[114:117]
	v_mfma_f32_16x16x32_bf16 v[102:105], v[192:195], v[216:219], v[102:105]
	v_mfma_f32_16x16x32_bf16 v[98:101], v[200:203], v[216:219], v[98:101]
	v_mfma_f32_16x16x32_bf16 v[86:89], v[192:195], v[224:227], v[86:89]
	v_mfma_f32_16x16x32_bf16 v[82:85], v[200:203], v[224:227], v[82:85]
	v_mfma_f32_16x16x32_bf16 v[70:73], v[192:195], v[232:235], v[70:73]
	v_mfma_f32_16x16x32_bf16 v[66:69], v[200:203], v[232:235], v[66:69]
	v_mfma_f32_16x16x32_bf16 v[118:121], v[196:199], v[212:215], v[118:121]
	v_mfma_f32_16x16x32_bf16 v[114:117], v[204:207], v[212:215], v[114:117]
	v_mfma_f32_16x16x32_bf16 v[102:105], v[196:199], v[220:223], v[102:105]
	v_mfma_f32_16x16x32_bf16 v[98:101], v[204:207], v[220:223], v[98:101]
	v_mfma_f32_16x16x32_bf16 v[86:89], v[196:199], v[228:231], v[86:89]
	v_mfma_f32_16x16x32_bf16 v[82:85], v[204:207], v[228:231], v[82:85]
	v_mfma_f32_16x16x32_bf16 v[70:73], v[196:199], v[236:239], v[70:73]
	v_mfma_f32_16x16x32_bf16 v[66:69], v[204:207], v[236:239], v[66:69]
	s_setprio 0
	s_barrier
	s_add_i32 s96, s96, s31
	v_lshl_add_u64 v[240:241], s[94:95], 0, v[132:133]
	s_mov_b32 m0, s96
	ds_read_b128 v[208:211], v164 offset:16384
	ds_read_b128 v[212:215], v164 offset:17408
	ds_read_b128 v[216:219], v164 offset:18432
	ds_read_b128 v[220:223], v164 offset:19456
	ds_read_b128 v[224:227], v164 offset:20480
	ds_read_b128 v[228:231], v164 offset:21504
	ds_read_b128 v[232:235], v164 offset:22528
	ds_read_b128 v[236:239], v164 offset:23552
	global_load_lds_dwordx4 v[240:241], off
	s_add_i32 m0, s96, 0x2000
	v_lshl_add_u64 v[242:243], s[94:95], 0, v[136:137]
	s_add_u32 s94, s94, s16
	s_addc_u32 s95, s95, 0
	s_add_i32 s93, s93, s31
	global_load_lds_dwordx4 v[242:243], off
	v_lshl_add_u64 v[244:245], s[94:95], 0, v[132:133]
	s_mov_b32 m0, s93
	v_lshl_add_u64 v[246:247], s[94:95], 0, v[136:137]
	global_load_lds_dwordx4 v[244:245], off
	s_add_i32 m0, s93, 0x2000
	v_lshl_add_u64 v[248:249], s[80:81], 0, v[130:131]
	global_load_lds_dwordx4 v[246:247], off
	s_mov_b32 m0, s70
	v_lshl_add_u64 v[250:251], s[80:81], 0, v[134:135]
	global_load_lds_dwordx4 v[248:249], off
	s_mov_b32 m0, s71
	s_nop 0
	global_load_lds_dwordx4 v[250:251], off
	s_waitcnt vmcnt(8)
	s_waitcnt lgkmcnt(0)
	s_barrier
; #define PG8_STAGE(bufoff, gbase, voff) do { _Pragma("unroll") for (int _i = 0; _i < 2; ++_i) \
;         __builtin_amdgcn_global_load_lds((const unsigned*)((const char*)(gbase) + (voff)[_i]), (LAS unsigned*)(lds + (bufoff) + ldsw + _i * 8192), 16, 0, 0); } while (0)
; #define PG8_LDA(dst, b, h) do { _Pragma("unroll") for (int m = 0; m < 4; ++m) _Pragma("unroll") for (int k = 0; k < 2; ++k) dst[m][k] = *(const LAS bf16x8*)(lds + PG8_SA(b, h) + aoff + m * 2048 + k * 1024); } while (0)
; #define PG8_LDB(dst, b, h) do { _Pragma("unroll") for (int n = 0; n < 2; ++n) _Pragma("unroll") for (int k = 0; k < 2; ++k) dst[n][k] = *(const LAS bf16x8*)(lds + PG8_SB(b, h) + boff + n * 2048 + k * 1024); } while (0)
; #define PG8_MMA(ai, bj, At, Bt) do { __builtin_amdgcn_s_setprio(3); _Pragma("unroll") for (int m = 0; m < 4; ++m) _Pragma("unroll") for (int n = 0; n < 2; ++n) _Pragma("unroll") for (int k = 0; k < 2; ++k) \
;         acc[ai][bj][m][n] = __builtin_amdgcn_mfma_f32_16x16x32_bf16(Bt[n][k], At[m][k], acc[ai][bj][m][n], 0, 0, 0); __builtin_amdgcn_s_setprio(0); } while (0)
; #define PG8_WAIT_V(n) asm volatile("s_waitcnt vmcnt(" #n ")" ::: "memory")
; #define PG8_WAIT_L(n) asm volatile("s_waitcnt lgkmcnt(" #n ")" ::: "memory")
; #define PG8_BAR __builtin_amdgcn_s_barrier()
; #define PG8_SCHED __builtin_amdgcn_sched_barrier(0)
;     ...
;             PG8_WAIT_V(8); PG8_WAIT_L(0); PG8_BAR; PG8_MMA(1, 0, At, B0); PG8_MMA(1, 1, At, B1); PG8_BAR; PG8_SCHED;
;             PG8_LDB(B0, 1, 0); PG8_LDB(B1, 1, 1); PG8_SCHED; PG8_LDA(At, 1, 0); PG8_STAGE(PG8_SA(0, 1), a2 + hstepA, voffA);
;             PG8_WAIT_V(8); PG8_WAIT_L(0); PG8_BAR; PG8_MMA(0, 0, At, B0); PG8_MMA(0, 1, At, B1); PG8_BAR; PG8_SCHED;
	s_setprio 3
	s_waitcnt lgkmcnt(0)
	v_mfma_f32_16x16x32_bf16 v[62:65], v[142:145], v[208:211], v[62:65]
	v_mfma_f32_16x16x32_bf16 v[58:61], v[170:173], v[208:211], v[58:61]
	v_mfma_f32_16x16x32_bf16 v[46:49], v[142:145], v[216:219], v[46:49]
	v_mfma_f32_16x16x32_bf16 v[42:45], v[170:173], v[216:219], v[42:45]
	v_mfma_f32_16x16x32_bf16 v[30:33], v[142:145], v[224:227], v[30:33]
	v_mfma_f32_16x16x32_bf16 v[26:29], v[170:173], v[224:227], v[26:29]
	v_mfma_f32_16x16x32_bf16 v[14:17], v[142:145], v[232:235], v[14:17]
	v_mfma_f32_16x16x32_bf16 v[10:13], v[170:173], v[232:235], v[10:13]
	v_mfma_f32_16x16x32_bf16 v[62:65], v[166:169], v[212:215], v[62:65]
	v_mfma_f32_16x16x32_bf16 v[58:61], v[174:177], v[212:215], v[58:61]
	v_mfma_f32_16x16x32_bf16 v[46:49], v[166:169], v[220:223], v[46:49]
	v_mfma_f32_16x16x32_bf16 v[42:45], v[174:177], v[220:223], v[42:45]
	v_mfma_f32_16x16x32_bf16 v[30:33], v[166:169], v[228:231], v[30:33]
	v_mfma_f32_16x16x32_bf16 v[26:29], v[174:177], v[228:231], v[26:29]
	v_mfma_f32_16x16x32_bf16 v[14:17], v[166:169], v[236:239], v[14:17]
	v_mfma_f32_16x16x32_bf16 v[10:13], v[174:177], v[236:239], v[10:13]
	v_mfma_f32_16x16x32_bf16 v[54:57], v[192:195], v[208:211], v[54:57]
	v_mfma_f32_16x16x32_bf16 v[50:53], v[200:203], v[208:211], v[50:53]
	v_mfma_f32_16x16x32_bf16 v[38:41], v[192:195], v[216:219], v[38:41]
	v_mfma_f32_16x16x32_bf16 v[34:37], v[200:203], v[216:219], v[34:37]
	v_mfma_f32_16x16x32_bf16 v[22:25], v[192:195], v[224:227], v[22:25]
	v_mfma_f32_16x16x32_bf16 v[18:21], v[200:203], v[224:227], v[18:21]
	v_mfma_f32_16x16x32_bf16 v[6:9], v[192:195], v[232:235], v[6:9]
	v_mfma_f32_16x16x32_bf16 v[2:5], v[200:203], v[232:235], v[2:5]
	v_mfma_f32_16x16x32_bf16 v[54:57], v[196:199], v[212:215], v[54:57]
	v_mfma_f32_16x16x32_bf16 v[50:53], v[204:207], v[212:215], v[50:53]
	v_mfma_f32_16x16x32_bf16 v[38:41], v[196:199], v[220:223], v[38:41]
	v_mfma_f32_16x16x32_bf16 v[34:37], v[204:207], v[220:223], v[34:37]
	v_mfma_f32_16x16x32_bf16 v[22:25], v[196:199], v[228:231], v[22:25]
	v_mfma_f32_16x16x32_bf16 v[18:21], v[204:207], v[228:231], v[18:21]
	v_mfma_f32_16x16x32_bf16 v[6:9], v[196:199], v[236:239], v[6:9]
	v_mfma_f32_16x16x32_bf16 v[2:5], v[204:207], v[236:239], v[2:5]
	s_setprio 0
	s_barrier
	s_add_i32 s93, 0, 0x18000
	v_add_u32_e32 v165, s93, v146
	s_add_i32 s94, 0, 0x1c000
	ds_read_b128 v[142:145], v165
	ds_read_b128 v[166:169], v165 offset:1024
	ds_read_b128 v[170:173], v165 offset:2048
	ds_read_b128 v[174:177], v165 offset:3072
	v_add_u32_e32 v165, s94, v146
	ds_read_b128 v[192:195], v165
	ds_read_b128 v[196:199], v165 offset:1024
	ds_read_b128 v[200:203], v165 offset:2048
	ds_read_b128 v[204:207], v165 offset:3072
	s_add_u32 s80, s80, s16
	s_addc_u32 s81, s81, 0
	s_mov_b32 m0, s84
	v_lshl_add_u64 v[252:253], s[80:81], 0, v[130:131]
	ds_read_b128 v[208:211], v164 offset:32768
	ds_read_b128 v[212:215], v164 offset:33792
	ds_read_b128 v[216:219], v164 offset:34816
	ds_read_b128 v[220:223], v164 offset:35840
	ds_read_b128 v[224:227], v164 offset:36864
	ds_read_b128 v[228:231], v164 offset:37888
	ds_read_b128 v[232:235], v164 offset:38912
	ds_read_b128 v[236:239], v164 offset:39936
	global_load_lds_dwordx4 v[252:253], off
	v_lshl_add_u64 v[252:253], s[80:81], 0, v[134:135]
	s_mov_b32 m0, s85
	s_nop 0
	global_load_lds_dwordx4 v[252:253], off
	s_waitcnt vmcnt(8)
	s_waitcnt lgkmcnt(0)
	s_barrier
	s_setprio 3
	s_waitcnt lgkmcnt(0)
	v_mfma_f32_16x16x32_bf16 v[126:129], v[142:145], v[208:211], v[126:129]
	v_mfma_f32_16x16x32_bf16 v[122:125], v[170:173], v[208:211], v[122:125]
	v_mfma_f32_16x16x32_bf16 v[110:113], v[142:145], v[216:219], v[110:113]
	v_mfma_f32_16x16x32_bf16 v[106:109], v[170:173], v[216:219], v[106:109]
	v_mfma_f32_16x16x32_bf16 v[94:97], v[142:145], v[224:227], v[94:97]
	v_mfma_f32_16x16x32_bf16 v[90:93], v[170:173], v[224:227], v[90:93]
	v_mfma_f32_16x16x32_bf16 v[78:81], v[142:145], v[232:235], v[78:81]
	v_mfma_f32_16x16x32_bf16 v[74:77], v[170:173], v[232:235], v[74:77]
	v_mfma_f32_16x16x32_bf16 v[126:129], v[166:169], v[212:215], v[126:129]
	v_mfma_f32_16x16x32_bf16 v[122:125], v[174:177], v[212:215], v[122:125]
	v_mfma_f32_16x16x32_bf16 v[110:113], v[166:169], v[220:223], v[110:113]
	v_mfma_f32_16x16x32_bf16 v[106:109], v[174:177], v[220:223], v[106:109]
	v_mfma_f32_16x16x32_bf16 v[94:97], v[166:169], v[228:231], v[94:97]
	v_mfma_f32_16x16x32_bf16 v[90:93], v[174:177], v[228:231], v[90:93]
	v_mfma_f32_16x16x32_bf16 v[78:81], v[166:169], v[236:239], v[78:81]
	v_mfma_f32_16x16x32_bf16 v[74:77], v[174:177], v[236:239], v[74:77]
	v_mfma_f32_16x16x32_bf16 v[118:121], v[192:195], v[208:211], v[118:121]
	v_mfma_f32_16x16x32_bf16 v[114:117], v[200:203], v[208:211], v[114:117]
	v_mfma_f32_16x16x32_bf16 v[102:105], v[192:195], v[216:219], v[102:105]
	v_mfma_f32_16x16x32_bf16 v[98:101], v[200:203], v[216:219], v[98:101]
	v_mfma_f32_16x16x32_bf16 v[86:89], v[192:195], v[224:227], v[86:89]
	v_mfma_f32_16x16x32_bf16 v[82:85], v[200:203], v[224:227], v[82:85]
	v_mfma_f32_16x16x32_bf16 v[70:73], v[192:195], v[232:235], v[70:73]
	v_mfma_f32_16x16x32_bf16 v[66:69], v[200:203], v[232:235], v[66:69]
	v_mfma_f32_16x16x32_bf16 v[118:121], v[196:199], v[212:215], v[118:121]
	v_mfma_f32_16x16x32_bf16 v[114:117], v[204:207], v[212:215], v[114:117]
	v_mfma_f32_16x16x32_bf16 v[102:105], v[196:199], v[220:223], v[102:105]
	v_mfma_f32_16x16x32_bf16 v[98:101], v[204:207], v[220:223], v[98:101]
	v_mfma_f32_16x16x32_bf16 v[86:89], v[196:199], v[228:231], v[86:89]
	v_mfma_f32_16x16x32_bf16 v[82:85], v[204:207], v[228:231], v[82:85]
	v_mfma_f32_16x16x32_bf16 v[70:73], v[196:199], v[236:239], v[70:73]
	v_mfma_f32_16x16x32_bf16 v[66:69], v[204:207], v[236:239], v[66:69]
	s_setprio 0
	s_barrier
; #define PG8_STAGE(bufoff, gbase, voff) do { _Pragma("unroll") for (int _i = 0; _i < 2; ++_i) \
;         __builtin_amdgcn_global_load_lds((const unsigned*)((const char*)(gbase) + (voff)[_i]), (LAS unsigned*)(lds + (bufoff) + ldsw + _i * 8192), 16, 0, 0); } while (0)
; #define PG8_LDA(dst, b, h) do { _Pragma("unroll") for (int m = 0; m < 4; ++m) _Pragma("unroll") for (int k = 0; k < 2; ++k) dst[m][k] = *(const LAS bf16x8*)(lds + PG8_SA(b, h) + aoff + m * 2048 + k * 1024); } while (0)
; #define PG8_MMA(ai, bj, At, Bt) do { __builtin_amdgcn_s_setprio(3); _Pragma("unroll") for (int m = 0; m < 4; ++m) _Pragma("unroll") for (int n = 0; n < 2; ++n) _Pragma("unroll") for (int k = 0; k < 2; ++k) \
;         acc[ai][bj][m][n] = __builtin_amdgcn_mfma_f32_16x16x32_bf16(Bt[n][k], At[m][k], acc[ai][bj][m][n], 0, 0, 0); __builtin_amdgcn_s_setprio(0); } while (0)
; #define PG8_WAIT_V(n) asm volatile("s_waitcnt vmcnt(" #n ")" ::: "memory")
; #define PG8_WAIT_L(n) asm volatile("s_waitcnt lgkmcnt(" #n ")" ::: "memory")
; #define PG8_BAR __builtin_amdgcn_s_barrier()
; #define PG8_SCHED __builtin_amdgcn_sched_barrier(0)
;     ...
;             PG8_LDA(At, 1, 1); PG8_STAGE(PG8_SB(1, 0), b3, voffB); PG8_STAGE(PG8_SB(1, 1), b3 + hstepB, voffB); PG8_STAGE(PG8_SA(1, 0), a3, voffA);
;             PG8_WAIT_V(8); PG8_WAIT_L(0); PG8_BAR; PG8_MMA(1, 0, At, B0); PG8_MMA(1, 1, At, B1); PG8_BAR; PG8_SCHED;
;     __device__ __forceinline__ void operator()(const f32x4 (&acc)[2][2][4][2], const Unit& u, int wr, int wc, int fr, int fq) const {
;         const int row0 = u.pm * BM + wr * 64 + fr, col0 = u.pn * BM + wc * 32 + 8 * fq;
;         const float* xin = (u.pm * BM < T_P) ? this->xin : xin_hi;
; #pragma unroll
;         for (int ai = 0; ai < 2; ++ai)
; #pragma unroll
;             for (int m = 0; m < 4; ++m) {
;                 const int row = row0 + ai * HALF + m * 16; const size_t off = (size_t)row * D + col0; float ss = 0.f;
; #pragma unroll
;                 for (int bj = 0; bj < 2; ++bj) {
;                     const f32x4 xo0 = *(const f32x4*)(xin + off + bj * HALF), xo1 = *(const f32x4*)(xin + off + bj * HALF + 4);
	s_add_i32 s80, s93, s31
	v_lshl_add_u64 v[240:241], v[240:241], 0, s[46:47]
	s_mov_b32 m0, s80
	ds_read_b128 v[208:211], v164 offset:49152
	ds_read_b128 v[212:215], v164 offset:50176
	ds_read_b128 v[216:219], v164 offset:51200
	ds_read_b128 v[220:223], v164 offset:52224
	ds_read_b128 v[224:227], v164 offset:53248
	ds_read_b128 v[228:231], v164 offset:54272
	ds_read_b128 v[232:235], v164 offset:55296
	ds_read_b128 v[236:239], v164 offset:56320
	global_load_lds_dwordx4 v[240:241], off
	v_lshl_add_u64 v[240:241], v[242:243], 0, s[46:47]
	s_add_i32 m0, s80, 0x2000
	s_add_i32 s80, s94, s31
	global_load_lds_dwordx4 v[240:241], off
	v_lshl_add_u64 v[240:241], v[244:245], 0, s[46:47]
	s_mov_b32 m0, s80
	s_nop 0
	global_load_lds_dwordx4 v[240:241], off
	v_lshl_add_u64 v[240:241], v[246:247], 0, s[46:47]
	s_add_i32 m0, s80, 0x2000
	s_nop 0
	global_load_lds_dwordx4 v[240:241], off
	v_lshl_add_u64 v[240:241], v[248:249], 0, s[46:47]
	s_mov_b32 m0, s86
	s_nop 0
	global_load_lds_dwordx4 v[240:241], off
	v_lshl_add_u64 v[240:241], v[250:251], 0, s[46:47]
	s_mov_b32 m0, s19
	s_nop 0
	global_load_lds_dwordx4 v[240:241], off
	s_waitcnt vmcnt(8)
	s_waitcnt lgkmcnt(0)
	s_barrier
	s_setprio 3
	s_waitcnt lgkmcnt(0)
	v_mfma_f32_16x16x32_bf16 v[62:65], v[142:145], v[208:211], v[62:65]
	v_mfma_f32_16x16x32_bf16 v[58:61], v[170:173], v[208:211], v[58:61]
	v_mfma_f32_16x16x32_bf16 v[46:49], v[142:145], v[216:219], v[46:49]
	v_mfma_f32_16x16x32_bf16 v[42:45], v[170:173], v[216:219], v[42:45]
	v_mfma_f32_16x16x32_bf16 v[30:33], v[142:145], v[224:227], v[30:33]
	v_mfma_f32_16x16x32_bf16 v[26:29], v[170:173], v[224:227], v[26:29]
	v_mfma_f32_16x16x32_bf16 v[14:17], v[142:145], v[232:235], v[14:17]
	v_mfma_f32_16x16x32_bf16 v[10:13], v[170:173], v[232:235], v[10:13]
	v_mfma_f32_16x16x32_bf16 v[62:65], v[166:169], v[212:215], v[62:65]
	v_mfma_f32_16x16x32_bf16 v[58:61], v[174:177], v[212:215], v[58:61]
	v_mfma_f32_16x16x32_bf16 v[46:49], v[166:169], v[220:223], v[46:49]
	v_mfma_f32_16x16x32_bf16 v[42:45], v[174:177], v[220:223], v[42:45]
	v_mfma_f32_16x16x32_bf16 v[30:33], v[166:169], v[228:231], v[30:33]
	v_mfma_f32_16x16x32_bf16 v[26:29], v[174:177], v[228:231], v[26:29]
	v_mfma_f32_16x16x32_bf16 v[14:17], v[166:169], v[236:239], v[14:17]
	v_mfma_f32_16x16x32_bf16 v[10:13], v[174:177], v[236:239], v[10:13]
	v_mfma_f32_16x16x32_bf16 v[54:57], v[192:195], v[208:211], v[54:57]
	v_mfma_f32_16x16x32_bf16 v[50:53], v[200:203], v[208:211], v[50:53]
	v_mfma_f32_16x16x32_bf16 v[38:41], v[192:195], v[216:219], v[38:41]
	v_mfma_f32_16x16x32_bf16 v[34:37], v[200:203], v[216:219], v[34:37]
	v_mfma_f32_16x16x32_bf16 v[22:25], v[192:195], v[224:227], v[22:25]
	v_mfma_f32_16x16x32_bf16 v[18:21], v[200:203], v[224:227], v[18:21]
	v_mfma_f32_16x16x32_bf16 v[6:9], v[192:195], v[232:235], v[6:9]
	v_mfma_f32_16x16x32_bf16 v[2:5], v[200:203], v[232:235], v[2:5]
	v_mfma_f32_16x16x32_bf16 v[54:57], v[196:199], v[212:215], v[54:57]
	v_mfma_f32_16x16x32_bf16 v[50:53], v[204:207], v[212:215], v[50:53]
	v_mfma_f32_16x16x32_bf16 v[38:41], v[196:199], v[220:223], v[38:41]
	v_mfma_f32_16x16x32_bf16 v[34:37], v[204:207], v[220:223], v[34:37]
	v_mfma_f32_16x16x32_bf16 v[22:25], v[196:199], v[228:231], v[22:25]
	v_mfma_f32_16x16x32_bf16 v[18:21], v[204:207], v[228:231], v[18:21]
	v_mfma_f32_16x16x32_bf16 v[6:9], v[196:199], v[236:239], v[6:9]
	v_mfma_f32_16x16x32_bf16 v[2:5], v[204:207], v[236:239], v[2:5]
	s_setprio 0
	s_barrier
	s_add_u32 s83, s83, 0x100
	s_addc_u32 vcc_lo, vcc_lo, 0
	s_add_u32 s78, s78, 0x100
	s_addc_u32 s79, s79, 0
	s_cmp_ge_u32 vcc_hi, s42
	s_mov_b32 s80, vcc_hi
	s_cbranch_scc0 .LBB0_842
	s_cmp_lt_i32 s82, 64
	s_cselect_b32 s81, s65, s67
	s_cselect_b32 s80, s64, s66
	v_lshl_add_u32 v142, s82, 8, v1
	v_lshl_or_b32 v143, s40, 8, v147
	v_lshl_add_u32 v143, v142, 10, v143
	v_lshlrev_b32_e32 v143, 2, v143
	s_lshl_b32 s78, s40, 4
	s_lshl_b32 s79, s87, 2
	s_add_i32 s78, s78, s79
	v_lshlrev_b32_e32 v142, 6, v142
	v_add_u32_e32 v142, s78, v142
	global_load_dwordx4 v[192:195], v143, s[80:81]
	global_load_dwordx4 v[196:199], v143, s[80:81] offset:16
	global_load_dwordx4 v[200:203], v143, s[80:81] offset:512
	global_load_dwordx4 v[204:207], v143, s[80:81] offset:528
	v_add_u32_e32 v144, 0x10000, v143
	global_load_dwordx4 v[208:211], v144, s[80:81]
	global_load_dwordx4 v[212:215], v144, s[80:81] offset:16
	global_load_dwordx4 v[216:219], v144, s[80:81] offset:512
	global_load_dwordx4 v[220:223], v144, s[80:81] offset:528
	v_add_u32_e32 v144, 0x20000, v143
	global_load_dwordx4 v[224:227], v144, s[80:81]
	global_load_dwordx4 v[228:231], v144, s[80:81] offset:16
	global_load_dwordx4 v[232:235], v144, s[80:81] offset:512
	global_load_dwordx4 v[236:239], v144, s[80:81] offset:528
	v_add_u32_e32 v144, 0x30000, v143
	global_load_dwordx4 v[240:243], v144, s[80:81]
	global_load_dwordx4 v[244:247], v144, s[80:81] offset:16
	global_load_dwordx4 v[248:251], v144, s[80:81] offset:512
	global_load_dwordx4 v[172:175], v144, s[80:81] offset:528
	v_xor_b32_e32 v170, 16, v182
	v_xor_b32_e32 v171, 32, v182
	v_lshlrev_b32_e32 v170, 2, v170
	v_lshlrev_b32_e32 v171, 2, v171
	s_and_b64 vcc, exec, s[72:73]
	s_cbranch_vccz .LBB0_845
	s_barrier

; #define PG8_STAGE(bufoff, gbase, voff) do { _Pragma("unroll") for (int _i = 0; _i < 2; ++_i) \
;         __builtin_amdgcn_global_load_lds((const unsigned*)((const char*)(gbase) + (voff)[_i]), (LAS unsigned*)(lds + (bufoff) + ldsw + _i * 8192), 16, 0, 0); } while (0)
; #define PG8_LDA(dst, b, h) do { _Pragma("unroll") for (int m = 0; m < 4; ++m) _Pragma("unroll") for (int k = 0; k < 2; ++k) dst[m][k] = *(const LAS bf16x8*)(lds + PG8_SA(b, h) + aoff + m * 2048 + k * 1024); } while (0)
; #define PG8_LDB(dst, b, h) do { _Pragma("unroll") for (int n = 0; n < 2; ++n) _Pragma("unroll") for (int k = 0; k < 2; ++k) dst[n][k] = *(const LAS bf16x8*)(lds + PG8_SB(b, h) + boff + n * 2048 + k * 1024); } while (0)
; #define PG8_MMA(ai, bj, At, Bt) do { __builtin_amdgcn_s_setprio(3); _Pragma("unroll") for (int m = 0; m < 4; ++m) _Pragma("unroll") for (int n = 0; n < 2; ++n) _Pragma("unroll") for (int k = 0; k < 2; ++k) \
;         acc[ai][bj][m][n] = __builtin_amdgcn_mfma_f32_16x16x32_bf16(Bt[n][k], At[m][k], acc[ai][bj][m][n], 0, 0, 0); __builtin_amdgcn_s_setprio(0); } while (0)
; #define PG8_WAIT_V(n) asm volatile("s_waitcnt vmcnt(" #n ")" ::: "memory")
; #define PG8_WAIT_L(n) asm volatile("s_waitcnt lgkmcnt(" #n ")" ::: "memory")
; #define PG8_BAR __builtin_amdgcn_s_barrier()
; #define PG8_SCHED __builtin_amdgcn_sched_barrier(0)
;     ...
;             PG8_LDB(B0, 0, 0); PG8_LDB(B1, 0, 1); PG8_SCHED; PG8_LDA(At, 0, 0); PG8_STAGE(PG8_SA(1, 1), a1 + hstepA, voffA);
;             PG8_WAIT_V(8); PG8_WAIT_L(0); PG8_BAR; PG8_MMA(0, 0, At, B0); PG8_MMA(0, 1, At, B1); PG8_BAR; PG8_SCHED;
;             PG8_LDA(At, 0, 1); PG8_STAGE(PG8_SB(0, 0), b2, voffB); PG8_STAGE(PG8_SB(0, 1), b2 + hstepB, voffB); PG8_STAGE(PG8_SA(0, 0), a2, voffA);
;             PG8_WAIT_V(8); PG8_WAIT_L(0); PG8_BAR; PG8_MMA(1, 0, At, B0); PG8_MMA(1, 1, At, B1); PG8_BAR; PG8_SCHED;
.LBB0_877:
	s_add_u32 s30, s26, 0xfffc0080
	s_addc_u32 s31, s27, -1
	s_add_i32 s77, 0, 0x10000
	s_cmp_eq_u32 s76, 12
	s_cselect_b32 s35, s11, s31
	s_cselect_b32 s34, s72, s30
	v_add_u32_e32 v144, s77, v146
	s_cselect_b32 s31, s9, s75
	s_cselect_b32 s30, s73, s74
	s_add_i32 s80, 0, 0x14000
	ds_read_b128 v[166:169], v144
	ds_read_b128 v[170:173], v144 offset:1024
	ds_read_b128 v[174:177], v144 offset:2048
	ds_read_b128 v[192:195], v144 offset:3072
	v_add_u32_e32 v144, s80, v146
	ds_read_b128 v[196:199], v144
	ds_read_b128 v[200:203], v144 offset:1024
	ds_read_b128 v[204:207], v144 offset:2048
	ds_read_b128 v[208:211], v144 offset:3072
	v_lshl_add_u64 v[144:145], s[26:27], 0, v[142:143]
	s_add_i32 m0, s19, 0xc000
	ds_read_b128 v[212:215], v164
	ds_read_b128 v[216:219], v164 offset:1024
	ds_read_b128 v[220:223], v164 offset:2048
	ds_read_b128 v[224:227], v164 offset:3072
	ds_read_b128 v[228:231], v164 offset:4096
	ds_read_b128 v[232:235], v164 offset:5120
	ds_read_b128 v[236:239], v164 offset:6144
	ds_read_b128 v[240:243], v164 offset:7168
	global_load_lds_dwordx4 v[144:145], off
	v_lshl_add_u64 v[144:145], s[26:27], 0, v[140:141]
	s_add_i32 m0, s19, 0xe000
	s_nop 0
	global_load_lds_dwordx4 v[144:145], off
	s_waitcnt vmcnt(8)
	s_waitcnt lgkmcnt(0)
	s_barrier
	s_setprio 3
	s_waitcnt lgkmcnt(0)
	v_mfma_f32_16x16x32_bf16 v[118:121], v[166:169], v[212:215], v[118:121]
	v_mfma_f32_16x16x32_bf16 v[114:117], v[174:177], v[212:215], v[114:117]
	v_mfma_f32_16x16x32_bf16 v[106:109], v[166:169], v[220:223], v[106:109]
	v_mfma_f32_16x16x32_bf16 v[98:101], v[174:177], v[220:223], v[98:101]
	v_mfma_f32_16x16x32_bf16 v[90:93], v[166:169], v[228:231], v[90:93]
	v_mfma_f32_16x16x32_bf16 v[82:85], v[174:177], v[228:231], v[82:85]
	v_mfma_f32_16x16x32_bf16 v[74:77], v[166:169], v[236:239], v[74:77]
	v_mfma_f32_16x16x32_bf16 v[66:69], v[174:177], v[236:239], v[66:69]
	v_mfma_f32_16x16x32_bf16 v[118:121], v[170:173], v[216:219], v[118:121]
	v_mfma_f32_16x16x32_bf16 v[114:117], v[192:195], v[216:219], v[114:117]
	v_mfma_f32_16x16x32_bf16 v[106:109], v[170:173], v[224:227], v[106:109]
	v_mfma_f32_16x16x32_bf16 v[98:101], v[192:195], v[224:227], v[98:101]
	v_mfma_f32_16x16x32_bf16 v[90:93], v[170:173], v[232:235], v[90:93]
	v_mfma_f32_16x16x32_bf16 v[82:85], v[192:195], v[232:235], v[82:85]
	v_mfma_f32_16x16x32_bf16 v[74:77], v[170:173], v[240:243], v[74:77]
	v_mfma_f32_16x16x32_bf16 v[66:69], v[192:195], v[240:243], v[66:69]
	v_mfma_f32_16x16x32_bf16 v[126:129], v[196:199], v[212:215], v[126:129]
	v_mfma_f32_16x16x32_bf16 v[122:125], v[204:207], v[212:215], v[122:125]
	v_mfma_f32_16x16x32_bf16 v[110:113], v[196:199], v[220:223], v[110:113]
	v_mfma_f32_16x16x32_bf16 v[102:105], v[204:207], v[220:223], v[102:105]
	v_mfma_f32_16x16x32_bf16 v[94:97], v[196:199], v[228:231], v[94:97]
	v_mfma_f32_16x16x32_bf16 v[86:89], v[204:207], v[228:231], v[86:89]
	v_mfma_f32_16x16x32_bf16 v[78:81], v[196:199], v[236:239], v[78:81]
	v_mfma_f32_16x16x32_bf16 v[70:73], v[204:207], v[236:239], v[70:73]
	v_mfma_f32_16x16x32_bf16 v[126:129], v[200:203], v[216:219], v[126:129]
	v_mfma_f32_16x16x32_bf16 v[122:125], v[208:211], v[216:219], v[122:125]
	v_mfma_f32_16x16x32_bf16 v[110:113], v[200:203], v[224:227], v[110:113]
	v_mfma_f32_16x16x32_bf16 v[102:105], v[208:211], v[224:227], v[102:105]
	v_mfma_f32_16x16x32_bf16 v[94:97], v[200:203], v[232:235], v[94:97]
	v_mfma_f32_16x16x32_bf16 v[86:89], v[208:211], v[232:235], v[86:89]
	v_mfma_f32_16x16x32_bf16 v[78:81], v[200:203], v[240:243], v[78:81]
	v_mfma_f32_16x16x32_bf16 v[70:73], v[208:211], v[240:243], v[70:73]
	s_setprio 0
	s_barrier
	s_add_i32 s77, s77, s65
	v_lshl_add_u64 v[144:145], s[30:31], 0, v[134:135]
	s_mov_b32 m0, s77
	ds_read_b128 v[212:215], v164 offset:16384
	ds_read_b128 v[216:219], v164 offset:17408
	ds_read_b128 v[220:223], v164 offset:18432
	ds_read_b128 v[224:227], v164 offset:19456
	ds_read_b128 v[228:231], v164 offset:20480
	ds_read_b128 v[232:235], v164 offset:21504
	ds_read_b128 v[236:239], v164 offset:22528
	ds_read_b128 v[240:243], v164 offset:23552
	global_load_lds_dwordx4 v[144:145], off
	s_add_i32 m0, s77, 0x2000
	s_add_u32 s78, s30, 0x40000
	v_lshl_add_u64 v[244:245], s[30:31], 0, v[130:131]
	s_addc_u32 s79, s31, 0
	s_add_i32 s77, s80, s65
	global_load_lds_dwordx4 v[244:245], off
	v_lshl_add_u64 v[246:247], s[78:79], 0, v[134:135]
	s_mov_b32 m0, s77
	v_lshl_add_u64 v[248:249], s[34:35], 0, v[132:133]
	global_load_lds_dwordx4 v[246:247], off
	v_lshl_add_u64 v[246:247], s[78:79], 0, v[130:131]
	s_add_i32 m0, s77, 0x2000
	s_nop 0
	global_load_lds_dwordx4 v[246:247], off
	v_lshl_add_u64 v[246:247], s[34:35], 0, v[136:137]
	s_mov_b32 m0, s19
	s_nop 0
	global_load_lds_dwordx4 v[246:247], off
	s_mov_b32 m0, s29
	s_nop 0
	global_load_lds_dwordx4 v[248:249], off
	s_waitcnt vmcnt(8)
	s_waitcnt lgkmcnt(0)
	s_barrier
; #define PG8_STAGE(bufoff, gbase, voff) do { _Pragma("unroll") for (int _i = 0; _i < 2; ++_i) \
;         __builtin_amdgcn_global_load_lds((const unsigned*)((const char*)(gbase) + (voff)[_i]), (LAS unsigned*)(lds + (bufoff) + ldsw + _i * 8192), 16, 0, 0); } while (0)
; #define PG8_LDA(dst, b, h) do { _Pragma("unroll") for (int m = 0; m < 4; ++m) _Pragma("unroll") for (int k = 0; k < 2; ++k) dst[m][k] = *(const LAS bf16x8*)(lds + PG8_SA(b, h) + aoff + m * 2048 + k * 1024); } while (0)
; #define PG8_LDB(dst, b, h) do { _Pragma("unroll") for (int n = 0; n < 2; ++n) _Pragma("unroll") for (int k = 0; k < 2; ++k) dst[n][k] = *(const LAS bf16x8*)(lds + PG8_SB(b, h) + boff + n * 2048 + k * 1024); } while (0)
; #define PG8_MMA(ai, bj, At, Bt) do { __builtin_amdgcn_s_setprio(3); _Pragma("unroll") for (int m = 0; m < 4; ++m) _Pragma("unroll") for (int n = 0; n < 2; ++n) _Pragma("unroll") for (int k = 0; k < 2; ++k) \
;         acc[ai][bj][m][n] = __builtin_amdgcn_mfma_f32_16x16x32_bf16(Bt[n][k], At[m][k], acc[ai][bj][m][n], 0, 0, 0); __builtin_amdgcn_s_setprio(0); } while (0)
; #define PG8_WAIT_V(n) asm volatile("s_waitcnt vmcnt(" #n ")" ::: "memory")
; #define PG8_WAIT_L(n) asm volatile("s_waitcnt lgkmcnt(" #n ")" ::: "memory")
; #define PG8_BAR __builtin_amdgcn_s_barrier()
; #define PG8_SCHED __builtin_amdgcn_sched_barrier(0)
;     ...
;             PG8_WAIT_V(8); PG8_WAIT_L(0); PG8_BAR; PG8_MMA(1, 0, At, B0); PG8_MMA(1, 1, At, B1); PG8_BAR; PG8_SCHED;
;             PG8_LDB(B0, 1, 0); PG8_LDB(B1, 1, 1); PG8_SCHED; PG8_LDA(At, 1, 0); PG8_STAGE(PG8_SA(0, 1), a2 + hstepA, voffA);
;             PG8_WAIT_V(8); PG8_WAIT_L(0); PG8_BAR; PG8_MMA(0, 0, At, B0); PG8_MMA(0, 1, At, B1); PG8_BAR; PG8_SCHED;
	s_setprio 3
	s_waitcnt lgkmcnt(0)
	v_mfma_f32_16x16x32_bf16 v[58:61], v[166:169], v[212:215], v[58:61]
	v_mfma_f32_16x16x32_bf16 v[50:53], v[174:177], v[212:215], v[50:53]
	v_mfma_f32_16x16x32_bf16 v[42:45], v[166:169], v[220:223], v[42:45]
	v_mfma_f32_16x16x32_bf16 v[34:37], v[174:177], v[220:223], v[34:37]
	v_mfma_f32_16x16x32_bf16 v[26:29], v[166:169], v[228:231], v[26:29]
	v_mfma_f32_16x16x32_bf16 v[18:21], v[174:177], v[228:231], v[18:21]
	v_mfma_f32_16x16x32_bf16 v[10:13], v[166:169], v[236:239], v[10:13]
	v_mfma_f32_16x16x32_bf16 v[6:9], v[174:177], v[236:239], v[6:9]
	v_mfma_f32_16x16x32_bf16 v[58:61], v[170:173], v[216:219], v[58:61]
	v_mfma_f32_16x16x32_bf16 v[50:53], v[192:195], v[216:219], v[50:53]
	v_mfma_f32_16x16x32_bf16 v[42:45], v[170:173], v[224:227], v[42:45]
	v_mfma_f32_16x16x32_bf16 v[34:37], v[192:195], v[224:227], v[34:37]
	v_mfma_f32_16x16x32_bf16 v[26:29], v[170:173], v[232:235], v[26:29]
	v_mfma_f32_16x16x32_bf16 v[18:21], v[192:195], v[232:235], v[18:21]
	v_mfma_f32_16x16x32_bf16 v[10:13], v[170:173], v[240:243], v[10:13]
	v_mfma_f32_16x16x32_bf16 v[6:9], v[192:195], v[240:243], v[6:9]
	v_mfma_f32_16x16x32_bf16 v[62:65], v[196:199], v[212:215], v[62:65]
	v_mfma_f32_16x16x32_bf16 v[54:57], v[204:207], v[212:215], v[54:57]
	v_mfma_f32_16x16x32_bf16 v[46:49], v[196:199], v[220:223], v[46:49]
	v_mfma_f32_16x16x32_bf16 v[38:41], v[204:207], v[220:223], v[38:41]
	v_mfma_f32_16x16x32_bf16 v[30:33], v[196:199], v[228:231], v[30:33]
	v_mfma_f32_16x16x32_bf16 v[22:25], v[204:207], v[228:231], v[22:25]
	v_mfma_f32_16x16x32_bf16 v[14:17], v[196:199], v[236:239], v[14:17]
	v_mfma_f32_16x16x32_bf16 v[2:5], v[204:207], v[236:239], v[2:5]
	v_mfma_f32_16x16x32_bf16 v[62:65], v[200:203], v[216:219], v[62:65]
	v_mfma_f32_16x16x32_bf16 v[54:57], v[208:211], v[216:219], v[54:57]
	v_mfma_f32_16x16x32_bf16 v[46:49], v[200:203], v[224:227], v[46:49]
	v_mfma_f32_16x16x32_bf16 v[38:41], v[208:211], v[224:227], v[38:41]
	v_mfma_f32_16x16x32_bf16 v[30:33], v[200:203], v[232:235], v[30:33]
	v_mfma_f32_16x16x32_bf16 v[22:25], v[208:211], v[232:235], v[22:25]
	v_mfma_f32_16x16x32_bf16 v[14:17], v[200:203], v[240:243], v[14:17]
	v_mfma_f32_16x16x32_bf16 v[2:5], v[208:211], v[240:243], v[2:5]
	s_setprio 0
	s_barrier
	s_add_i32 s77, 0, 0x18000
	v_add_u32_e32 v165, s77, v146
	s_add_i32 s78, 0, 0x1c000
	ds_read_b128 v[166:169], v165
	ds_read_b128 v[170:173], v165 offset:1024
	ds_read_b128 v[174:177], v165 offset:2048
	ds_read_b128 v[192:195], v165 offset:3072
	v_add_u32_e32 v165, s78, v146
	ds_read_b128 v[196:199], v165
	ds_read_b128 v[200:203], v165 offset:1024
	ds_read_b128 v[204:207], v165 offset:2048
	ds_read_b128 v[208:211], v165 offset:3072
	s_add_u32 s34, s34, 0x40000
	s_addc_u32 s35, s35, 0
	s_mov_b32 m0, s42
	v_lshl_add_u64 v[250:251], s[34:35], 0, v[136:137]
	ds_read_b128 v[212:215], v164 offset:32768
	ds_read_b128 v[216:219], v164 offset:33792
	ds_read_b128 v[220:223], v164 offset:34816
	ds_read_b128 v[224:227], v164 offset:35840
	ds_read_b128 v[228:231], v164 offset:36864
	ds_read_b128 v[232:235], v164 offset:37888
	ds_read_b128 v[236:239], v164 offset:38912
	ds_read_b128 v[240:243], v164 offset:39936
	global_load_lds_dwordx4 v[250:251], off
	v_lshl_add_u64 v[250:251], s[34:35], 0, v[132:133]
	s_mov_b32 m0, s60
	s_nop 0
	global_load_lds_dwordx4 v[250:251], off
	s_waitcnt vmcnt(8)
	s_waitcnt lgkmcnt(0)
	s_barrier
	s_setprio 3
	s_waitcnt lgkmcnt(0)
	v_mfma_f32_16x16x32_bf16 v[118:121], v[166:169], v[212:215], v[118:121]
	v_mfma_f32_16x16x32_bf16 v[114:117], v[174:177], v[212:215], v[114:117]
	v_mfma_f32_16x16x32_bf16 v[106:109], v[166:169], v[220:223], v[106:109]
	v_mfma_f32_16x16x32_bf16 v[98:101], v[174:177], v[220:223], v[98:101]
	v_mfma_f32_16x16x32_bf16 v[90:93], v[166:169], v[228:231], v[90:93]
	v_mfma_f32_16x16x32_bf16 v[82:85], v[174:177], v[228:231], v[82:85]
	v_mfma_f32_16x16x32_bf16 v[74:77], v[166:169], v[236:239], v[74:77]
	v_mfma_f32_16x16x32_bf16 v[66:69], v[174:177], v[236:239], v[66:69]
	v_mfma_f32_16x16x32_bf16 v[118:121], v[170:173], v[216:219], v[118:121]
	v_mfma_f32_16x16x32_bf16 v[114:117], v[192:195], v[216:219], v[114:117]
	v_mfma_f32_16x16x32_bf16 v[106:109], v[170:173], v[224:227], v[106:109]
	v_mfma_f32_16x16x32_bf16 v[98:101], v[192:195], v[224:227], v[98:101]
	v_mfma_f32_16x16x32_bf16 v[90:93], v[170:173], v[232:235], v[90:93]
	v_mfma_f32_16x16x32_bf16 v[82:85], v[192:195], v[232:235], v[82:85]
	v_mfma_f32_16x16x32_bf16 v[74:77], v[170:173], v[240:243], v[74:77]
	v_mfma_f32_16x16x32_bf16 v[66:69], v[192:195], v[240:243], v[66:69]
	v_mfma_f32_16x16x32_bf16 v[126:129], v[196:199], v[212:215], v[126:129]
	v_mfma_f32_16x16x32_bf16 v[122:125], v[204:207], v[212:215], v[122:125]
	v_mfma_f32_16x16x32_bf16 v[110:113], v[196:199], v[220:223], v[110:113]
	v_mfma_f32_16x16x32_bf16 v[102:105], v[204:207], v[220:223], v[102:105]
	v_mfma_f32_16x16x32_bf16 v[94:97], v[196:199], v[228:231], v[94:97]
	v_mfma_f32_16x16x32_bf16 v[86:89], v[204:207], v[228:231], v[86:89]
	v_mfma_f32_16x16x32_bf16 v[78:81], v[196:199], v[236:239], v[78:81]
	v_mfma_f32_16x16x32_bf16 v[70:73], v[204:207], v[236:239], v[70:73]
	v_mfma_f32_16x16x32_bf16 v[126:129], v[200:203], v[216:219], v[126:129]
	v_mfma_f32_16x16x32_bf16 v[122:125], v[208:211], v[216:219], v[122:125]
	v_mfma_f32_16x16x32_bf16 v[110:113], v[200:203], v[224:227], v[110:113]
	v_mfma_f32_16x16x32_bf16 v[102:105], v[208:211], v[224:227], v[102:105]
	v_mfma_f32_16x16x32_bf16 v[94:97], v[200:203], v[232:235], v[94:97]
	v_mfma_f32_16x16x32_bf16 v[86:89], v[208:211], v[232:235], v[86:89]
	v_mfma_f32_16x16x32_bf16 v[78:81], v[200:203], v[240:243], v[78:81]
	v_mfma_f32_16x16x32_bf16 v[70:73], v[208:211], v[240:243], v[70:73]
	s_setprio 0
	s_barrier
; #define PG8_STAGE(bufoff, gbase, voff) do { _Pragma("unroll") for (int _i = 0; _i < 2; ++_i) \
;         __builtin_amdgcn_global_load_lds((const unsigned*)((const char*)(gbase) + (voff)[_i]), (LAS unsigned*)(lds + (bufoff) + ldsw + _i * 8192), 16, 0, 0); } while (0)
; #define PG8_LDA(dst, b, h) do { _Pragma("unroll") for (int m = 0; m < 4; ++m) _Pragma("unroll") for (int k = 0; k < 2; ++k) dst[m][k] = *(const LAS bf16x8*)(lds + PG8_SA(b, h) + aoff + m * 2048 + k * 1024); } while (0)
; #define PG8_MMA(ai, bj, At, Bt) do { __builtin_amdgcn_s_setprio(3); _Pragma("unroll") for (int m = 0; m < 4; ++m) _Pragma("unroll") for (int n = 0; n < 2; ++n) _Pragma("unroll") for (int k = 0; k < 2; ++k) \
;         acc[ai][bj][m][n] = __builtin_amdgcn_mfma_f32_16x16x32_bf16(Bt[n][k], At[m][k], acc[ai][bj][m][n], 0, 0, 0); __builtin_amdgcn_s_setprio(0); } while (0)
; #define PG8_WAIT_V(n) asm volatile("s_waitcnt vmcnt(" #n ")" ::: "memory")
; #define PG8_WAIT_L(n) asm volatile("s_waitcnt lgkmcnt(" #n ")" ::: "memory")
; #define PG8_BAR __builtin_amdgcn_s_barrier()
; #define PG8_SCHED __builtin_amdgcn_sched_barrier(0)
;     ...
;             PG8_LDA(At, 1, 1); PG8_STAGE(PG8_SB(1, 0), b3, voffB); PG8_STAGE(PG8_SB(1, 1), b3 + hstepB, voffB); PG8_STAGE(PG8_SA(1, 0), a3, voffA);
;             PG8_WAIT_V(8); PG8_WAIT_L(0); PG8_BAR; PG8_MMA(1, 0, At, B0); PG8_MMA(1, 1, At, B1); PG8_BAR; PG8_SCHED;
;     __device__ __forceinline__ void operator()(const f32x4 (&acc)[2][2][4][2], const Unit& u, int wr, int wc, int fr, int fq) const {
;         const int row0 = u.pm * BM + wr * 64 + fr, col0 = u.pn * 128 + wc * 32 + 8 * fq;
; #pragma unroll
;         for (int ai = 0; ai < 2; ++ai)
; #pragma unroll
;             for (int m = 0; m < 4; ++m) {
;                 const int row = row0 + ai * HALF + m * 16; const float rs = row_rs4(ssq, row, fq), rs2 = rs * rs, nrs = -LOG2E * rs;
	s_add_i32 s34, s77, s65
	v_lshl_add_u64 v[144:145], v[144:145], 0, s[46:47]
	s_mov_b32 m0, s34
	ds_read_b128 v[212:215], v164 offset:49152
	ds_read_b128 v[216:219], v164 offset:50176
	ds_read_b128 v[220:223], v164 offset:51200
	ds_read_b128 v[224:227], v164 offset:52224
	ds_read_b128 v[228:231], v164 offset:53248
	ds_read_b128 v[232:235], v164 offset:54272
	ds_read_b128 v[236:239], v164 offset:55296
	ds_read_b128 v[240:243], v164 offset:56320
	global_load_lds_dwordx4 v[144:145], off
	s_add_i32 m0, s34, 0x2000
	s_add_u32 s30, s30, 0x40080
	v_lshl_add_u64 v[144:145], v[244:245], 0, s[46:47]
	s_addc_u32 s31, s31, 0
	s_add_i32 s34, s78, s65
	global_load_lds_dwordx4 v[144:145], off
	v_lshl_add_u64 v[144:145], s[30:31], 0, v[134:135]
	s_mov_b32 m0, s34
	s_nop 0
	global_load_lds_dwordx4 v[144:145], off
	v_lshl_add_u64 v[144:145], s[30:31], 0, v[130:131]
	s_add_i32 m0, s34, 0x2000
	s_nop 0
	global_load_lds_dwordx4 v[144:145], off
	v_lshl_add_u64 v[144:145], v[246:247], 0, s[46:47]
	s_mov_b32 m0, s67
	s_nop 0
	global_load_lds_dwordx4 v[144:145], off
	v_lshl_add_u64 v[144:145], v[248:249], 0, s[46:47]
	s_mov_b32 m0, s68
	s_nop 0
	global_load_lds_dwordx4 v[144:145], off
	s_waitcnt vmcnt(8)
	s_waitcnt lgkmcnt(0)
	s_barrier
	s_setprio 3
	s_waitcnt lgkmcnt(0)
	v_mfma_f32_16x16x32_bf16 v[58:61], v[166:169], v[212:215], v[58:61]
	v_mfma_f32_16x16x32_bf16 v[50:53], v[174:177], v[212:215], v[50:53]
	v_mfma_f32_16x16x32_bf16 v[42:45], v[166:169], v[220:223], v[42:45]
	v_mfma_f32_16x16x32_bf16 v[34:37], v[174:177], v[220:223], v[34:37]
	v_mfma_f32_16x16x32_bf16 v[26:29], v[166:169], v[228:231], v[26:29]
	v_mfma_f32_16x16x32_bf16 v[18:21], v[174:177], v[228:231], v[18:21]
	v_mfma_f32_16x16x32_bf16 v[10:13], v[166:169], v[236:239], v[10:13]
	v_mfma_f32_16x16x32_bf16 v[6:9], v[174:177], v[236:239], v[6:9]
	v_mfma_f32_16x16x32_bf16 v[58:61], v[170:173], v[216:219], v[58:61]
	v_mfma_f32_16x16x32_bf16 v[50:53], v[192:195], v[216:219], v[50:53]
	v_mfma_f32_16x16x32_bf16 v[42:45], v[170:173], v[224:227], v[42:45]
	v_mfma_f32_16x16x32_bf16 v[34:37], v[192:195], v[224:227], v[34:37]
	v_mfma_f32_16x16x32_bf16 v[26:29], v[170:173], v[232:235], v[26:29]
	v_mfma_f32_16x16x32_bf16 v[18:21], v[192:195], v[232:235], v[18:21]
	v_mfma_f32_16x16x32_bf16 v[10:13], v[170:173], v[240:243], v[10:13]
	v_mfma_f32_16x16x32_bf16 v[6:9], v[192:195], v[240:243], v[6:9]
	v_mfma_f32_16x16x32_bf16 v[62:65], v[196:199], v[212:215], v[62:65]
	v_mfma_f32_16x16x32_bf16 v[54:57], v[204:207], v[212:215], v[54:57]
	v_mfma_f32_16x16x32_bf16 v[46:49], v[196:199], v[220:223], v[46:49]
	v_mfma_f32_16x16x32_bf16 v[38:41], v[204:207], v[220:223], v[38:41]
	v_mfma_f32_16x16x32_bf16 v[30:33], v[196:199], v[228:231], v[30:33]
	v_mfma_f32_16x16x32_bf16 v[22:25], v[204:207], v[228:231], v[22:25]
	v_mfma_f32_16x16x32_bf16 v[14:17], v[196:199], v[236:239], v[14:17]
	v_mfma_f32_16x16x32_bf16 v[2:5], v[204:207], v[236:239], v[2:5]
	v_mfma_f32_16x16x32_bf16 v[62:65], v[200:203], v[216:219], v[62:65]
	v_mfma_f32_16x16x32_bf16 v[54:57], v[208:211], v[216:219], v[54:57]
	v_mfma_f32_16x16x32_bf16 v[46:49], v[200:203], v[224:227], v[46:49]
	v_mfma_f32_16x16x32_bf16 v[38:41], v[208:211], v[224:227], v[38:41]
	v_mfma_f32_16x16x32_bf16 v[30:33], v[200:203], v[232:235], v[30:33]
	v_mfma_f32_16x16x32_bf16 v[22:25], v[208:211], v[232:235], v[22:25]
	v_mfma_f32_16x16x32_bf16 v[14:17], v[200:203], v[240:243], v[14:17]
	v_mfma_f32_16x16x32_bf16 v[2:5], v[208:211], v[240:243], v[2:5]
	s_setprio 0
	s_barrier
	s_add_i32 s76, s76, 2
	s_add_u32 s74, s74, 0x100
	s_addc_u32 s75, s75, 0
	s_add_u32 s26, s26, 0x100
	s_addc_u32 s27, s27, 0
	s_cmp_gt_u32 s76, 13
	s_cbranch_scc0 .LBB0_877
	v_lshl_add_u32 v236, s28, 8, v1
	v_ashrrev_i32_e32 v237, 31, v236
	v_lshlrev_b64 v[238:239], 6, v[236:237]
	v_lshl_add_u64 v[238:239], v[138:139], 0, v[238:239]
	global_load_dwordx4 v[196:199], v[238:239], off
	global_load_dwordx4 v[200:203], v[238:239], off offset:1024
	global_load_dwordx4 v[204:207], v[238:239], off offset:2048
	global_load_dwordx4 v[208:211], v[238:239], off offset:3072
	v_add_u32_e32 v236, 0x80, v236
	v_ashrrev_i32_e32 v237, 31, v236
	v_lshlrev_b64 v[238:239], 6, v[236:237]
	v_lshl_add_u64 v[238:239], v[138:139], 0, v[238:239]
	global_load_dwordx4 v[212:215], v[238:239], off
	global_load_dwordx4 v[216:219], v[238:239], off offset:1024
	global_load_dwordx4 v[220:223], v[238:239], off offset:2048
	global_load_dwordx4 v[224:227], v[238:239], off offset:3072
	v_xor_b32_e32 v240, 16, v182
	v_xor_b32_e32 v241, 32, v182
	v_lshlrev_b32_e32 v240, 2, v240
	v_lshlrev_b32_e32 v241, 2, v241
	s_and_b64 vcc, exec, s[6:7]
	s_cbranch_vccz .LBB0_880
	s_barrier

; #define PG8_STAGE(bufoff, gbase, voff) do { _Pragma("unroll") for (int _i = 0; _i < 2; ++_i) \
;         __builtin_amdgcn_global_load_lds((const unsigned*)((const char*)(gbase) + (voff)[_i]), (LAS unsigned*)(lds + (bufoff) + ldsw + _i * 8192), 16, 0, 0); } while (0)
; #define PG8_LDA(dst, b, h) do { _Pragma("unroll") for (int m = 0; m < 4; ++m) _Pragma("unroll") for (int k = 0; k < 2; ++k) dst[m][k] = *(const LAS bf16x8*)(lds + PG8_SA(b, h) + aoff + m * 2048 + k * 1024); } while (0)
; #define PG8_LDB(dst, b, h) do { _Pragma("unroll") for (int n = 0; n < 2; ++n) _Pragma("unroll") for (int k = 0; k < 2; ++k) dst[n][k] = *(const LAS bf16x8*)(lds + PG8_SB(b, h) + boff + n * 2048 + k * 1024); } while (0)
; #define PG8_MMA(ai, bj, At, Bt) do { __builtin_amdgcn_s_setprio(3); _Pragma("unroll") for (int m = 0; m < 4; ++m) _Pragma("unroll") for (int n = 0; n < 2; ++n) _Pragma("unroll") for (int k = 0; k < 2; ++k) \
;         acc[ai][bj][m][n] = __builtin_amdgcn_mfma_f32_16x16x32_bf16(Bt[n][k], At[m][k], acc[ai][bj][m][n], 0, 0, 0); __builtin_amdgcn_s_setprio(0); } while (0)
; #define PG8_WAIT_V(n) asm volatile("s_waitcnt vmcnt(" #n ")" ::: "memory")
; #define PG8_WAIT_L(n) asm volatile("s_waitcnt lgkmcnt(" #n ")" ::: "memory")
; #define PG8_BAR __builtin_amdgcn_s_barrier()
; #define PG8_SCHED __builtin_amdgcn_sched_barrier(0)
;     ...
;             PG8_LDB(B0, 0, 0); PG8_LDB(B1, 0, 1); PG8_SCHED; PG8_LDA(At, 0, 0); PG8_STAGE(PG8_SA(1, 1), a1 + hstepA, voffA);
;             PG8_WAIT_V(8); PG8_WAIT_L(0); PG8_BAR; PG8_MMA(0, 0, At, B0); PG8_MMA(0, 1, At, B1); PG8_BAR; PG8_SCHED;
;             PG8_LDA(At, 0, 1); PG8_STAGE(PG8_SB(0, 0), b2, voffB); PG8_STAGE(PG8_SB(0, 1), b2 + hstepB, voffB); PG8_STAGE(PG8_SA(0, 0), a2, voffA);
;             PG8_WAIT_V(8); PG8_WAIT_L(0); PG8_BAR; PG8_MMA(1, 0, At, B0); PG8_MMA(1, 1, At, B1); PG8_BAR; PG8_SCHED;
.LBB0_899:
	s_add_u32 s4, s24, 0x100
	s_addc_u32 s5, s25, 0
	s_add_i32 s77, 0, 0x10000
	s_cmp_eq_u32 s76, 12
	s_cselect_b32 s29, s13, s5
	s_cselect_b32 s28, s12, s4
	v_add_u32_e32 v146, s77, v168
	s_cselect_b32 s27, s11, s75
	s_cselect_b32 s26, s61, s74
	s_add_i32 s78, 0, 0x14000
	ds_read_b128 v[142:145], v146
	ds_read_b128 v[164:167], v146 offset:1024
	ds_read_b128 v[172:175], v146 offset:2048
	ds_read_b128 v[192:195], v146 offset:3072
	v_add_u32_e32 v146, s78, v168
	ds_read_b128 v[196:199], v146
	ds_read_b128 v[200:203], v146 offset:1024
	ds_read_b128 v[204:207], v146 offset:2048
	ds_read_b128 v[208:211], v146 offset:3072
	v_lshl_add_u64 v[146:147], s[24:25], 0, v[140:141]
	s_add_i32 m0, s64, 0xc000
	ds_read_b128 v[212:215], v170
	ds_read_b128 v[216:219], v170 offset:1024
	ds_read_b128 v[220:223], v170 offset:2048
	ds_read_b128 v[224:227], v170 offset:3072
	ds_read_b128 v[228:231], v170 offset:4096
	ds_read_b128 v[232:235], v170 offset:5120
	ds_read_b128 v[236:239], v170 offset:6144
	ds_read_b128 v[240:243], v170 offset:7168
	global_load_lds_dwordx4 v[146:147], off
	v_lshl_add_u64 v[146:147], s[24:25], 0, v[138:139]
	s_add_i32 m0, s64, 0xe000
	s_nop 0
	global_load_lds_dwordx4 v[146:147], off
	s_waitcnt vmcnt(8)
	s_waitcnt lgkmcnt(0)
	s_barrier
	s_setprio 3
	s_waitcnt lgkmcnt(0)
	v_mfma_f32_16x16x32_bf16 v[126:129], v[142:145], v[212:215], v[126:129]
	v_mfma_f32_16x16x32_bf16 v[122:125], v[172:175], v[212:215], v[122:125]
	v_mfma_f32_16x16x32_bf16 v[110:113], v[142:145], v[220:223], v[110:113]
	v_mfma_f32_16x16x32_bf16 v[106:109], v[172:175], v[220:223], v[106:109]
	v_mfma_f32_16x16x32_bf16 v[94:97], v[142:145], v[228:231], v[94:97]
	v_mfma_f32_16x16x32_bf16 v[90:93], v[172:175], v[228:231], v[90:93]
	v_mfma_f32_16x16x32_bf16 v[78:81], v[142:145], v[236:239], v[78:81]
	v_mfma_f32_16x16x32_bf16 v[74:77], v[172:175], v[236:239], v[74:77]
	v_mfma_f32_16x16x32_bf16 v[126:129], v[164:167], v[216:219], v[126:129]
	v_mfma_f32_16x16x32_bf16 v[122:125], v[192:195], v[216:219], v[122:125]
	v_mfma_f32_16x16x32_bf16 v[110:113], v[164:167], v[224:227], v[110:113]
	v_mfma_f32_16x16x32_bf16 v[106:109], v[192:195], v[224:227], v[106:109]
	v_mfma_f32_16x16x32_bf16 v[94:97], v[164:167], v[232:235], v[94:97]
	v_mfma_f32_16x16x32_bf16 v[90:93], v[192:195], v[232:235], v[90:93]
	v_mfma_f32_16x16x32_bf16 v[78:81], v[164:167], v[240:243], v[78:81]
	v_mfma_f32_16x16x32_bf16 v[74:77], v[192:195], v[240:243], v[74:77]
	v_mfma_f32_16x16x32_bf16 v[118:121], v[196:199], v[212:215], v[118:121]
	v_mfma_f32_16x16x32_bf16 v[114:117], v[204:207], v[212:215], v[114:117]
	v_mfma_f32_16x16x32_bf16 v[102:105], v[196:199], v[220:223], v[102:105]
	v_mfma_f32_16x16x32_bf16 v[98:101], v[204:207], v[220:223], v[98:101]
	v_mfma_f32_16x16x32_bf16 v[86:89], v[196:199], v[228:231], v[86:89]
	v_mfma_f32_16x16x32_bf16 v[82:85], v[204:207], v[228:231], v[82:85]
	v_mfma_f32_16x16x32_bf16 v[70:73], v[196:199], v[236:239], v[70:73]
	v_mfma_f32_16x16x32_bf16 v[66:69], v[204:207], v[236:239], v[66:69]
	v_mfma_f32_16x16x32_bf16 v[118:121], v[200:203], v[216:219], v[118:121]
	v_mfma_f32_16x16x32_bf16 v[114:117], v[208:211], v[216:219], v[114:117]
	v_mfma_f32_16x16x32_bf16 v[102:105], v[200:203], v[224:227], v[102:105]
	v_mfma_f32_16x16x32_bf16 v[98:101], v[208:211], v[224:227], v[98:101]
	v_mfma_f32_16x16x32_bf16 v[86:89], v[200:203], v[232:235], v[86:89]
	v_mfma_f32_16x16x32_bf16 v[82:85], v[208:211], v[232:235], v[82:85]
	v_mfma_f32_16x16x32_bf16 v[70:73], v[200:203], v[240:243], v[70:73]
	v_mfma_f32_16x16x32_bf16 v[66:69], v[208:211], v[240:243], v[66:69]
	s_setprio 0
	s_barrier
	s_add_i32 s24, s77, s35
	v_lshl_add_u64 v[146:147], s[26:27], 0, v[134:135]
	s_mov_b32 m0, s24
	ds_read_b128 v[212:215], v170 offset:16384
	ds_read_b128 v[216:219], v170 offset:17408
	ds_read_b128 v[220:223], v170 offset:18432
	ds_read_b128 v[224:227], v170 offset:19456
	ds_read_b128 v[228:231], v170 offset:20480
	ds_read_b128 v[232:235], v170 offset:21504
	ds_read_b128 v[236:239], v170 offset:22528
	ds_read_b128 v[240:243], v170 offset:23552
	global_load_lds_dwordx4 v[146:147], off
	s_add_i32 m0, s24, 0x2000
	s_add_u32 s24, s26, 0x10000
	v_lshl_add_u64 v[176:177], s[26:27], 0, v[130:131]
	s_addc_u32 s25, s27, 0
	s_add_i32 s77, s78, s35
	global_load_lds_dwordx4 v[176:177], off
	v_lshl_add_u64 v[244:245], s[24:25], 0, v[134:135]
	s_mov_b32 m0, s77
	v_lshl_add_u64 v[246:247], s[28:29], 0, v[132:133]
	global_load_lds_dwordx4 v[244:245], off
	v_lshl_add_u64 v[244:245], s[24:25], 0, v[130:131]
	s_add_i32 m0, s77, 0x2000
	s_nop 0
	global_load_lds_dwordx4 v[244:245], off
	v_lshl_add_u64 v[244:245], s[28:29], 0, v[136:137]
	s_mov_b32 m0, s64
	s_nop 0
	global_load_lds_dwordx4 v[244:245], off
	s_mov_b32 m0, s65
	s_nop 0
	global_load_lds_dwordx4 v[246:247], off
	s_waitcnt vmcnt(8)
	s_waitcnt lgkmcnt(0)
	s_barrier
; #define PG8_STAGE(bufoff, gbase, voff) do { _Pragma("unroll") for (int _i = 0; _i < 2; ++_i) \
;         __builtin_amdgcn_global_load_lds((const unsigned*)((const char*)(gbase) + (voff)[_i]), (LAS unsigned*)(lds + (bufoff) + ldsw + _i * 8192), 16, 0, 0); } while (0)
; #define PG8_LDA(dst, b, h) do { _Pragma("unroll") for (int m = 0; m < 4; ++m) _Pragma("unroll") for (int k = 0; k < 2; ++k) dst[m][k] = *(const LAS bf16x8*)(lds + PG8_SA(b, h) + aoff + m * 2048 + k * 1024); } while (0)
; #define PG8_LDB(dst, b, h) do { _Pragma("unroll") for (int n = 0; n < 2; ++n) _Pragma("unroll") for (int k = 0; k < 2; ++k) dst[n][k] = *(const LAS bf16x8*)(lds + PG8_SB(b, h) + boff + n * 2048 + k * 1024); } while (0)
; #define PG8_MMA(ai, bj, At, Bt) do { __builtin_amdgcn_s_setprio(3); _Pragma("unroll") for (int m = 0; m < 4; ++m) _Pragma("unroll") for (int n = 0; n < 2; ++n) _Pragma("unroll") for (int k = 0; k < 2; ++k) \
;         acc[ai][bj][m][n] = __builtin_amdgcn_mfma_f32_16x16x32_bf16(Bt[n][k], At[m][k], acc[ai][bj][m][n], 0, 0, 0); __builtin_amdgcn_s_setprio(0); } while (0)
; #define PG8_WAIT_V(n) asm volatile("s_waitcnt vmcnt(" #n ")" ::: "memory")
; #define PG8_WAIT_L(n) asm volatile("s_waitcnt lgkmcnt(" #n ")" ::: "memory")
; #define PG8_BAR __builtin_amdgcn_s_barrier()
; #define PG8_SCHED __builtin_amdgcn_sched_barrier(0)
;     ...
;             PG8_WAIT_V(8); PG8_WAIT_L(0); PG8_BAR; PG8_MMA(1, 0, At, B0); PG8_MMA(1, 1, At, B1); PG8_BAR; PG8_SCHED;
;             PG8_LDB(B0, 1, 0); PG8_LDB(B1, 1, 1); PG8_SCHED; PG8_LDA(At, 1, 0); PG8_STAGE(PG8_SA(0, 1), a2 + hstepA, voffA);
;             PG8_WAIT_V(8); PG8_WAIT_L(0); PG8_BAR; PG8_MMA(0, 0, At, B0); PG8_MMA(0, 1, At, B1); PG8_BAR; PG8_SCHED;
	s_setprio 3
	s_waitcnt lgkmcnt(0)
	v_mfma_f32_16x16x32_bf16 v[62:65], v[142:145], v[212:215], v[62:65]
	v_mfma_f32_16x16x32_bf16 v[58:61], v[172:175], v[212:215], v[58:61]
	v_mfma_f32_16x16x32_bf16 v[46:49], v[142:145], v[220:223], v[46:49]
	v_mfma_f32_16x16x32_bf16 v[42:45], v[172:175], v[220:223], v[42:45]
	v_mfma_f32_16x16x32_bf16 v[30:33], v[142:145], v[228:231], v[30:33]
	v_mfma_f32_16x16x32_bf16 v[26:29], v[172:175], v[228:231], v[26:29]
	v_mfma_f32_16x16x32_bf16 v[14:17], v[142:145], v[236:239], v[14:17]
	v_mfma_f32_16x16x32_bf16 v[10:13], v[172:175], v[236:239], v[10:13]
	v_mfma_f32_16x16x32_bf16 v[62:65], v[164:167], v[216:219], v[62:65]
	v_mfma_f32_16x16x32_bf16 v[58:61], v[192:195], v[216:219], v[58:61]
	v_mfma_f32_16x16x32_bf16 v[46:49], v[164:167], v[224:227], v[46:49]
	v_mfma_f32_16x16x32_bf16 v[42:45], v[192:195], v[224:227], v[42:45]
	v_mfma_f32_16x16x32_bf16 v[30:33], v[164:167], v[232:235], v[30:33]
	v_mfma_f32_16x16x32_bf16 v[26:29], v[192:195], v[232:235], v[26:29]
	v_mfma_f32_16x16x32_bf16 v[14:17], v[164:167], v[240:243], v[14:17]
	v_mfma_f32_16x16x32_bf16 v[10:13], v[192:195], v[240:243], v[10:13]
	v_mfma_f32_16x16x32_bf16 v[54:57], v[196:199], v[212:215], v[54:57]
	v_mfma_f32_16x16x32_bf16 v[50:53], v[204:207], v[212:215], v[50:53]
	v_mfma_f32_16x16x32_bf16 v[38:41], v[196:199], v[220:223], v[38:41]
	v_mfma_f32_16x16x32_bf16 v[34:37], v[204:207], v[220:223], v[34:37]
	v_mfma_f32_16x16x32_bf16 v[22:25], v[196:199], v[228:231], v[22:25]
	v_mfma_f32_16x16x32_bf16 v[18:21], v[204:207], v[228:231], v[18:21]
	v_mfma_f32_16x16x32_bf16 v[6:9], v[196:199], v[236:239], v[6:9]
	v_mfma_f32_16x16x32_bf16 v[2:5], v[204:207], v[236:239], v[2:5]
	v_mfma_f32_16x16x32_bf16 v[54:57], v[200:203], v[216:219], v[54:57]
	v_mfma_f32_16x16x32_bf16 v[50:53], v[208:211], v[216:219], v[50:53]
	v_mfma_f32_16x16x32_bf16 v[38:41], v[200:203], v[224:227], v[38:41]
	v_mfma_f32_16x16x32_bf16 v[34:37], v[208:211], v[224:227], v[34:37]
	v_mfma_f32_16x16x32_bf16 v[22:25], v[200:203], v[232:235], v[22:25]
	v_mfma_f32_16x16x32_bf16 v[18:21], v[208:211], v[232:235], v[18:21]
	v_mfma_f32_16x16x32_bf16 v[6:9], v[200:203], v[240:243], v[6:9]
	v_mfma_f32_16x16x32_bf16 v[2:5], v[208:211], v[240:243], v[2:5]
	s_setprio 0
	s_barrier
	s_add_i32 s77, 0, 0x18000
	v_add_u32_e32 v171, s77, v168
	s_add_i32 s78, 0, 0x1c000
	ds_read_b128 v[142:145], v171
	ds_read_b128 v[164:167], v171 offset:1024
	ds_read_b128 v[172:175], v171 offset:2048
	ds_read_b128 v[192:195], v171 offset:3072
	v_add_u32_e32 v171, s78, v168
	ds_read_b128 v[196:199], v171
	ds_read_b128 v[200:203], v171 offset:1024
	ds_read_b128 v[204:207], v171 offset:2048
	ds_read_b128 v[208:211], v171 offset:3072
	s_add_u32 s24, s28, 0xe0000
	s_addc_u32 s25, s29, 0
	s_mov_b32 m0, s66
	v_lshl_add_u64 v[248:249], s[24:25], 0, v[136:137]
	ds_read_b128 v[212:215], v170 offset:32768
	ds_read_b128 v[216:219], v170 offset:33792
	ds_read_b128 v[220:223], v170 offset:34816
	ds_read_b128 v[224:227], v170 offset:35840
	ds_read_b128 v[228:231], v170 offset:36864
	ds_read_b128 v[232:235], v170 offset:37888
	ds_read_b128 v[236:239], v170 offset:38912
	ds_read_b128 v[240:243], v170 offset:39936
	global_load_lds_dwordx4 v[248:249], off
	v_lshl_add_u64 v[248:249], s[24:25], 0, v[132:133]
	s_mov_b32 m0, s67
	s_nop 0
	global_load_lds_dwordx4 v[248:249], off
	s_waitcnt vmcnt(8)
	s_waitcnt lgkmcnt(0)
	s_barrier
	s_setprio 3
	s_waitcnt lgkmcnt(0)
	v_mfma_f32_16x16x32_bf16 v[126:129], v[142:145], v[212:215], v[126:129]
	v_mfma_f32_16x16x32_bf16 v[122:125], v[172:175], v[212:215], v[122:125]
	v_mfma_f32_16x16x32_bf16 v[110:113], v[142:145], v[220:223], v[110:113]
	v_mfma_f32_16x16x32_bf16 v[106:109], v[172:175], v[220:223], v[106:109]
	v_mfma_f32_16x16x32_bf16 v[94:97], v[142:145], v[228:231], v[94:97]
	v_mfma_f32_16x16x32_bf16 v[90:93], v[172:175], v[228:231], v[90:93]
	v_mfma_f32_16x16x32_bf16 v[78:81], v[142:145], v[236:239], v[78:81]
	v_mfma_f32_16x16x32_bf16 v[74:77], v[172:175], v[236:239], v[74:77]
	v_mfma_f32_16x16x32_bf16 v[126:129], v[164:167], v[216:219], v[126:129]
	v_mfma_f32_16x16x32_bf16 v[122:125], v[192:195], v[216:219], v[122:125]
	v_mfma_f32_16x16x32_bf16 v[110:113], v[164:167], v[224:227], v[110:113]
	v_mfma_f32_16x16x32_bf16 v[106:109], v[192:195], v[224:227], v[106:109]
	v_mfma_f32_16x16x32_bf16 v[94:97], v[164:167], v[232:235], v[94:97]
	v_mfma_f32_16x16x32_bf16 v[90:93], v[192:195], v[232:235], v[90:93]
	v_mfma_f32_16x16x32_bf16 v[78:81], v[164:167], v[240:243], v[78:81]
	v_mfma_f32_16x16x32_bf16 v[74:77], v[192:195], v[240:243], v[74:77]
	v_mfma_f32_16x16x32_bf16 v[118:121], v[196:199], v[212:215], v[118:121]
	v_mfma_f32_16x16x32_bf16 v[114:117], v[204:207], v[212:215], v[114:117]
	v_mfma_f32_16x16x32_bf16 v[102:105], v[196:199], v[220:223], v[102:105]
	v_mfma_f32_16x16x32_bf16 v[98:101], v[204:207], v[220:223], v[98:101]
	v_mfma_f32_16x16x32_bf16 v[86:89], v[196:199], v[228:231], v[86:89]
	v_mfma_f32_16x16x32_bf16 v[82:85], v[204:207], v[228:231], v[82:85]
	v_mfma_f32_16x16x32_bf16 v[70:73], v[196:199], v[236:239], v[70:73]
	v_mfma_f32_16x16x32_bf16 v[66:69], v[204:207], v[236:239], v[66:69]
	v_mfma_f32_16x16x32_bf16 v[118:121], v[200:203], v[216:219], v[118:121]
	v_mfma_f32_16x16x32_bf16 v[114:117], v[208:211], v[216:219], v[114:117]
	v_mfma_f32_16x16x32_bf16 v[102:105], v[200:203], v[224:227], v[102:105]
	v_mfma_f32_16x16x32_bf16 v[98:101], v[208:211], v[224:227], v[98:101]
	v_mfma_f32_16x16x32_bf16 v[86:89], v[200:203], v[232:235], v[86:89]
	v_mfma_f32_16x16x32_bf16 v[82:85], v[208:211], v[232:235], v[82:85]
	v_mfma_f32_16x16x32_bf16 v[70:73], v[200:203], v[240:243], v[70:73]
	v_mfma_f32_16x16x32_bf16 v[66:69], v[208:211], v[240:243], v[66:69]
	s_setprio 0
	s_barrier
; #define PG8_STAGE(bufoff, gbase, voff) do { _Pragma("unroll") for (int _i = 0; _i < 2; ++_i) \
;         __builtin_amdgcn_global_load_lds((const unsigned*)((const char*)(gbase) + (voff)[_i]), (LAS unsigned*)(lds + (bufoff) + ldsw + _i * 8192), 16, 0, 0); } while (0)
; #define PG8_LDA(dst, b, h) do { _Pragma("unroll") for (int m = 0; m < 4; ++m) _Pragma("unroll") for (int k = 0; k < 2; ++k) dst[m][k] = *(const LAS bf16x8*)(lds + PG8_SA(b, h) + aoff + m * 2048 + k * 1024); } while (0)
; #define PG8_MMA(ai, bj, At, Bt) do { __builtin_amdgcn_s_setprio(3); _Pragma("unroll") for (int m = 0; m < 4; ++m) _Pragma("unroll") for (int n = 0; n < 2; ++n) _Pragma("unroll") for (int k = 0; k < 2; ++k) \
;         acc[ai][bj][m][n] = __builtin_amdgcn_mfma_f32_16x16x32_bf16(Bt[n][k], At[m][k], acc[ai][bj][m][n], 0, 0, 0); __builtin_amdgcn_s_setprio(0); } while (0)
; #define PG8_WAIT_V(n) asm volatile("s_waitcnt vmcnt(" #n ")" ::: "memory")
; #define PG8_WAIT_L(n) asm volatile("s_waitcnt lgkmcnt(" #n ")" ::: "memory")
; #define PG8_BAR __builtin_amdgcn_s_barrier()
; #define PG8_SCHED __builtin_amdgcn_sched_barrier(0)
;     ...
;             PG8_LDA(At, 1, 1); PG8_STAGE(PG8_SB(1, 0), b3, voffB); PG8_STAGE(PG8_SB(1, 1), b3 + hstepB, voffB); PG8_STAGE(PG8_SA(1, 0), a3, voffA);
;             PG8_WAIT_V(8); PG8_WAIT_L(0); PG8_BAR; PG8_MMA(1, 0, At, B0); PG8_MMA(1, 1, At, B1); PG8_BAR; PG8_SCHED;
;     ...
;         if constexpr (ALIGN_EPI) { if (wr == 0) PG8_BAR; }
	s_add_i32 s24, s77, s35
	v_lshl_add_u64 v[146:147], v[146:147], 0, s[46:47]
	s_mov_b32 m0, s24
	ds_read_b128 v[212:215], v170 offset:49152
	ds_read_b128 v[216:219], v170 offset:50176
	ds_read_b128 v[220:223], v170 offset:51200
	ds_read_b128 v[224:227], v170 offset:52224
	ds_read_b128 v[228:231], v170 offset:53248
	ds_read_b128 v[232:235], v170 offset:54272
	ds_read_b128 v[236:239], v170 offset:55296
	ds_read_b128 v[240:243], v170 offset:56320
	global_load_lds_dwordx4 v[146:147], off
	s_add_i32 m0, s24, 0x2000
	s_add_u32 s24, s26, 0x10080
	v_lshl_add_u64 v[146:147], v[176:177], 0, s[46:47]
	s_addc_u32 s25, s27, 0
	s_add_i32 s26, s78, s35
	global_load_lds_dwordx4 v[146:147], off
	v_lshl_add_u64 v[146:147], s[24:25], 0, v[134:135]
	s_mov_b32 m0, s26
	s_nop 0
	global_load_lds_dwordx4 v[146:147], off
	v_lshl_add_u64 v[146:147], s[24:25], 0, v[130:131]
	s_add_i32 m0, s26, 0x2000
	s_nop 0
	global_load_lds_dwordx4 v[146:147], off
	v_lshl_add_u64 v[146:147], v[244:245], 0, s[46:47]
	s_mov_b32 m0, s69
	s_nop 0
	global_load_lds_dwordx4 v[146:147], off
	v_lshl_add_u64 v[146:147], v[246:247], 0, s[46:47]
	s_mov_b32 m0, s70
	s_nop 0
	global_load_lds_dwordx4 v[146:147], off
	s_waitcnt vmcnt(8)
	s_waitcnt lgkmcnt(0)
	s_barrier
	s_setprio 3
	s_waitcnt lgkmcnt(0)
	v_mfma_f32_16x16x32_bf16 v[62:65], v[142:145], v[212:215], v[62:65]
	v_mfma_f32_16x16x32_bf16 v[58:61], v[172:175], v[212:215], v[58:61]
	v_mfma_f32_16x16x32_bf16 v[46:49], v[142:145], v[220:223], v[46:49]
	v_mfma_f32_16x16x32_bf16 v[42:45], v[172:175], v[220:223], v[42:45]
	v_mfma_f32_16x16x32_bf16 v[30:33], v[142:145], v[228:231], v[30:33]
	v_mfma_f32_16x16x32_bf16 v[26:29], v[172:175], v[228:231], v[26:29]
	v_mfma_f32_16x16x32_bf16 v[14:17], v[142:145], v[236:239], v[14:17]
	v_mfma_f32_16x16x32_bf16 v[10:13], v[172:175], v[236:239], v[10:13]
	v_mfma_f32_16x16x32_bf16 v[62:65], v[164:167], v[216:219], v[62:65]
	v_mfma_f32_16x16x32_bf16 v[58:61], v[192:195], v[216:219], v[58:61]
	v_mfma_f32_16x16x32_bf16 v[46:49], v[164:167], v[224:227], v[46:49]
	v_mfma_f32_16x16x32_bf16 v[42:45], v[192:195], v[224:227], v[42:45]
	v_mfma_f32_16x16x32_bf16 v[30:33], v[164:167], v[232:235], v[30:33]
	v_mfma_f32_16x16x32_bf16 v[26:29], v[192:195], v[232:235], v[26:29]
	v_mfma_f32_16x16x32_bf16 v[14:17], v[164:167], v[240:243], v[14:17]
	v_mfma_f32_16x16x32_bf16 v[10:13], v[192:195], v[240:243], v[10:13]
	v_mfma_f32_16x16x32_bf16 v[54:57], v[196:199], v[212:215], v[54:57]
	v_mfma_f32_16x16x32_bf16 v[50:53], v[204:207], v[212:215], v[50:53]
	v_mfma_f32_16x16x32_bf16 v[38:41], v[196:199], v[220:223], v[38:41]
	v_mfma_f32_16x16x32_bf16 v[34:37], v[204:207], v[220:223], v[34:37]
	v_mfma_f32_16x16x32_bf16 v[22:25], v[196:199], v[228:231], v[22:25]
	v_mfma_f32_16x16x32_bf16 v[18:21], v[204:207], v[228:231], v[18:21]
	v_mfma_f32_16x16x32_bf16 v[6:9], v[196:199], v[236:239], v[6:9]
	v_mfma_f32_16x16x32_bf16 v[2:5], v[204:207], v[236:239], v[2:5]
	v_mfma_f32_16x16x32_bf16 v[54:57], v[200:203], v[216:219], v[54:57]
	v_mfma_f32_16x16x32_bf16 v[50:53], v[208:211], v[216:219], v[50:53]
	v_mfma_f32_16x16x32_bf16 v[38:41], v[200:203], v[224:227], v[38:41]
	v_mfma_f32_16x16x32_bf16 v[34:37], v[208:211], v[224:227], v[34:37]
	v_mfma_f32_16x16x32_bf16 v[22:25], v[200:203], v[232:235], v[22:25]
	v_mfma_f32_16x16x32_bf16 v[18:21], v[208:211], v[232:235], v[18:21]
	v_mfma_f32_16x16x32_bf16 v[6:9], v[200:203], v[240:243], v[6:9]
	v_mfma_f32_16x16x32_bf16 v[2:5], v[208:211], v[240:243], v[2:5]
	s_setprio 0
	s_barrier
	s_add_i32 s76, s76, 2
	s_add_u32 s74, s74, 0x100
	s_addc_u32 s75, s75, 0
	s_cmp_gt_u32 s76, 13
	s_mov_b64 s[24:25], s[4:5]
	s_cbranch_scc0 .LBB0_899
	s_and_b64 vcc, exec, s[8:9]
	s_cbranch_vccz .LBB0_902
	s_barrier
